# v48 + GEMM loops: LDS-stage base constants folded into literals (2 SALU fewer per K-iteration)
# speedup vs baseline: 1.0098x; 1.0098x over previous
.LBB0_127:
	s_add_u32 s22, s20, 0xfff80080
	s_addc_u32 s23, s21, -1
	s_cmp_eq_u32 s49, 4
	s_cselect_b32 s23, s81, s23
	s_cselect_b32 s22, s80, s22
	s_cselect_b32 s39, s19, s48
	s_cselect_b32 s38, s31, s47
	v_lshl_add_u64 v[178:179], s[20:21], 0, v[138:139]
	s_add_i32 m0, s27, 0xc000
	ds_read_b128 v[162:165], v144
	ds_read_b128 v[166:169], v144 offset:1024
	ds_read_b128 v[170:173], v144 offset:2048
	ds_read_b128 v[174:177], v144 offset:3072
	ds_read_b128 v[192:195], v144 offset:4096
	ds_read_b128 v[196:199], v144 offset:5120
	ds_read_b128 v[200:203], v144 offset:6144
	ds_read_b128 v[204:207], v144 offset:7168
	global_load_lds_dwordx4 v[178:179], off
	s_add_i32 m0, s27, 0xe000
	v_lshl_add_u64 v[178:179], s[20:21], 0, v[140:141]
	global_load_lds_dwordx4 v[178:179], off
	s_barrier
	s_waitcnt lgkmcnt(0)
	v_mfma_f32_16x16x32_bf16 v[126:129], v[146:149], v[162:165], v[126:129]
	v_mfma_f32_16x16x32_bf16 v[122:125], v[154:157], v[162:165], v[122:125]
	v_mfma_f32_16x16x32_bf16 v[118:121], v[146:149], v[170:173], v[118:121]
	v_mfma_f32_16x16x32_bf16 v[114:117], v[154:157], v[170:173], v[114:117]
	v_mfma_f32_16x16x32_bf16 v[102:105], v[146:149], v[192:195], v[102:105]
	v_mfma_f32_16x16x32_bf16 v[98:101], v[154:157], v[192:195], v[98:101]
	v_mfma_f32_16x16x32_bf16 v[86:89], v[146:149], v[200:203], v[86:89]
	v_mfma_f32_16x16x32_bf16 v[82:85], v[154:157], v[200:203], v[82:85]
	v_mfma_f32_16x16x32_bf16 v[126:129], v[150:153], v[166:169], v[126:129]
	v_mfma_f32_16x16x32_bf16 v[122:125], v[158:161], v[166:169], v[122:125]
	v_mfma_f32_16x16x32_bf16 v[118:121], v[150:153], v[174:177], v[118:121]
	v_mfma_f32_16x16x32_bf16 v[114:117], v[158:161], v[174:177], v[114:117]
	v_mfma_f32_16x16x32_bf16 v[102:105], v[150:153], v[196:199], v[102:105]
	v_mfma_f32_16x16x32_bf16 v[98:101], v[158:161], v[196:199], v[98:101]
	v_mfma_f32_16x16x32_bf16 v[86:89], v[150:153], v[204:207], v[86:89]
	v_mfma_f32_16x16x32_bf16 v[82:85], v[158:161], v[204:207], v[82:85]
	s_barrier
	s_add_i32 s50, s26, 0x10000
	v_add_u32_e32 v145, 0x14000, v142
	v_lshl_add_u64 v[178:179], s[38:39], 0, v[134:135]
	s_mov_b32 m0, s50
	ds_read_b128 v[208:211], v145
	ds_read_b128 v[224:227], v145 offset:1024
	ds_read_b128 v[228:231], v145 offset:2048
	ds_read_b128 v[232:235], v145 offset:3072
	global_load_lds_dwordx4 v[178:179], off
	s_add_i32 m0, s50, 0x2000
	v_lshl_add_u64 v[212:213], s[38:39], 0, v[130:131]
	global_load_lds_dwordx4 v[212:213], off
	s_mov_b32 m0, s27
	v_lshl_add_u64 v[236:237], s[22:23], 0, v[136:137]
	s_waitcnt lgkmcnt(0)
	s_barrier
	v_mfma_f32_16x16x32_bf16 v[110:113], v[208:211], v[162:165], v[110:113]
	v_mfma_f32_16x16x32_bf16 v[106:109], v[228:231], v[162:165], v[106:109]
	v_mfma_f32_16x16x32_bf16 v[94:97], v[208:211], v[170:173], v[94:97]
	v_mfma_f32_16x16x32_bf16 v[90:93], v[228:231], v[170:173], v[90:93]
	v_mfma_f32_16x16x32_bf16 v[78:81], v[208:211], v[192:195], v[78:81]
	v_mfma_f32_16x16x32_bf16 v[74:77], v[228:231], v[192:195], v[74:77]
	v_mfma_f32_16x16x32_bf16 v[70:73], v[208:211], v[200:203], v[70:73]
	v_mfma_f32_16x16x32_bf16 v[66:69], v[228:231], v[200:203], v[66:69]
	v_mfma_f32_16x16x32_bf16 v[110:113], v[224:227], v[166:169], v[110:113]
	v_mfma_f32_16x16x32_bf16 v[106:109], v[232:235], v[166:169], v[106:109]
	v_mfma_f32_16x16x32_bf16 v[94:97], v[224:227], v[174:177], v[94:97]
	v_mfma_f32_16x16x32_bf16 v[90:93], v[232:235], v[174:177], v[90:93]
	v_mfma_f32_16x16x32_bf16 v[78:81], v[224:227], v[196:199], v[78:81]
	v_mfma_f32_16x16x32_bf16 v[74:77], v[232:235], v[196:199], v[74:77]
	v_mfma_f32_16x16x32_bf16 v[70:73], v[224:227], v[204:207], v[70:73]
	v_mfma_f32_16x16x32_bf16 v[66:69], v[232:235], v[204:207], v[66:69]
	s_barrier
	ds_read_b128 v[162:165], v144 offset:16384
	ds_read_b128 v[166:169], v144 offset:17408
	ds_read_b128 v[170:173], v144 offset:18432
	ds_read_b128 v[174:177], v144 offset:19456
	ds_read_b128 v[192:195], v144 offset:20480
	ds_read_b128 v[196:199], v144 offset:21504
	ds_read_b128 v[200:203], v144 offset:22528
	ds_read_b128 v[204:207], v144 offset:23552
	global_load_lds_dwordx4 v[236:237], off
	s_mov_b32 m0, s28
	v_lshl_add_u64 v[238:239], s[22:23], 0, v[132:133]
	global_load_lds_dwordx4 v[238:239], off
	s_waitcnt vmcnt(10)
	s_barrier
	s_waitcnt lgkmcnt(0)
	v_mfma_f32_16x16x32_bf16 v[62:65], v[146:149], v[162:165], v[62:65]
	v_mfma_f32_16x16x32_bf16 v[58:61], v[154:157], v[162:165], v[58:61]
	v_mfma_f32_16x16x32_bf16 v[54:57], v[146:149], v[170:173], v[54:57]
	v_mfma_f32_16x16x32_bf16 v[50:53], v[154:157], v[170:173], v[50:53]
	v_mfma_f32_16x16x32_bf16 v[38:41], v[146:149], v[192:195], v[38:41]
	v_mfma_f32_16x16x32_bf16 v[34:37], v[154:157], v[192:195], v[34:37]
	v_mfma_f32_16x16x32_bf16 v[22:25], v[146:149], v[200:203], v[22:25]
	v_mfma_f32_16x16x32_bf16 v[18:21], v[154:157], v[200:203], v[18:21]
	v_mfma_f32_16x16x32_bf16 v[62:65], v[150:153], v[166:169], v[62:65]
	v_mfma_f32_16x16x32_bf16 v[58:61], v[158:161], v[166:169], v[58:61]
	v_mfma_f32_16x16x32_bf16 v[54:57], v[150:153], v[174:177], v[54:57]
	v_mfma_f32_16x16x32_bf16 v[50:53], v[158:161], v[174:177], v[50:53]
	v_mfma_f32_16x16x32_bf16 v[38:41], v[150:153], v[196:199], v[38:41]
	v_mfma_f32_16x16x32_bf16 v[34:37], v[158:161], v[196:199], v[34:37]
	v_mfma_f32_16x16x32_bf16 v[22:25], v[150:153], v[204:207], v[22:25]
	v_mfma_f32_16x16x32_bf16 v[18:21], v[158:161], v[204:207], v[18:21]
	s_barrier
	s_add_u32 s50, s38, 0x20000
	s_addc_u32 s51, s39, 0
	s_add_i32 s52, s26, 0x14000
	s_mov_b32 m0, s52
	v_lshl_add_u64 v[146:147], s[50:51], 0, v[134:135]
	global_load_lds_dwordx4 v[146:147], off
	s_add_i32 m0, s52, 0x2000
	v_lshl_add_u64 v[146:147], s[50:51], 0, v[130:131]
	global_load_lds_dwordx4 v[146:147], off
	v_add_u32_e32 v145, 0x18000, v142
	ds_read_b128 v[146:149], v145
	ds_read_b128 v[150:153], v145 offset:1024
	ds_read_b128 v[154:157], v145 offset:2048
	ds_read_b128 v[158:161], v145 offset:3072
	s_add_i32 s50, 0, 0x18000
	s_waitcnt vmcnt(6)
	s_barrier
	v_mfma_f32_16x16x32_bf16 v[46:49], v[208:211], v[162:165], v[46:49]
	v_mfma_f32_16x16x32_bf16 v[42:45], v[228:231], v[162:165], v[42:45]
	v_mfma_f32_16x16x32_bf16 v[30:33], v[208:211], v[170:173], v[30:33]
	v_mfma_f32_16x16x32_bf16 v[26:29], v[228:231], v[170:173], v[26:29]
	v_mfma_f32_16x16x32_bf16 v[14:17], v[208:211], v[192:195], v[14:17]
	v_mfma_f32_16x16x32_bf16 v[10:13], v[228:231], v[192:195], v[10:13]
	v_mfma_f32_16x16x32_bf16 v[6:9], v[208:211], v[200:203], v[6:9]
	v_mfma_f32_16x16x32_bf16 v[2:5], v[228:231], v[200:203], v[2:5]
	v_mfma_f32_16x16x32_bf16 v[46:49], v[224:227], v[166:169], v[46:49]
	v_mfma_f32_16x16x32_bf16 v[42:45], v[232:235], v[166:169], v[42:45]
	v_mfma_f32_16x16x32_bf16 v[30:33], v[224:227], v[174:177], v[30:33]
	v_mfma_f32_16x16x32_bf16 v[26:29], v[232:235], v[174:177], v[26:29]
	v_mfma_f32_16x16x32_bf16 v[14:17], v[224:227], v[196:199], v[14:17]
	v_mfma_f32_16x16x32_bf16 v[10:13], v[232:235], v[196:199], v[10:13]
	v_mfma_f32_16x16x32_bf16 v[6:9], v[224:227], v[204:207], v[6:9]
	v_mfma_f32_16x16x32_bf16 v[2:5], v[232:235], v[204:207], v[2:5]
	s_barrier
	s_add_u32 s22, s22, 0x80000
	s_addc_u32 s23, s23, 0
	s_mov_b32 m0, s29
	v_lshl_add_u64 v[208:209], s[22:23], 0, v[136:137]
	ds_read_b128 v[162:165], v144 offset:32768
	ds_read_b128 v[166:169], v144 offset:33792
	ds_read_b128 v[170:173], v144 offset:34816
	ds_read_b128 v[174:177], v144 offset:35840
	ds_read_b128 v[192:195], v144 offset:36864
	ds_read_b128 v[196:199], v144 offset:37888
	ds_read_b128 v[200:203], v144 offset:38912
	ds_read_b128 v[204:207], v144 offset:39936
	global_load_lds_dwordx4 v[208:209], off
	s_mov_b32 m0, s36
	v_lshl_add_u64 v[208:209], s[22:23], 0, v[132:133]
	global_load_lds_dwordx4 v[208:209], off
	s_barrier
	s_waitcnt lgkmcnt(0)
	v_mfma_f32_16x16x32_bf16 v[126:129], v[146:149], v[162:165], v[126:129]
	v_mfma_f32_16x16x32_bf16 v[122:125], v[154:157], v[162:165], v[122:125]
	v_mfma_f32_16x16x32_bf16 v[118:121], v[146:149], v[170:173], v[118:121]
	v_mfma_f32_16x16x32_bf16 v[114:117], v[154:157], v[170:173], v[114:117]
	v_mfma_f32_16x16x32_bf16 v[102:105], v[146:149], v[192:195], v[102:105]
	v_mfma_f32_16x16x32_bf16 v[98:101], v[154:157], v[192:195], v[98:101]
	v_mfma_f32_16x16x32_bf16 v[86:89], v[146:149], v[200:203], v[86:89]
	v_mfma_f32_16x16x32_bf16 v[82:85], v[154:157], v[200:203], v[82:85]
	v_mfma_f32_16x16x32_bf16 v[126:129], v[150:153], v[166:169], v[126:129]
	v_mfma_f32_16x16x32_bf16 v[122:125], v[158:161], v[166:169], v[122:125]
	v_mfma_f32_16x16x32_bf16 v[118:121], v[150:153], v[174:177], v[118:121]
	v_mfma_f32_16x16x32_bf16 v[114:117], v[158:161], v[174:177], v[114:117]
	v_mfma_f32_16x16x32_bf16 v[102:105], v[150:153], v[196:199], v[102:105]
	v_mfma_f32_16x16x32_bf16 v[98:101], v[158:161], v[196:199], v[98:101]
	v_mfma_f32_16x16x32_bf16 v[86:89], v[150:153], v[204:207], v[86:89]
	v_mfma_f32_16x16x32_bf16 v[82:85], v[158:161], v[204:207], v[82:85]
	s_barrier
	s_add_i32 s51, 0, 0x1c000
	s_add_i32 s22, s50, s26
	v_add_u32_e32 v145, s51, v142
	v_lshl_add_u64 v[178:179], v[178:179], 0, s[78:79]
	s_mov_b32 m0, s22
	ds_read_b128 v[208:211], v145
	ds_read_b128 v[224:227], v145 offset:1024
	ds_read_b128 v[228:231], v145 offset:2048
	ds_read_b128 v[232:235], v145 offset:3072
	global_load_lds_dwordx4 v[178:179], off
	s_add_i32 m0, s22, 0x2000
	v_lshl_add_u64 v[178:179], v[212:213], 0, s[78:79]
	global_load_lds_dwordx4 v[178:179], off
	s_mov_b32 m0, s42
	v_lshl_add_u64 v[178:179], v[236:237], 0, s[78:79]
	s_waitcnt lgkmcnt(0)
	s_barrier
	v_mfma_f32_16x16x32_bf16 v[110:113], v[208:211], v[162:165], v[110:113]
	v_mfma_f32_16x16x32_bf16 v[106:109], v[228:231], v[162:165], v[106:109]
	v_mfma_f32_16x16x32_bf16 v[94:97], v[208:211], v[170:173], v[94:97]
	v_mfma_f32_16x16x32_bf16 v[90:93], v[228:231], v[170:173], v[90:93]
	v_mfma_f32_16x16x32_bf16 v[78:81], v[208:211], v[192:195], v[78:81]
	v_mfma_f32_16x16x32_bf16 v[74:77], v[228:231], v[192:195], v[74:77]
	v_mfma_f32_16x16x32_bf16 v[70:73], v[208:211], v[200:203], v[70:73]
	v_mfma_f32_16x16x32_bf16 v[66:69], v[228:231], v[200:203], v[66:69]
	v_mfma_f32_16x16x32_bf16 v[110:113], v[224:227], v[166:169], v[110:113]
	v_mfma_f32_16x16x32_bf16 v[106:109], v[232:235], v[166:169], v[106:109]
	v_mfma_f32_16x16x32_bf16 v[94:97], v[224:227], v[174:177], v[94:97]
	v_mfma_f32_16x16x32_bf16 v[90:93], v[232:235], v[174:177], v[90:93]
	v_mfma_f32_16x16x32_bf16 v[78:81], v[224:227], v[196:199], v[78:81]
	v_mfma_f32_16x16x32_bf16 v[74:77], v[232:235], v[196:199], v[74:77]
	v_mfma_f32_16x16x32_bf16 v[70:73], v[224:227], v[204:207], v[70:73]
	v_mfma_f32_16x16x32_bf16 v[66:69], v[232:235], v[204:207], v[66:69]
	s_barrier
	ds_read_b128 v[162:165], v144 offset:49152
	ds_read_b128 v[166:169], v144 offset:50176
	ds_read_b128 v[170:173], v144 offset:51200
	ds_read_b128 v[174:177], v144 offset:52224
	ds_read_b128 v[192:195], v144 offset:53248
	ds_read_b128 v[196:199], v144 offset:54272
	ds_read_b128 v[200:203], v144 offset:55296
	ds_read_b128 v[204:207], v144 offset:56320
	global_load_lds_dwordx4 v[178:179], off
	s_mov_b32 m0, s43
	v_lshl_add_u64 v[178:179], v[238:239], 0, s[78:79]
	global_load_lds_dwordx4 v[178:179], off
	s_waitcnt vmcnt(10)
	s_barrier
	s_waitcnt lgkmcnt(0)
	v_mfma_f32_16x16x32_bf16 v[62:65], v[146:149], v[162:165], v[62:65]
	v_mfma_f32_16x16x32_bf16 v[58:61], v[154:157], v[162:165], v[58:61]
	v_mfma_f32_16x16x32_bf16 v[54:57], v[146:149], v[170:173], v[54:57]
	v_mfma_f32_16x16x32_bf16 v[50:53], v[154:157], v[170:173], v[50:53]
	v_mfma_f32_16x16x32_bf16 v[38:41], v[146:149], v[192:195], v[38:41]
	v_mfma_f32_16x16x32_bf16 v[34:37], v[154:157], v[192:195], v[34:37]
	v_mfma_f32_16x16x32_bf16 v[22:25], v[146:149], v[200:203], v[22:25]
	v_mfma_f32_16x16x32_bf16 v[18:21], v[154:157], v[200:203], v[18:21]
	v_mfma_f32_16x16x32_bf16 v[62:65], v[150:153], v[166:169], v[62:65]
	v_mfma_f32_16x16x32_bf16 v[58:61], v[158:161], v[166:169], v[58:61]
	v_mfma_f32_16x16x32_bf16 v[54:57], v[150:153], v[174:177], v[54:57]
	v_mfma_f32_16x16x32_bf16 v[50:53], v[158:161], v[174:177], v[50:53]
	v_mfma_f32_16x16x32_bf16 v[38:41], v[150:153], v[196:199], v[38:41]
	v_mfma_f32_16x16x32_bf16 v[34:37], v[158:161], v[196:199], v[34:37]
	v_mfma_f32_16x16x32_bf16 v[22:25], v[150:153], v[204:207], v[22:25]
	v_mfma_f32_16x16x32_bf16 v[18:21], v[158:161], v[204:207], v[18:21]
	s_barrier
	s_add_u32 s22, s38, 0x20080
	s_addc_u32 s23, s39, 0
	s_add_i32 s38, s51, s26
	s_mov_b32 m0, s38
	v_lshl_add_u64 v[146:147], s[22:23], 0, v[134:135]
	global_load_lds_dwordx4 v[146:147], off
	s_add_i32 m0, s38, 0x2000
	v_lshl_add_u64 v[146:147], s[22:23], 0, v[130:131]
	global_load_lds_dwordx4 v[146:147], off
	v_add_u32_e32 v145, 0x10000, v142
	ds_read_b128 v[146:149], v145
	ds_read_b128 v[150:153], v145 offset:1024
	ds_read_b128 v[154:157], v145 offset:2048
	ds_read_b128 v[158:161], v145 offset:3072
	s_add_i32 s49, s49, 2
	s_add_u32 s20, s20, 0x100
	s_addc_u32 s21, s21, 0
	s_add_u32 s47, s47, 0x100
	s_addc_u32 s48, s48, 0
	s_cmp_gt_u32 s49, 5
	s_waitcnt vmcnt(6)
	s_barrier
	v_mfma_f32_16x16x32_bf16 v[46:49], v[208:211], v[162:165], v[46:49]
	v_mfma_f32_16x16x32_bf16 v[42:45], v[228:231], v[162:165], v[42:45]
	v_mfma_f32_16x16x32_bf16 v[30:33], v[208:211], v[170:173], v[30:33]
	v_mfma_f32_16x16x32_bf16 v[26:29], v[228:231], v[170:173], v[26:29]
	v_mfma_f32_16x16x32_bf16 v[14:17], v[208:211], v[192:195], v[14:17]
	v_mfma_f32_16x16x32_bf16 v[10:13], v[228:231], v[192:195], v[10:13]
	v_mfma_f32_16x16x32_bf16 v[6:9], v[208:211], v[200:203], v[6:9]
	v_mfma_f32_16x16x32_bf16 v[2:5], v[228:231], v[200:203], v[2:5]
	v_mfma_f32_16x16x32_bf16 v[46:49], v[224:227], v[166:169], v[46:49]
	v_mfma_f32_16x16x32_bf16 v[42:45], v[232:235], v[166:169], v[42:45]
	v_mfma_f32_16x16x32_bf16 v[30:33], v[224:227], v[174:177], v[30:33]
	v_mfma_f32_16x16x32_bf16 v[26:29], v[232:235], v[174:177], v[26:29]
	v_mfma_f32_16x16x32_bf16 v[14:17], v[224:227], v[196:199], v[14:17]
	v_mfma_f32_16x16x32_bf16 v[10:13], v[232:235], v[196:199], v[10:13]
	v_mfma_f32_16x16x32_bf16 v[6:9], v[224:227], v[204:207], v[6:9]
	v_mfma_f32_16x16x32_bf16 v[2:5], v[232:235], v[204:207], v[2:5]
	s_barrier
	s_cbranch_scc0 .LBB0_127
	s_waitcnt lgkmcnt(0)
	v_lshl_add_u32 v146, s46, 8, v1
	v_lshl_or_b32 v148, s45, 8, v143
	v_ashrrev_i32_e32 v147, 31, v146
	v_readlane_b32 s48, v254, 40
	v_ashrrev_i32_e32 v149, 31, v148
	v_lshlrev_b64 v[150:151], 12, v[146:147]
	v_readlane_b32 s52, v254, 44
	v_readlane_b32 s53, v254, 45
	v_lshlrev_b64 v[148:149], 1, v[148:149]
	s_mov_b32 s19, 0x80000
	v_lshl_add_u64 v[150:151], s[52:53], 0, v[150:151]
	v_lshl_add_u64 v[150:151], v[150:151], 0, v[148:149]
	s_mov_b64 s[20:21], 0x80000
	v_cvt_pk_bf16_f32 v62, v62, v63
	v_cvt_pk_bf16_f32 v63, v64, v65
	v_cvt_pk_bf16_f32 v64, v58, v59
	v_add_co_u32_e32 v58, vcc, s19, v150
	v_cvt_pk_bf16_f32 v70, v70, v71
	v_cvt_pk_bf16_f32 v71, v72, v73
	v_cvt_pk_bf16_f32 v72, v66, v67
	v_lshl_add_u64 v[66:67], v[150:151], 0, s[20:21]
	v_addc_co_u32_e32 v59, vcc, 0, v151, vcc
	v_cvt_pk_bf16_f32 v46, v46, v47
	v_cvt_pk_bf16_f32 v47, v48, v49
	v_cvt_pk_bf16_f32 v48, v42, v43
	v_cvt_pk_bf16_f32 v49, v44, v45
	s_mov_b32 s19, 0x90000
	v_cvt_pk_bf16_f32 v110, v110, v111
	v_cvt_pk_bf16_f32 v111, v112, v113
	v_cvt_pk_bf16_f32 v112, v106, v107
	v_or_b32_e32 v106, 16, v146
	global_store_dwordx4 v[66:67], v[46:49], off offset:256
	s_mov_b64 s[20:21], 0x90000
	v_ashrrev_i32_e32 v107, 31, v106
	v_add_co_u32_e32 v48, vcc, s19, v150
	v_cvt_pk_bf16_f32 v94, v94, v95
	v_cvt_pk_bf16_f32 v95, v96, v97
	v_cvt_pk_bf16_f32 v96, v90, v91
	v_or_b32_e32 v90, 32, v146
	v_lshl_add_u64 v[46:47], v[150:151], 0, s[20:21]
	v_addc_co_u32_e32 v49, vcc, 0, v151, vcc
	v_cvt_pk_bf16_f32 v30, v30, v31
	v_cvt_pk_bf16_f32 v31, v32, v33
	v_cvt_pk_bf16_f32 v32, v26, v27
	v_cvt_pk_bf16_f32 v33, v28, v29
	s_mov_b32 s19, 0xa0000
	v_lshlrev_b64 v[106:107], 12, v[106:107]
	v_ashrrev_i32_e32 v91, 31, v90
	v_cvt_pk_bf16_f32 v78, v78, v79
	v_cvt_pk_bf16_f32 v79, v80, v81
	v_cvt_pk_bf16_f32 v80, v74, v75
	v_or_b32_e32 v74, 48, v146
	global_store_dwordx4 v[46:47], v[30:33], off offset:256
	s_mov_b64 s[20:21], 0xa0000
	v_cvt_pk_bf16_f32 v113, v108, v109
	v_add_co_u32_e32 v32, vcc, s19, v150
	v_lshl_add_u64 v[106:107], s[52:53], 0, v[106:107]
	v_lshlrev_b64 v[90:91], 12, v[90:91]
	v_ashrrev_i32_e32 v75, 31, v74
	v_lshl_add_u64 v[30:31], v[150:151], 0, s[20:21]
	v_addc_co_u32_e32 v33, vcc, 0, v151, vcc
	v_cvt_pk_bf16_f32 v14, v14, v15
	v_cvt_pk_bf16_f32 v15, v16, v17
	v_cvt_pk_bf16_f32 v16, v10, v11
	v_cvt_pk_bf16_f32 v17, v12, v13
	s_mov_b32 s19, 0xb0000
	global_store_dwordx4 v[150:151], v[110:113], off offset:256
	v_cvt_pk_bf16_f32 v97, v92, v93
	v_lshl_add_u64 v[90:91], s[52:53], 0, v[90:91]
	v_lshl_add_u64 v[110:111], v[106:107], 0, v[148:149]
	v_lshlrev_b64 v[74:75], 12, v[74:75]
	global_store_dwordx4 v[30:31], v[14:17], off offset:256
	global_store_dwordx4 v[110:111], v[94:97], off offset:256
	v_cvt_pk_bf16_f32 v81, v76, v77
	v_add_co_u32_e32 v16, vcc, s19, v150
	v_lshl_add_u64 v[94:95], v[90:91], 0, v[148:149]
	v_lshl_add_u64 v[74:75], s[52:53], 0, v[74:75]
	s_mov_b64 s[20:21], 0xb0000
	v_addc_co_u32_e32 v17, vcc, 0, v151, vcc
	v_cvt_pk_bf16_f32 v126, v126, v127
	v_cvt_pk_bf16_f32 v127, v128, v129
	v_cvt_pk_bf16_f32 v128, v122, v123
	v_cvt_pk_bf16_f32 v129, v124, v125
	v_cvt_pk_bf16_f32 v106, v118, v119
	v_cvt_pk_bf16_f32 v107, v120, v121
	v_cvt_pk_bf16_f32 v108, v114, v115
	v_cvt_pk_bf16_f32 v109, v116, v117
	v_cvt_pk_bf16_f32 v90, v102, v103
	v_cvt_pk_bf16_f32 v91, v104, v105
	v_cvt_pk_bf16_f32 v92, v98, v99
	v_cvt_pk_bf16_f32 v93, v100, v101
	global_store_dwordx4 v[94:95], v[78:81], off offset:256
	v_cvt_pk_bf16_f32 v76, v82, v83
	v_cvt_pk_bf16_f32 v77, v84, v85
	v_lshl_add_u64 v[78:79], v[74:75], 0, v[148:149]
	v_cvt_pk_bf16_f32 v74, v86, v87
	v_cvt_pk_bf16_f32 v75, v88, v89
	v_cvt_pk_bf16_f32 v73, v68, v69
	v_cvt_pk_bf16_f32 v65, v60, v61
	v_cvt_pk_bf16_f32 v42, v54, v55
	v_cvt_pk_bf16_f32 v43, v56, v57
	v_cvt_pk_bf16_f32 v44, v50, v51
	v_cvt_pk_bf16_f32 v45, v52, v53
	v_cvt_pk_bf16_f32 v26, v38, v39
	v_cvt_pk_bf16_f32 v27, v40, v41
	v_cvt_pk_bf16_f32 v28, v34, v35
	v_cvt_pk_bf16_f32 v29, v36, v37
	v_lshl_add_u64 v[14:15], v[150:151], 0, s[20:21]
	v_cvt_pk_bf16_f32 v10, v22, v23
	v_cvt_pk_bf16_f32 v11, v24, v25
	v_cvt_pk_bf16_f32 v12, v18, v19
	v_cvt_pk_bf16_f32 v13, v20, v21
	v_cvt_pk_bf16_f32 v6, v6, v7
	v_cvt_pk_bf16_f32 v7, v8, v9
	v_cvt_pk_bf16_f32 v8, v2, v3
	v_cvt_pk_bf16_f32 v9, v4, v5
	s_and_b64 vcc, exec, s[0:1]
	s_mov_b32 s45, s18
	s_mov_b32 s46, s30
	s_mov_b64 s[22:23], s[82:83]
	s_mov_b64 s[20:21], s[80:81]
	s_mov_b32 s64, 0x800000
	s_movk_i32 s65, 0x1fff
	v_readlane_b32 s49, v254, 41
	v_readlane_b32 s50, v254, 42
	v_readlane_b32 s51, v254, 43
	v_readlane_b32 s54, v254, 46
	v_readlane_b32 s55, v254, 47
	v_readlane_b32 s56, v254, 48
	v_readlane_b32 s57, v254, 49
	v_readlane_b32 s58, v254, 50
	v_readlane_b32 s59, v254, 51
	v_readlane_b32 s60, v254, 52
	v_readlane_b32 s61, v254, 53
	v_readlane_b32 s62, v254, 54
	v_readlane_b32 s63, v254, 55
	global_store_dwordx4 v[150:151], v[126:129], off
	global_store_dwordx4 v[110:111], v[106:109], off
	global_store_dwordx4 v[94:95], v[90:93], off
	global_store_dwordx4 v[78:79], v[74:77], off
	global_store_dwordx4 v[78:79], v[70:73], off offset:256
	global_store_dwordx4 v[58:59], v[62:65], off
	global_store_dwordx4 v[48:49], v[42:45], off
	global_store_dwordx4 v[32:33], v[26:29], off
	global_store_dwordx4 v[16:17], v[10:13], off
	global_store_dwordx4 v[14:15], v[6:9], off offset:256
	s_cbranch_vccz .LBB0_118
	s_waitcnt vmcnt(0)
	v_readlane_b32 s44, v255, 30
	s_mov_b32 s66, s90
	s_cmpk_gt_u32 s25, 0xff
	v_readlane_b32 s45, v255, 31
	v_readlane_b32 s42, v255, 32
	s_cbranch_scc1 .LBB0_131
	s_barrier

.LBB0_240:
	s_add_u32 s22, s80, 0xfff80080
	s_addc_u32 s23, s81, -1
	s_cmp_eq_u32 s51, 28
	s_cselect_b32 s23, s21, s23
	s_cselect_b32 s22, s47, s22
	s_cselect_b32 s83, s19, s50
	s_cselect_b32 s82, s48, s49
	v_lshl_add_u64 v[178:179], s[80:81], 0, v[134:135]
	s_add_i32 m0, s27, 0xc000
	ds_read_b128 v[158:161], v140
	ds_read_b128 v[162:165], v140 offset:1024
	ds_read_b128 v[166:169], v140 offset:2048
	ds_read_b128 v[170:173], v140 offset:3072
	ds_read_b128 v[174:177], v140 offset:4096
	ds_read_b128 v[192:195], v140 offset:5120
	ds_read_b128 v[196:199], v140 offset:6144
	ds_read_b128 v[200:203], v140 offset:7168
	global_load_lds_dwordx4 v[178:179], off
	s_add_i32 m0, s27, 0xe000
	v_lshl_add_u64 v[178:179], s[80:81], 0, v[136:137]
	global_load_lds_dwordx4 v[178:179], off
	s_barrier
	s_waitcnt lgkmcnt(0)
	v_mfma_f32_16x16x32_bf16 v[126:129], v[142:145], v[158:161], v[126:129]
	v_mfma_f32_16x16x32_bf16 v[122:125], v[150:153], v[158:161], v[122:125]
	v_mfma_f32_16x16x32_bf16 v[118:121], v[142:145], v[166:169], v[118:121]
	v_mfma_f32_16x16x32_bf16 v[114:117], v[150:153], v[166:169], v[114:117]
	v_mfma_f32_16x16x32_bf16 v[110:113], v[142:145], v[174:177], v[110:113]
	v_mfma_f32_16x16x32_bf16 v[102:105], v[150:153], v[174:177], v[102:105]
	v_mfma_f32_16x16x32_bf16 v[94:97], v[142:145], v[196:199], v[94:97]
	v_mfma_f32_16x16x32_bf16 v[86:89], v[150:153], v[196:199], v[86:89]
	v_mfma_f32_16x16x32_bf16 v[126:129], v[146:149], v[162:165], v[126:129]
	v_mfma_f32_16x16x32_bf16 v[122:125], v[154:157], v[162:165], v[122:125]
	v_mfma_f32_16x16x32_bf16 v[118:121], v[146:149], v[170:173], v[118:121]
	v_mfma_f32_16x16x32_bf16 v[114:117], v[154:157], v[170:173], v[114:117]
	v_mfma_f32_16x16x32_bf16 v[110:113], v[146:149], v[192:195], v[110:113]
	v_mfma_f32_16x16x32_bf16 v[102:105], v[154:157], v[192:195], v[102:105]
	v_mfma_f32_16x16x32_bf16 v[94:97], v[146:149], v[200:203], v[94:97]
	v_mfma_f32_16x16x32_bf16 v[86:89], v[154:157], v[200:203], v[86:89]
	s_barrier
	s_add_i32 s52, s26, 0x10000
	v_add_u32_e32 v141, 0x14000, v138
	v_lshl_add_u64 v[178:179], s[82:83], 0, v[132:133]
	s_mov_b32 m0, s52
	ds_read_b128 v[204:207], v141
	ds_read_b128 v[208:211], v141 offset:1024
	ds_read_b128 v[224:227], v141 offset:2048
	ds_read_b128 v[228:231], v141 offset:3072
	global_load_lds_dwordx4 v[178:179], off
	s_add_i32 m0, s52, 0x2000
	v_lshl_add_u64 v[212:213], s[82:83], 0, v[130:131]
	global_load_lds_dwordx4 v[212:213], off
	s_mov_b32 m0, s27
	v_lshl_add_u64 v[232:233], s[22:23], 0, v[132:133]
	s_waitcnt lgkmcnt(0)
	s_barrier
	v_mfma_f32_16x16x32_bf16 v[106:109], v[204:207], v[158:161], v[106:109]
	v_mfma_f32_16x16x32_bf16 v[98:101], v[224:227], v[158:161], v[98:101]
	v_mfma_f32_16x16x32_bf16 v[90:93], v[204:207], v[166:169], v[90:93]
	v_mfma_f32_16x16x32_bf16 v[82:85], v[224:227], v[166:169], v[82:85]
	v_mfma_f32_16x16x32_bf16 v[78:81], v[204:207], v[174:177], v[78:81]
	v_mfma_f32_16x16x32_bf16 v[74:77], v[224:227], v[174:177], v[74:77]
	v_mfma_f32_16x16x32_bf16 v[70:73], v[204:207], v[196:199], v[70:73]
	v_mfma_f32_16x16x32_bf16 v[66:69], v[224:227], v[196:199], v[66:69]
	v_mfma_f32_16x16x32_bf16 v[106:109], v[208:211], v[162:165], v[106:109]
	v_mfma_f32_16x16x32_bf16 v[98:101], v[228:231], v[162:165], v[98:101]
	v_mfma_f32_16x16x32_bf16 v[90:93], v[208:211], v[170:173], v[90:93]
	v_mfma_f32_16x16x32_bf16 v[82:85], v[228:231], v[170:173], v[82:85]
	v_mfma_f32_16x16x32_bf16 v[78:81], v[208:211], v[192:195], v[78:81]
	v_mfma_f32_16x16x32_bf16 v[74:77], v[228:231], v[192:195], v[74:77]
	v_mfma_f32_16x16x32_bf16 v[70:73], v[208:211], v[200:203], v[70:73]
	v_mfma_f32_16x16x32_bf16 v[66:69], v[228:231], v[200:203], v[66:69]
	s_barrier
	ds_read_b128 v[158:161], v140 offset:16384
	ds_read_b128 v[162:165], v140 offset:17408
	ds_read_b128 v[166:169], v140 offset:18432
	ds_read_b128 v[170:173], v140 offset:19456
	ds_read_b128 v[174:177], v140 offset:20480
	ds_read_b128 v[192:195], v140 offset:21504
	ds_read_b128 v[196:199], v140 offset:22528
	ds_read_b128 v[200:203], v140 offset:23552
	global_load_lds_dwordx4 v[232:233], off
	s_mov_b32 m0, s28
	v_lshl_add_u64 v[234:235], s[22:23], 0, v[130:131]
	global_load_lds_dwordx4 v[234:235], off
	s_waitcnt vmcnt(10)
	s_barrier
	s_waitcnt lgkmcnt(0)
	v_mfma_f32_16x16x32_bf16 v[62:65], v[142:145], v[158:161], v[62:65]
	v_mfma_f32_16x16x32_bf16 v[58:61], v[150:153], v[158:161], v[58:61]
	v_mfma_f32_16x16x32_bf16 v[54:57], v[142:145], v[166:169], v[54:57]
	v_mfma_f32_16x16x32_bf16 v[50:53], v[150:153], v[166:169], v[50:53]
	v_mfma_f32_16x16x32_bf16 v[46:49], v[142:145], v[174:177], v[46:49]
	v_mfma_f32_16x16x32_bf16 v[38:41], v[150:153], v[174:177], v[38:41]
	v_mfma_f32_16x16x32_bf16 v[30:33], v[142:145], v[196:199], v[30:33]
	v_mfma_f32_16x16x32_bf16 v[22:25], v[150:153], v[196:199], v[22:25]
	v_mfma_f32_16x16x32_bf16 v[62:65], v[146:149], v[162:165], v[62:65]
	v_mfma_f32_16x16x32_bf16 v[58:61], v[154:157], v[162:165], v[58:61]
	v_mfma_f32_16x16x32_bf16 v[54:57], v[146:149], v[170:173], v[54:57]
	v_mfma_f32_16x16x32_bf16 v[50:53], v[154:157], v[170:173], v[50:53]
	v_mfma_f32_16x16x32_bf16 v[46:49], v[146:149], v[192:195], v[46:49]
	v_mfma_f32_16x16x32_bf16 v[38:41], v[154:157], v[192:195], v[38:41]
	v_mfma_f32_16x16x32_bf16 v[30:33], v[146:149], v[200:203], v[30:33]
	v_mfma_f32_16x16x32_bf16 v[22:25], v[154:157], v[200:203], v[22:25]
	s_barrier
	s_add_u32 s52, s82, 0x80000
	s_addc_u32 s53, s83, 0
	s_add_i32 s54, s26, 0x14000
	s_mov_b32 m0, s54
	v_lshl_add_u64 v[142:143], s[52:53], 0, v[132:133]
	global_load_lds_dwordx4 v[142:143], off
	s_add_i32 m0, s54, 0x2000
	v_lshl_add_u64 v[142:143], s[52:53], 0, v[130:131]
	global_load_lds_dwordx4 v[142:143], off
	v_add_u32_e32 v141, 0x18000, v138
	ds_read_b128 v[142:145], v141
	ds_read_b128 v[146:149], v141 offset:1024
	ds_read_b128 v[150:153], v141 offset:2048
	ds_read_b128 v[154:157], v141 offset:3072
	s_add_i32 s52, 0, 0x18000
	s_waitcnt vmcnt(6)
	s_barrier
	v_mfma_f32_16x16x32_bf16 v[42:45], v[204:207], v[158:161], v[42:45]
	v_mfma_f32_16x16x32_bf16 v[34:37], v[224:227], v[158:161], v[34:37]
	v_mfma_f32_16x16x32_bf16 v[26:29], v[204:207], v[166:169], v[26:29]
	v_mfma_f32_16x16x32_bf16 v[18:21], v[224:227], v[166:169], v[18:21]
	v_mfma_f32_16x16x32_bf16 v[14:17], v[204:207], v[174:177], v[14:17]
	v_mfma_f32_16x16x32_bf16 v[10:13], v[224:227], v[174:177], v[10:13]
	v_mfma_f32_16x16x32_bf16 v[6:9], v[204:207], v[196:199], v[6:9]
	v_mfma_f32_16x16x32_bf16 v[2:5], v[224:227], v[196:199], v[2:5]
	v_mfma_f32_16x16x32_bf16 v[42:45], v[208:211], v[162:165], v[42:45]
	v_mfma_f32_16x16x32_bf16 v[34:37], v[228:231], v[162:165], v[34:37]
	v_mfma_f32_16x16x32_bf16 v[26:29], v[208:211], v[170:173], v[26:29]
	v_mfma_f32_16x16x32_bf16 v[18:21], v[228:231], v[170:173], v[18:21]
	v_mfma_f32_16x16x32_bf16 v[14:17], v[208:211], v[192:195], v[14:17]
	v_mfma_f32_16x16x32_bf16 v[10:13], v[228:231], v[192:195], v[10:13]
	v_mfma_f32_16x16x32_bf16 v[6:9], v[208:211], v[200:203], v[6:9]
	v_mfma_f32_16x16x32_bf16 v[2:5], v[228:231], v[200:203], v[2:5]
	s_barrier
	s_add_u32 s22, s22, 0x80000
	s_addc_u32 s23, s23, 0
	s_mov_b32 m0, s29
	v_lshl_add_u64 v[204:205], s[22:23], 0, v[132:133]
	ds_read_b128 v[158:161], v140 offset:32768
	ds_read_b128 v[162:165], v140 offset:33792
	ds_read_b128 v[166:169], v140 offset:34816
	ds_read_b128 v[170:173], v140 offset:35840
	ds_read_b128 v[174:177], v140 offset:36864
	ds_read_b128 v[192:195], v140 offset:37888
	ds_read_b128 v[196:199], v140 offset:38912
	ds_read_b128 v[200:203], v140 offset:39936
	global_load_lds_dwordx4 v[204:205], off
	s_mov_b32 m0, s36
	v_lshl_add_u64 v[204:205], s[22:23], 0, v[130:131]
	global_load_lds_dwordx4 v[204:205], off
	s_barrier
	s_waitcnt lgkmcnt(0)
	v_mfma_f32_16x16x32_bf16 v[126:129], v[142:145], v[158:161], v[126:129]
	v_mfma_f32_16x16x32_bf16 v[122:125], v[150:153], v[158:161], v[122:125]
	v_mfma_f32_16x16x32_bf16 v[118:121], v[142:145], v[166:169], v[118:121]
	v_mfma_f32_16x16x32_bf16 v[114:117], v[150:153], v[166:169], v[114:117]
	v_mfma_f32_16x16x32_bf16 v[110:113], v[142:145], v[174:177], v[110:113]
	v_mfma_f32_16x16x32_bf16 v[102:105], v[150:153], v[174:177], v[102:105]
	v_mfma_f32_16x16x32_bf16 v[94:97], v[142:145], v[196:199], v[94:97]
	v_mfma_f32_16x16x32_bf16 v[86:89], v[150:153], v[196:199], v[86:89]
	v_mfma_f32_16x16x32_bf16 v[126:129], v[146:149], v[162:165], v[126:129]
	v_mfma_f32_16x16x32_bf16 v[122:125], v[154:157], v[162:165], v[122:125]
	v_mfma_f32_16x16x32_bf16 v[118:121], v[146:149], v[170:173], v[118:121]
	v_mfma_f32_16x16x32_bf16 v[114:117], v[154:157], v[170:173], v[114:117]
	v_mfma_f32_16x16x32_bf16 v[110:113], v[146:149], v[192:195], v[110:113]
	v_mfma_f32_16x16x32_bf16 v[102:105], v[154:157], v[192:195], v[102:105]
	v_mfma_f32_16x16x32_bf16 v[94:97], v[146:149], v[200:203], v[94:97]
	v_mfma_f32_16x16x32_bf16 v[86:89], v[154:157], v[200:203], v[86:89]
	s_barrier
	s_add_i32 s53, 0, 0x1c000
	s_add_i32 s22, s52, s26
	v_add_u32_e32 v141, s53, v138
	v_lshl_add_u64 v[178:179], v[178:179], 0, s[78:79]
	s_mov_b32 m0, s22
	ds_read_b128 v[204:207], v141
	ds_read_b128 v[208:211], v141 offset:1024
	ds_read_b128 v[224:227], v141 offset:2048
	ds_read_b128 v[228:231], v141 offset:3072
	global_load_lds_dwordx4 v[178:179], off
	s_add_i32 m0, s22, 0x2000
	v_lshl_add_u64 v[178:179], v[212:213], 0, s[78:79]
	global_load_lds_dwordx4 v[178:179], off
	s_mov_b32 m0, s42
	v_lshl_add_u64 v[178:179], v[232:233], 0, s[78:79]
	s_waitcnt lgkmcnt(0)
	s_barrier
	v_mfma_f32_16x16x32_bf16 v[106:109], v[204:207], v[158:161], v[106:109]
	v_mfma_f32_16x16x32_bf16 v[98:101], v[224:227], v[158:161], v[98:101]
	v_mfma_f32_16x16x32_bf16 v[90:93], v[204:207], v[166:169], v[90:93]
	v_mfma_f32_16x16x32_bf16 v[82:85], v[224:227], v[166:169], v[82:85]
	v_mfma_f32_16x16x32_bf16 v[78:81], v[204:207], v[174:177], v[78:81]
	v_mfma_f32_16x16x32_bf16 v[74:77], v[224:227], v[174:177], v[74:77]
	v_mfma_f32_16x16x32_bf16 v[70:73], v[204:207], v[196:199], v[70:73]
	v_mfma_f32_16x16x32_bf16 v[66:69], v[224:227], v[196:199], v[66:69]
	v_mfma_f32_16x16x32_bf16 v[106:109], v[208:211], v[162:165], v[106:109]
	v_mfma_f32_16x16x32_bf16 v[98:101], v[228:231], v[162:165], v[98:101]
	v_mfma_f32_16x16x32_bf16 v[90:93], v[208:211], v[170:173], v[90:93]
	v_mfma_f32_16x16x32_bf16 v[82:85], v[228:231], v[170:173], v[82:85]
	v_mfma_f32_16x16x32_bf16 v[78:81], v[208:211], v[192:195], v[78:81]
	v_mfma_f32_16x16x32_bf16 v[74:77], v[228:231], v[192:195], v[74:77]
	v_mfma_f32_16x16x32_bf16 v[70:73], v[208:211], v[200:203], v[70:73]
	v_mfma_f32_16x16x32_bf16 v[66:69], v[228:231], v[200:203], v[66:69]
	s_barrier
	ds_read_b128 v[158:161], v140 offset:49152
	ds_read_b128 v[162:165], v140 offset:50176
	ds_read_b128 v[166:169], v140 offset:51200
	ds_read_b128 v[170:173], v140 offset:52224
	ds_read_b128 v[174:177], v140 offset:53248
	ds_read_b128 v[192:195], v140 offset:54272
	ds_read_b128 v[196:199], v140 offset:55296
	ds_read_b128 v[200:203], v140 offset:56320
	global_load_lds_dwordx4 v[178:179], off
	s_mov_b32 m0, s43
	v_lshl_add_u64 v[178:179], v[234:235], 0, s[78:79]
	global_load_lds_dwordx4 v[178:179], off
	s_waitcnt vmcnt(10)
	s_barrier
	s_waitcnt lgkmcnt(0)
	v_mfma_f32_16x16x32_bf16 v[62:65], v[142:145], v[158:161], v[62:65]
	v_mfma_f32_16x16x32_bf16 v[58:61], v[150:153], v[158:161], v[58:61]
	v_mfma_f32_16x16x32_bf16 v[54:57], v[142:145], v[166:169], v[54:57]
	v_mfma_f32_16x16x32_bf16 v[50:53], v[150:153], v[166:169], v[50:53]
	v_mfma_f32_16x16x32_bf16 v[46:49], v[142:145], v[174:177], v[46:49]
	v_mfma_f32_16x16x32_bf16 v[38:41], v[150:153], v[174:177], v[38:41]
	v_mfma_f32_16x16x32_bf16 v[30:33], v[142:145], v[196:199], v[30:33]
	v_mfma_f32_16x16x32_bf16 v[22:25], v[150:153], v[196:199], v[22:25]
	v_mfma_f32_16x16x32_bf16 v[62:65], v[146:149], v[162:165], v[62:65]
	v_mfma_f32_16x16x32_bf16 v[58:61], v[154:157], v[162:165], v[58:61]
	v_mfma_f32_16x16x32_bf16 v[54:57], v[146:149], v[170:173], v[54:57]
	v_mfma_f32_16x16x32_bf16 v[50:53], v[154:157], v[170:173], v[50:53]
	v_mfma_f32_16x16x32_bf16 v[46:49], v[146:149], v[192:195], v[46:49]
	v_mfma_f32_16x16x32_bf16 v[38:41], v[154:157], v[192:195], v[38:41]
	v_mfma_f32_16x16x32_bf16 v[30:33], v[146:149], v[200:203], v[30:33]
	v_mfma_f32_16x16x32_bf16 v[22:25], v[154:157], v[200:203], v[22:25]
	s_barrier
	s_add_u32 s22, s82, 0x80080
	s_addc_u32 s23, s83, 0
	s_add_i32 s52, s53, s26
	s_mov_b32 m0, s52
	v_lshl_add_u64 v[142:143], s[22:23], 0, v[132:133]
	global_load_lds_dwordx4 v[142:143], off
	s_add_i32 m0, s52, 0x2000
	v_lshl_add_u64 v[142:143], s[22:23], 0, v[130:131]
	global_load_lds_dwordx4 v[142:143], off
	v_add_u32_e32 v141, 0x10000, v138
	ds_read_b128 v[142:145], v141
	ds_read_b128 v[146:149], v141 offset:1024
	ds_read_b128 v[150:153], v141 offset:2048
	ds_read_b128 v[154:157], v141 offset:3072
	s_add_i32 s51, s51, 2
	s_add_u32 s80, s80, 0x100
	s_addc_u32 s81, s81, 0
	s_add_u32 s49, s49, 0x100
	s_addc_u32 s50, s50, 0
	s_cmp_gt_u32 s51, 29
	s_waitcnt vmcnt(6)
	s_barrier
	v_mfma_f32_16x16x32_bf16 v[42:45], v[204:207], v[158:161], v[42:45]
	v_mfma_f32_16x16x32_bf16 v[34:37], v[224:227], v[158:161], v[34:37]
	v_mfma_f32_16x16x32_bf16 v[26:29], v[204:207], v[166:169], v[26:29]
	v_mfma_f32_16x16x32_bf16 v[18:21], v[224:227], v[166:169], v[18:21]
	v_mfma_f32_16x16x32_bf16 v[14:17], v[204:207], v[174:177], v[14:17]
	v_mfma_f32_16x16x32_bf16 v[10:13], v[224:227], v[174:177], v[10:13]
	v_mfma_f32_16x16x32_bf16 v[6:9], v[204:207], v[196:199], v[6:9]
	v_mfma_f32_16x16x32_bf16 v[2:5], v[224:227], v[196:199], v[2:5]
	v_mfma_f32_16x16x32_bf16 v[42:45], v[208:211], v[162:165], v[42:45]
	v_mfma_f32_16x16x32_bf16 v[34:37], v[228:231], v[162:165], v[34:37]
	v_mfma_f32_16x16x32_bf16 v[26:29], v[208:211], v[170:173], v[26:29]
	v_mfma_f32_16x16x32_bf16 v[18:21], v[228:231], v[170:173], v[18:21]
	v_mfma_f32_16x16x32_bf16 v[14:17], v[208:211], v[192:195], v[14:17]
	v_mfma_f32_16x16x32_bf16 v[10:13], v[228:231], v[192:195], v[10:13]
	v_mfma_f32_16x16x32_bf16 v[6:9], v[208:211], v[200:203], v[6:9]
	v_mfma_f32_16x16x32_bf16 v[2:5], v[228:231], v[200:203], v[2:5]
	s_barrier
	s_cbranch_scc0 .LBB0_240
	s_waitcnt lgkmcnt(0)
	v_readlane_b32 s48, v254, 40
	v_lshl_or_b32 v142, s45, 8, v139
	v_readlane_b32 s52, v254, 44
	v_readlane_b32 s53, v254, 45
	v_lshl_add_u32 v141, s46, 8, v1
	v_ashrrev_i32_e32 v143, 31, v142
	v_mov_b64_e32 v[144:145], s[52:53]
	s_movk_i32 s19, 0x1400
	v_mad_i64_i32 v[146:147], s[22:23], v141, s19, v[144:145]
	v_lshlrev_b64 v[142:143], 2, v[142:143]
	v_lshl_add_u64 v[146:147], v[146:147], 0, v[142:143]
	global_store_dwordx4 v[146:147], v[126:129], off
	global_store_dwordx4 v[146:147], v[122:125], off offset:64
	global_store_dwordx4 v[146:147], v[106:109], off offset:512
	global_store_dwordx4 v[146:147], v[98:101], off offset:576
	s_movk_i32 s94, 0x1400
	s_and_b64 vcc, exec, s[0:1]
	v_or_b32_e32 v98, 16, v141
	v_mad_i64_i32 v[98:99], s[22:23], v98, s19, v[144:145]
	v_lshl_add_u64 v[98:99], v[98:99], 0, v[142:143]
	global_store_dwordx4 v[98:99], v[118:121], off
	global_store_dwordx4 v[98:99], v[114:117], off offset:64
	global_store_dwordx4 v[98:99], v[90:93], off offset:512
	global_store_dwordx4 v[98:99], v[82:85], off offset:576
	s_mov_b32 s45, s18
	s_mov_b32 s46, s20
	v_or_b32_e32 v82, 32, v141
	v_mad_i64_i32 v[82:83], s[22:23], v82, s19, v[144:145]
	v_lshl_add_u64 v[82:83], v[82:83], 0, v[142:143]
	global_store_dwordx4 v[82:83], v[110:113], off
	global_store_dwordx4 v[82:83], v[102:105], off offset:64
	global_store_dwordx4 v[82:83], v[78:81], off offset:512
	global_store_dwordx4 v[82:83], v[74:77], off offset:576
	s_mov_b64 s[80:81], s[30:31]
	v_readlane_b32 s49, v254, 41
	v_or_b32_e32 v74, 48, v141
	v_mad_i64_i32 v[74:75], s[22:23], v74, s19, v[144:145]
	v_lshl_add_u64 v[74:75], v[74:75], 0, v[142:143]
	global_store_dwordx4 v[74:75], v[94:97], off
	global_store_dwordx4 v[74:75], v[86:89], off offset:64
	global_store_dwordx4 v[74:75], v[70:73], off offset:512
	global_store_dwordx4 v[74:75], v[66:69], off offset:576
	v_readlane_b32 s50, v254, 42
	v_readlane_b32 s51, v254, 43
	v_add_u32_e32 v66, 0x80, v141
	v_mad_i64_i32 v[66:67], s[22:23], v66, s19, v[144:145]
	v_lshl_add_u64 v[66:67], v[66:67], 0, v[142:143]
	global_store_dwordx4 v[66:67], v[62:65], off
	global_store_dwordx4 v[66:67], v[58:61], off offset:64
	global_store_dwordx4 v[66:67], v[42:45], off offset:512
	global_store_dwordx4 v[66:67], v[34:37], off offset:576
	v_readlane_b32 s54, v254, 46
	v_readlane_b32 s55, v254, 47
	v_add_u32_e32 v34, 0x90, v141
	v_mad_i64_i32 v[34:35], s[22:23], v34, s19, v[144:145]
	v_lshl_add_u64 v[34:35], v[34:35], 0, v[142:143]
	global_store_dwordx4 v[34:35], v[54:57], off
	global_store_dwordx4 v[34:35], v[50:53], off offset:64
	global_store_dwordx4 v[34:35], v[26:29], off offset:512
	global_store_dwordx4 v[34:35], v[18:21], off offset:576
	v_readlane_b32 s56, v254, 48
	v_readlane_b32 s57, v254, 49
	v_add_u32_e32 v18, 0xa0, v141
	v_mad_i64_i32 v[18:19], s[22:23], v18, s19, v[144:145]
	v_lshl_add_u64 v[18:19], v[18:19], 0, v[142:143]
	global_store_dwordx4 v[18:19], v[46:49], off
	global_store_dwordx4 v[18:19], v[38:41], off offset:64
	global_store_dwordx4 v[18:19], v[14:17], off offset:512
	global_store_dwordx4 v[18:19], v[10:13], off offset:576
	v_readlane_b32 s58, v254, 50
	v_readlane_b32 s59, v254, 51
	v_add_u32_e32 v10, 0xb0, v141
	v_mad_i64_i32 v[10:11], s[22:23], v10, s19, v[144:145]
	v_lshl_add_u64 v[10:11], v[10:11], 0, v[142:143]
	s_mov_b64 s[22:23], s[38:39]
	v_readlane_b32 s60, v254, 52
	v_readlane_b32 s61, v254, 53
	v_readlane_b32 s62, v254, 54
	v_readlane_b32 s63, v254, 55
	global_store_dwordx4 v[10:11], v[30:33], off
	global_store_dwordx4 v[10:11], v[22:25], off offset:64
	global_store_dwordx4 v[10:11], v[6:9], off offset:512
	global_store_dwordx4 v[10:11], v[2:5], off offset:576
	s_cbranch_vccz .LBB0_237
	s_waitcnt vmcnt(0)
	v_readlane_b32 s44, v255, 30
	s_cmpk_gt_u32 s25, 0xff
	v_readlane_b32 s45, v255, 31
	v_readlane_b32 s42, v255, 32
	s_cbranch_scc1 .LBB0_244
	s_barrier

.LBB0_357:
	s_add_u32 s22, s20, 0xfffe0080
	s_addc_u32 s23, s21, -1
	s_cmp_eq_u32 s51, 4
	s_cselect_b32 s23, s31, s23
	s_cselect_b32 s22, s47, s22
	s_cselect_b32 s85, s19, s50
	s_cselect_b32 s84, s48, s49
	v_lshl_add_u64 v[178:179], s[20:21], 0, v[138:139]
	s_add_i32 m0, s27, 0xc000
	ds_read_b128 v[162:165], v144
	ds_read_b128 v[166:169], v144 offset:1024
	ds_read_b128 v[170:173], v144 offset:2048
	ds_read_b128 v[174:177], v144 offset:3072
	ds_read_b128 v[192:195], v144 offset:4096
	ds_read_b128 v[196:199], v144 offset:5120
	ds_read_b128 v[200:203], v144 offset:6144
	ds_read_b128 v[204:207], v144 offset:7168
	global_load_lds_dwordx4 v[178:179], off
	s_add_i32 m0, s27, 0xe000
	v_lshl_add_u64 v[178:179], s[20:21], 0, v[140:141]
	global_load_lds_dwordx4 v[178:179], off
	s_barrier
	s_waitcnt lgkmcnt(0)
	v_mfma_f32_16x16x32_bf16 v[126:129], v[146:149], v[162:165], v[126:129]
	v_mfma_f32_16x16x32_bf16 v[122:125], v[154:157], v[162:165], v[122:125]
	v_mfma_f32_16x16x32_bf16 v[118:121], v[146:149], v[170:173], v[118:121]
	v_mfma_f32_16x16x32_bf16 v[114:117], v[154:157], v[170:173], v[114:117]
	v_mfma_f32_16x16x32_bf16 v[102:105], v[146:149], v[192:195], v[102:105]
	v_mfma_f32_16x16x32_bf16 v[98:101], v[154:157], v[192:195], v[98:101]
	v_mfma_f32_16x16x32_bf16 v[86:89], v[146:149], v[200:203], v[86:89]
	v_mfma_f32_16x16x32_bf16 v[82:85], v[154:157], v[200:203], v[82:85]
	v_mfma_f32_16x16x32_bf16 v[126:129], v[150:153], v[166:169], v[126:129]
	v_mfma_f32_16x16x32_bf16 v[122:125], v[158:161], v[166:169], v[122:125]
	v_mfma_f32_16x16x32_bf16 v[118:121], v[150:153], v[174:177], v[118:121]
	v_mfma_f32_16x16x32_bf16 v[114:117], v[158:161], v[174:177], v[114:117]
	v_mfma_f32_16x16x32_bf16 v[102:105], v[150:153], v[196:199], v[102:105]
	v_mfma_f32_16x16x32_bf16 v[98:101], v[158:161], v[196:199], v[98:101]
	v_mfma_f32_16x16x32_bf16 v[86:89], v[150:153], v[204:207], v[86:89]
	v_mfma_f32_16x16x32_bf16 v[82:85], v[158:161], v[204:207], v[82:85]
	s_barrier
	s_add_i32 s52, s26, 0x10000
	v_add_u32_e32 v145, 0x14000, v142
	v_lshl_add_u64 v[178:179], s[84:85], 0, v[134:135]
	s_mov_b32 m0, s52
	ds_read_b128 v[208:211], v145
	ds_read_b128 v[224:227], v145 offset:1024
	ds_read_b128 v[228:231], v145 offset:2048
	ds_read_b128 v[232:235], v145 offset:3072
	global_load_lds_dwordx4 v[178:179], off
	s_add_i32 m0, s52, 0x2000
	v_lshl_add_u64 v[212:213], s[84:85], 0, v[130:131]
	global_load_lds_dwordx4 v[212:213], off
	s_mov_b32 m0, s27
	v_lshl_add_u64 v[236:237], s[22:23], 0, v[136:137]
	s_waitcnt lgkmcnt(0)
	s_barrier
	v_mfma_f32_16x16x32_bf16 v[110:113], v[208:211], v[162:165], v[110:113]
	v_mfma_f32_16x16x32_bf16 v[106:109], v[228:231], v[162:165], v[106:109]
	v_mfma_f32_16x16x32_bf16 v[94:97], v[208:211], v[170:173], v[94:97]
	v_mfma_f32_16x16x32_bf16 v[90:93], v[228:231], v[170:173], v[90:93]
	v_mfma_f32_16x16x32_bf16 v[78:81], v[208:211], v[192:195], v[78:81]
	v_mfma_f32_16x16x32_bf16 v[74:77], v[228:231], v[192:195], v[74:77]
	v_mfma_f32_16x16x32_bf16 v[70:73], v[208:211], v[200:203], v[70:73]
	v_mfma_f32_16x16x32_bf16 v[66:69], v[228:231], v[200:203], v[66:69]
	v_mfma_f32_16x16x32_bf16 v[110:113], v[224:227], v[166:169], v[110:113]
	v_mfma_f32_16x16x32_bf16 v[106:109], v[232:235], v[166:169], v[106:109]
	v_mfma_f32_16x16x32_bf16 v[94:97], v[224:227], v[174:177], v[94:97]
	v_mfma_f32_16x16x32_bf16 v[90:93], v[232:235], v[174:177], v[90:93]
	v_mfma_f32_16x16x32_bf16 v[78:81], v[224:227], v[196:199], v[78:81]
	v_mfma_f32_16x16x32_bf16 v[74:77], v[232:235], v[196:199], v[74:77]
	v_mfma_f32_16x16x32_bf16 v[70:73], v[224:227], v[204:207], v[70:73]
	v_mfma_f32_16x16x32_bf16 v[66:69], v[232:235], v[204:207], v[66:69]
	s_barrier
	ds_read_b128 v[162:165], v144 offset:16384
	ds_read_b128 v[166:169], v144 offset:17408
	ds_read_b128 v[170:173], v144 offset:18432
	ds_read_b128 v[174:177], v144 offset:19456
	ds_read_b128 v[192:195], v144 offset:20480
	ds_read_b128 v[196:199], v144 offset:21504
	ds_read_b128 v[200:203], v144 offset:22528
	ds_read_b128 v[204:207], v144 offset:23552
	global_load_lds_dwordx4 v[236:237], off
	s_mov_b32 m0, s28
	v_lshl_add_u64 v[238:239], s[22:23], 0, v[132:133]
	global_load_lds_dwordx4 v[238:239], off
	s_waitcnt vmcnt(10)
	s_barrier
	s_waitcnt lgkmcnt(0)
	v_mfma_f32_16x16x32_bf16 v[62:65], v[146:149], v[162:165], v[62:65]
	v_mfma_f32_16x16x32_bf16 v[58:61], v[154:157], v[162:165], v[58:61]
	v_mfma_f32_16x16x32_bf16 v[54:57], v[146:149], v[170:173], v[54:57]
	v_mfma_f32_16x16x32_bf16 v[50:53], v[154:157], v[170:173], v[50:53]
	v_mfma_f32_16x16x32_bf16 v[38:41], v[146:149], v[192:195], v[38:41]
	v_mfma_f32_16x16x32_bf16 v[34:37], v[154:157], v[192:195], v[34:37]
	v_mfma_f32_16x16x32_bf16 v[22:25], v[146:149], v[200:203], v[22:25]
	v_mfma_f32_16x16x32_bf16 v[18:21], v[154:157], v[200:203], v[18:21]
	v_mfma_f32_16x16x32_bf16 v[62:65], v[150:153], v[166:169], v[62:65]
	v_mfma_f32_16x16x32_bf16 v[58:61], v[158:161], v[166:169], v[58:61]
	v_mfma_f32_16x16x32_bf16 v[54:57], v[150:153], v[174:177], v[54:57]
	v_mfma_f32_16x16x32_bf16 v[50:53], v[158:161], v[174:177], v[50:53]
	v_mfma_f32_16x16x32_bf16 v[38:41], v[150:153], v[196:199], v[38:41]
	v_mfma_f32_16x16x32_bf16 v[34:37], v[158:161], v[196:199], v[34:37]
	v_mfma_f32_16x16x32_bf16 v[22:25], v[150:153], v[204:207], v[22:25]
	v_mfma_f32_16x16x32_bf16 v[18:21], v[158:161], v[204:207], v[18:21]
	s_barrier
	s_add_u32 s52, s84, 0x20000
	s_addc_u32 s53, s85, 0
	s_add_i32 s54, s26, 0x14000
	s_mov_b32 m0, s54
	v_lshl_add_u64 v[146:147], s[52:53], 0, v[134:135]
	global_load_lds_dwordx4 v[146:147], off
	s_add_i32 m0, s54, 0x2000
	v_lshl_add_u64 v[146:147], s[52:53], 0, v[130:131]
	global_load_lds_dwordx4 v[146:147], off
	v_add_u32_e32 v145, 0x18000, v142
	ds_read_b128 v[146:149], v145
	ds_read_b128 v[150:153], v145 offset:1024
	ds_read_b128 v[154:157], v145 offset:2048
	ds_read_b128 v[158:161], v145 offset:3072
	s_add_i32 s52, 0, 0x18000
	s_waitcnt vmcnt(6)
	s_barrier
	v_mfma_f32_16x16x32_bf16 v[46:49], v[208:211], v[162:165], v[46:49]
	v_mfma_f32_16x16x32_bf16 v[42:45], v[228:231], v[162:165], v[42:45]
	v_mfma_f32_16x16x32_bf16 v[30:33], v[208:211], v[170:173], v[30:33]
	v_mfma_f32_16x16x32_bf16 v[26:29], v[228:231], v[170:173], v[26:29]
	v_mfma_f32_16x16x32_bf16 v[14:17], v[208:211], v[192:195], v[14:17]
	v_mfma_f32_16x16x32_bf16 v[10:13], v[228:231], v[192:195], v[10:13]
	v_mfma_f32_16x16x32_bf16 v[6:9], v[208:211], v[200:203], v[6:9]
	v_mfma_f32_16x16x32_bf16 v[2:5], v[228:231], v[200:203], v[2:5]
	v_mfma_f32_16x16x32_bf16 v[46:49], v[224:227], v[166:169], v[46:49]
	v_mfma_f32_16x16x32_bf16 v[42:45], v[232:235], v[166:169], v[42:45]
	v_mfma_f32_16x16x32_bf16 v[30:33], v[224:227], v[174:177], v[30:33]
	v_mfma_f32_16x16x32_bf16 v[26:29], v[232:235], v[174:177], v[26:29]
	v_mfma_f32_16x16x32_bf16 v[14:17], v[224:227], v[196:199], v[14:17]
	v_mfma_f32_16x16x32_bf16 v[10:13], v[232:235], v[196:199], v[10:13]
	v_mfma_f32_16x16x32_bf16 v[6:9], v[224:227], v[204:207], v[6:9]
	v_mfma_f32_16x16x32_bf16 v[2:5], v[232:235], v[204:207], v[2:5]
	s_barrier
	s_add_u32 s22, s22, 0x20000
	s_addc_u32 s23, s23, 0
	s_mov_b32 m0, s29
	v_lshl_add_u64 v[208:209], s[22:23], 0, v[136:137]
	ds_read_b128 v[162:165], v144 offset:32768
	ds_read_b128 v[166:169], v144 offset:33792
	ds_read_b128 v[170:173], v144 offset:34816
	ds_read_b128 v[174:177], v144 offset:35840
	ds_read_b128 v[192:195], v144 offset:36864
	ds_read_b128 v[196:199], v144 offset:37888
	ds_read_b128 v[200:203], v144 offset:38912
	ds_read_b128 v[204:207], v144 offset:39936
	global_load_lds_dwordx4 v[208:209], off
	s_mov_b32 m0, s36
	v_lshl_add_u64 v[208:209], s[22:23], 0, v[132:133]
	global_load_lds_dwordx4 v[208:209], off
	s_barrier
	s_waitcnt lgkmcnt(0)
	v_mfma_f32_16x16x32_bf16 v[126:129], v[146:149], v[162:165], v[126:129]
	v_mfma_f32_16x16x32_bf16 v[122:125], v[154:157], v[162:165], v[122:125]
	v_mfma_f32_16x16x32_bf16 v[118:121], v[146:149], v[170:173], v[118:121]
	v_mfma_f32_16x16x32_bf16 v[114:117], v[154:157], v[170:173], v[114:117]
	v_mfma_f32_16x16x32_bf16 v[102:105], v[146:149], v[192:195], v[102:105]
	v_mfma_f32_16x16x32_bf16 v[98:101], v[154:157], v[192:195], v[98:101]
	v_mfma_f32_16x16x32_bf16 v[86:89], v[146:149], v[200:203], v[86:89]
	v_mfma_f32_16x16x32_bf16 v[82:85], v[154:157], v[200:203], v[82:85]
	v_mfma_f32_16x16x32_bf16 v[126:129], v[150:153], v[166:169], v[126:129]
	v_mfma_f32_16x16x32_bf16 v[122:125], v[158:161], v[166:169], v[122:125]
	v_mfma_f32_16x16x32_bf16 v[118:121], v[150:153], v[174:177], v[118:121]
	v_mfma_f32_16x16x32_bf16 v[114:117], v[158:161], v[174:177], v[114:117]
	v_mfma_f32_16x16x32_bf16 v[102:105], v[150:153], v[196:199], v[102:105]
	v_mfma_f32_16x16x32_bf16 v[98:101], v[158:161], v[196:199], v[98:101]
	v_mfma_f32_16x16x32_bf16 v[86:89], v[150:153], v[204:207], v[86:89]
	v_mfma_f32_16x16x32_bf16 v[82:85], v[158:161], v[204:207], v[82:85]
	s_barrier
	s_add_i32 s53, 0, 0x1c000
	s_add_i32 s22, s52, s26
	v_add_u32_e32 v145, s53, v142
	v_lshl_add_u64 v[178:179], v[178:179], 0, s[78:79]
	s_mov_b32 m0, s22
	ds_read_b128 v[208:211], v145
	ds_read_b128 v[224:227], v145 offset:1024
	ds_read_b128 v[228:231], v145 offset:2048
	ds_read_b128 v[232:235], v145 offset:3072
	global_load_lds_dwordx4 v[178:179], off
	s_add_i32 m0, s22, 0x2000
	v_lshl_add_u64 v[178:179], v[212:213], 0, s[78:79]
	global_load_lds_dwordx4 v[178:179], off
	s_mov_b32 m0, s42
	v_lshl_add_u64 v[178:179], v[236:237], 0, s[78:79]
	s_waitcnt lgkmcnt(0)
	s_barrier
	v_mfma_f32_16x16x32_bf16 v[110:113], v[208:211], v[162:165], v[110:113]
	v_mfma_f32_16x16x32_bf16 v[106:109], v[228:231], v[162:165], v[106:109]
	v_mfma_f32_16x16x32_bf16 v[94:97], v[208:211], v[170:173], v[94:97]
	v_mfma_f32_16x16x32_bf16 v[90:93], v[228:231], v[170:173], v[90:93]
	v_mfma_f32_16x16x32_bf16 v[78:81], v[208:211], v[192:195], v[78:81]
	v_mfma_f32_16x16x32_bf16 v[74:77], v[228:231], v[192:195], v[74:77]
	v_mfma_f32_16x16x32_bf16 v[70:73], v[208:211], v[200:203], v[70:73]
	v_mfma_f32_16x16x32_bf16 v[66:69], v[228:231], v[200:203], v[66:69]
	v_mfma_f32_16x16x32_bf16 v[110:113], v[224:227], v[166:169], v[110:113]
	v_mfma_f32_16x16x32_bf16 v[106:109], v[232:235], v[166:169], v[106:109]
	v_mfma_f32_16x16x32_bf16 v[94:97], v[224:227], v[174:177], v[94:97]
	v_mfma_f32_16x16x32_bf16 v[90:93], v[232:235], v[174:177], v[90:93]
	v_mfma_f32_16x16x32_bf16 v[78:81], v[224:227], v[196:199], v[78:81]
	v_mfma_f32_16x16x32_bf16 v[74:77], v[232:235], v[196:199], v[74:77]
	v_mfma_f32_16x16x32_bf16 v[70:73], v[224:227], v[204:207], v[70:73]
	v_mfma_f32_16x16x32_bf16 v[66:69], v[232:235], v[204:207], v[66:69]
	s_barrier
	ds_read_b128 v[162:165], v144 offset:49152
	ds_read_b128 v[166:169], v144 offset:50176
	ds_read_b128 v[170:173], v144 offset:51200
	ds_read_b128 v[174:177], v144 offset:52224
	ds_read_b128 v[192:195], v144 offset:53248
	ds_read_b128 v[196:199], v144 offset:54272
	ds_read_b128 v[200:203], v144 offset:55296
	ds_read_b128 v[204:207], v144 offset:56320
	global_load_lds_dwordx4 v[178:179], off
	s_mov_b32 m0, s43
	v_lshl_add_u64 v[178:179], v[238:239], 0, s[78:79]
	global_load_lds_dwordx4 v[178:179], off
	s_waitcnt vmcnt(10)
	s_barrier
	s_waitcnt lgkmcnt(0)
	v_mfma_f32_16x16x32_bf16 v[62:65], v[146:149], v[162:165], v[62:65]
	v_mfma_f32_16x16x32_bf16 v[58:61], v[154:157], v[162:165], v[58:61]
	v_mfma_f32_16x16x32_bf16 v[54:57], v[146:149], v[170:173], v[54:57]
	v_mfma_f32_16x16x32_bf16 v[50:53], v[154:157], v[170:173], v[50:53]
	v_mfma_f32_16x16x32_bf16 v[38:41], v[146:149], v[192:195], v[38:41]
	v_mfma_f32_16x16x32_bf16 v[34:37], v[154:157], v[192:195], v[34:37]
	v_mfma_f32_16x16x32_bf16 v[22:25], v[146:149], v[200:203], v[22:25]
	v_mfma_f32_16x16x32_bf16 v[18:21], v[154:157], v[200:203], v[18:21]
	v_mfma_f32_16x16x32_bf16 v[62:65], v[150:153], v[166:169], v[62:65]
	v_mfma_f32_16x16x32_bf16 v[58:61], v[158:161], v[166:169], v[58:61]
	v_mfma_f32_16x16x32_bf16 v[54:57], v[150:153], v[174:177], v[54:57]
	v_mfma_f32_16x16x32_bf16 v[50:53], v[158:161], v[174:177], v[50:53]
	v_mfma_f32_16x16x32_bf16 v[38:41], v[150:153], v[196:199], v[38:41]
	v_mfma_f32_16x16x32_bf16 v[34:37], v[158:161], v[196:199], v[34:37]
	v_mfma_f32_16x16x32_bf16 v[22:25], v[150:153], v[204:207], v[22:25]
	v_mfma_f32_16x16x32_bf16 v[18:21], v[158:161], v[204:207], v[18:21]
	s_barrier
	s_add_u32 s22, s84, 0x20080
	s_addc_u32 s23, s85, 0
	s_add_i32 s52, s53, s26
	s_mov_b32 m0, s52
	v_lshl_add_u64 v[146:147], s[22:23], 0, v[134:135]
	global_load_lds_dwordx4 v[146:147], off
	s_add_i32 m0, s52, 0x2000
	v_lshl_add_u64 v[146:147], s[22:23], 0, v[130:131]
	global_load_lds_dwordx4 v[146:147], off
	v_add_u32_e32 v145, 0x10000, v142
	ds_read_b128 v[146:149], v145
	ds_read_b128 v[150:153], v145 offset:1024
	ds_read_b128 v[154:157], v145 offset:2048
	ds_read_b128 v[158:161], v145 offset:3072
	s_add_i32 s51, s51, 2
	s_add_u32 s20, s20, 0x100
	s_addc_u32 s21, s21, 0
	s_add_u32 s49, s49, 0x100
	s_addc_u32 s50, s50, 0
	s_cmp_gt_u32 s51, 5
	s_waitcnt vmcnt(6)
	s_barrier
	v_mfma_f32_16x16x32_bf16 v[46:49], v[208:211], v[162:165], v[46:49]
	v_mfma_f32_16x16x32_bf16 v[42:45], v[228:231], v[162:165], v[42:45]
	v_mfma_f32_16x16x32_bf16 v[30:33], v[208:211], v[170:173], v[30:33]
	v_mfma_f32_16x16x32_bf16 v[26:29], v[228:231], v[170:173], v[26:29]
	v_mfma_f32_16x16x32_bf16 v[14:17], v[208:211], v[192:195], v[14:17]
	v_mfma_f32_16x16x32_bf16 v[10:13], v[228:231], v[192:195], v[10:13]
	v_mfma_f32_16x16x32_bf16 v[6:9], v[208:211], v[200:203], v[6:9]
	v_mfma_f32_16x16x32_bf16 v[2:5], v[228:231], v[200:203], v[2:5]
	v_mfma_f32_16x16x32_bf16 v[46:49], v[224:227], v[166:169], v[46:49]
	v_mfma_f32_16x16x32_bf16 v[42:45], v[232:235], v[166:169], v[42:45]
	v_mfma_f32_16x16x32_bf16 v[30:33], v[224:227], v[174:177], v[30:33]
	v_mfma_f32_16x16x32_bf16 v[26:29], v[232:235], v[174:177], v[26:29]
	v_mfma_f32_16x16x32_bf16 v[14:17], v[224:227], v[196:199], v[14:17]
	v_mfma_f32_16x16x32_bf16 v[10:13], v[232:235], v[196:199], v[10:13]
	v_mfma_f32_16x16x32_bf16 v[6:9], v[224:227], v[204:207], v[6:9]
	v_mfma_f32_16x16x32_bf16 v[2:5], v[232:235], v[204:207], v[2:5]
	s_barrier
	s_cbranch_scc0 .LBB0_357
	s_waitcnt lgkmcnt(0)
	v_lshl_add_u32 v146, s46, 8, v1
	v_lshl_or_b32 v148, s45, 8, v143
	v_ashrrev_i32_e32 v147, 31, v146
	v_readlane_b32 s48, v254, 40
	v_ashrrev_i32_e32 v149, 31, v148
	v_lshlrev_b64 v[150:151], 12, v[146:147]
	v_readlane_b32 s60, v254, 52
	v_readlane_b32 s61, v254, 53
	v_lshlrev_b64 v[148:149], 1, v[148:149]
	s_mov_b32 s19, 0x80000
	v_lshl_add_u64 v[150:151], s[60:61], 0, v[150:151]
	v_lshl_add_u64 v[150:151], v[150:151], 0, v[148:149]
	s_mov_b64 s[20:21], 0x80000
	v_cvt_pk_bf16_f32 v62, v62, v63
	v_cvt_pk_bf16_f32 v63, v64, v65
	v_cvt_pk_bf16_f32 v64, v58, v59
	v_add_co_u32_e32 v58, vcc, s19, v150
	v_cvt_pk_bf16_f32 v70, v70, v71
	v_cvt_pk_bf16_f32 v71, v72, v73
	v_cvt_pk_bf16_f32 v72, v66, v67
	v_lshl_add_u64 v[66:67], v[150:151], 0, s[20:21]
	v_addc_co_u32_e32 v59, vcc, 0, v151, vcc
	v_cvt_pk_bf16_f32 v46, v46, v47
	v_cvt_pk_bf16_f32 v47, v48, v49
	v_cvt_pk_bf16_f32 v48, v42, v43
	v_cvt_pk_bf16_f32 v49, v44, v45
	s_mov_b32 s19, 0x90000
	v_cvt_pk_bf16_f32 v110, v110, v111
	v_cvt_pk_bf16_f32 v111, v112, v113
	v_cvt_pk_bf16_f32 v112, v106, v107
	v_or_b32_e32 v106, 16, v146
	global_store_dwordx4 v[66:67], v[46:49], off offset:256
	s_mov_b64 s[20:21], 0x90000
	v_ashrrev_i32_e32 v107, 31, v106
	v_add_co_u32_e32 v48, vcc, s19, v150
	v_cvt_pk_bf16_f32 v94, v94, v95
	v_cvt_pk_bf16_f32 v95, v96, v97
	v_cvt_pk_bf16_f32 v96, v90, v91
	v_or_b32_e32 v90, 32, v146
	v_lshl_add_u64 v[46:47], v[150:151], 0, s[20:21]
	v_addc_co_u32_e32 v49, vcc, 0, v151, vcc
	v_cvt_pk_bf16_f32 v30, v30, v31
	v_cvt_pk_bf16_f32 v31, v32, v33
	v_cvt_pk_bf16_f32 v32, v26, v27
	v_cvt_pk_bf16_f32 v33, v28, v29
	s_mov_b32 s19, 0xa0000
	v_lshlrev_b64 v[106:107], 12, v[106:107]
	v_ashrrev_i32_e32 v91, 31, v90
	v_cvt_pk_bf16_f32 v78, v78, v79
	v_cvt_pk_bf16_f32 v79, v80, v81
	v_cvt_pk_bf16_f32 v80, v74, v75
	v_or_b32_e32 v74, 48, v146
	global_store_dwordx4 v[46:47], v[30:33], off offset:256
	s_mov_b64 s[20:21], 0xa0000
	v_cvt_pk_bf16_f32 v113, v108, v109
	v_add_co_u32_e32 v32, vcc, s19, v150
	v_lshl_add_u64 v[106:107], s[60:61], 0, v[106:107]
	v_lshlrev_b64 v[90:91], 12, v[90:91]
	v_ashrrev_i32_e32 v75, 31, v74
	v_lshl_add_u64 v[30:31], v[150:151], 0, s[20:21]
	v_addc_co_u32_e32 v33, vcc, 0, v151, vcc
	v_cvt_pk_bf16_f32 v14, v14, v15
	v_cvt_pk_bf16_f32 v15, v16, v17
	v_cvt_pk_bf16_f32 v16, v10, v11
	v_cvt_pk_bf16_f32 v17, v12, v13
	s_mov_b32 s19, 0xb0000
	global_store_dwordx4 v[150:151], v[110:113], off offset:256
	v_cvt_pk_bf16_f32 v97, v92, v93
	v_lshl_add_u64 v[90:91], s[60:61], 0, v[90:91]
	v_lshl_add_u64 v[110:111], v[106:107], 0, v[148:149]
	v_lshlrev_b64 v[74:75], 12, v[74:75]
	global_store_dwordx4 v[30:31], v[14:17], off offset:256
	global_store_dwordx4 v[110:111], v[94:97], off offset:256
	v_cvt_pk_bf16_f32 v81, v76, v77
	v_add_co_u32_e32 v16, vcc, s19, v150
	v_lshl_add_u64 v[94:95], v[90:91], 0, v[148:149]
	v_lshl_add_u64 v[74:75], s[60:61], 0, v[74:75]
	s_mov_b64 s[20:21], 0xb0000
	v_addc_co_u32_e32 v17, vcc, 0, v151, vcc
	v_cvt_pk_bf16_f32 v126, v126, v127
	v_cvt_pk_bf16_f32 v127, v128, v129
	v_cvt_pk_bf16_f32 v128, v122, v123
	v_cvt_pk_bf16_f32 v129, v124, v125
	v_cvt_pk_bf16_f32 v106, v118, v119
	v_cvt_pk_bf16_f32 v107, v120, v121
	v_cvt_pk_bf16_f32 v108, v114, v115
	v_cvt_pk_bf16_f32 v109, v116, v117
	v_cvt_pk_bf16_f32 v90, v102, v103
	v_cvt_pk_bf16_f32 v91, v104, v105
	v_cvt_pk_bf16_f32 v92, v98, v99
	v_cvt_pk_bf16_f32 v93, v100, v101
	global_store_dwordx4 v[94:95], v[78:81], off offset:256
	v_cvt_pk_bf16_f32 v76, v82, v83
	v_cvt_pk_bf16_f32 v77, v84, v85
	v_lshl_add_u64 v[78:79], v[74:75], 0, v[148:149]
	v_cvt_pk_bf16_f32 v74, v86, v87
	v_cvt_pk_bf16_f32 v75, v88, v89
	v_cvt_pk_bf16_f32 v73, v68, v69
	v_cvt_pk_bf16_f32 v65, v60, v61
	v_cvt_pk_bf16_f32 v42, v54, v55
	v_cvt_pk_bf16_f32 v43, v56, v57
	v_cvt_pk_bf16_f32 v44, v50, v51
	v_cvt_pk_bf16_f32 v45, v52, v53
	v_cvt_pk_bf16_f32 v26, v38, v39
	v_cvt_pk_bf16_f32 v27, v40, v41
	v_cvt_pk_bf16_f32 v28, v34, v35
	v_cvt_pk_bf16_f32 v29, v36, v37
	v_lshl_add_u64 v[14:15], v[150:151], 0, s[20:21]
	v_cvt_pk_bf16_f32 v10, v22, v23
	v_cvt_pk_bf16_f32 v11, v24, v25
	v_cvt_pk_bf16_f32 v12, v18, v19
	v_cvt_pk_bf16_f32 v13, v20, v21
	v_cvt_pk_bf16_f32 v6, v6, v7
	v_cvt_pk_bf16_f32 v7, v8, v9
	v_cvt_pk_bf16_f32 v8, v2, v3
	v_cvt_pk_bf16_f32 v9, v4, v5
	s_and_b64 vcc, exec, s[38:39]
	s_mov_b32 s45, s18
	s_mov_b32 s46, s30
	s_mov_b64 s[22:23], s[82:83]
	s_mov_b64 s[20:21], s[80:81]
	s_mov_b32 s64, 0x800000
	s_movk_i32 s65, 0x1fff
	v_readlane_b32 s49, v254, 41
	v_readlane_b32 s50, v254, 42
	v_readlane_b32 s51, v254, 43
	v_readlane_b32 s52, v254, 44
	v_readlane_b32 s53, v254, 45
	v_readlane_b32 s54, v254, 46
	v_readlane_b32 s55, v254, 47
	v_readlane_b32 s56, v254, 48
	v_readlane_b32 s57, v254, 49
	v_readlane_b32 s58, v254, 50
	v_readlane_b32 s59, v254, 51
	v_readlane_b32 s62, v254, 54
	v_readlane_b32 s63, v254, 55
	global_store_dwordx4 v[150:151], v[126:129], off
	global_store_dwordx4 v[110:111], v[106:109], off
	global_store_dwordx4 v[94:95], v[90:93], off
	global_store_dwordx4 v[78:79], v[74:77], off
	global_store_dwordx4 v[78:79], v[70:73], off offset:256
	global_store_dwordx4 v[58:59], v[62:65], off
	global_store_dwordx4 v[48:49], v[42:45], off
	global_store_dwordx4 v[32:33], v[26:29], off
	global_store_dwordx4 v[16:17], v[10:13], off
	global_store_dwordx4 v[14:15], v[6:9], off offset:256
	s_cbranch_vccz .LBB0_350
	s_waitcnt vmcnt(0)
	v_readlane_b32 s44, v255, 30
	s_mov_b32 s66, s90
	s_cmpk_gt_u32 s25, 0xff
	v_readlane_b32 s45, v255, 31
	v_readlane_b32 s42, v255, 32
	s_cbranch_scc1 .LBB0_361
	s_barrier

.LBB0_373:
	s_add_u32 s22, s20, 0xfffe0080
	s_addc_u32 s23, s21, -1
	s_cmp_eq_u32 s51, 4
	s_cselect_b32 s23, s31, s23
	s_cselect_b32 s22, s47, s22
	s_cselect_b32 s83, s19, s50
	s_cselect_b32 s82, s48, s49
	v_lshl_add_u64 v[178:179], s[20:21], 0, v[138:139]
	s_add_i32 m0, s27, 0xc000
	ds_read_b128 v[162:165], v144
	ds_read_b128 v[166:169], v144 offset:1024
	ds_read_b128 v[170:173], v144 offset:2048
	ds_read_b128 v[174:177], v144 offset:3072
	ds_read_b128 v[192:195], v144 offset:4096
	ds_read_b128 v[196:199], v144 offset:5120
	ds_read_b128 v[200:203], v144 offset:6144
	ds_read_b128 v[204:207], v144 offset:7168
	global_load_lds_dwordx4 v[178:179], off
	s_add_i32 m0, s27, 0xe000
	v_lshl_add_u64 v[178:179], s[20:21], 0, v[140:141]
	global_load_lds_dwordx4 v[178:179], off
	s_barrier
	s_waitcnt lgkmcnt(0)
	v_mfma_f32_16x16x32_bf16 v[126:129], v[146:149], v[162:165], v[126:129]
	v_mfma_f32_16x16x32_bf16 v[122:125], v[154:157], v[162:165], v[122:125]
	v_mfma_f32_16x16x32_bf16 v[118:121], v[146:149], v[170:173], v[118:121]
	v_mfma_f32_16x16x32_bf16 v[114:117], v[154:157], v[170:173], v[114:117]
	v_mfma_f32_16x16x32_bf16 v[102:105], v[146:149], v[192:195], v[102:105]
	v_mfma_f32_16x16x32_bf16 v[98:101], v[154:157], v[192:195], v[98:101]
	v_mfma_f32_16x16x32_bf16 v[86:89], v[146:149], v[200:203], v[86:89]
	v_mfma_f32_16x16x32_bf16 v[82:85], v[154:157], v[200:203], v[82:85]
	v_mfma_f32_16x16x32_bf16 v[126:129], v[150:153], v[166:169], v[126:129]
	v_mfma_f32_16x16x32_bf16 v[122:125], v[158:161], v[166:169], v[122:125]
	v_mfma_f32_16x16x32_bf16 v[118:121], v[150:153], v[174:177], v[118:121]
	v_mfma_f32_16x16x32_bf16 v[114:117], v[158:161], v[174:177], v[114:117]
	v_mfma_f32_16x16x32_bf16 v[102:105], v[150:153], v[196:199], v[102:105]
	v_mfma_f32_16x16x32_bf16 v[98:101], v[158:161], v[196:199], v[98:101]
	v_mfma_f32_16x16x32_bf16 v[86:89], v[150:153], v[204:207], v[86:89]
	v_mfma_f32_16x16x32_bf16 v[82:85], v[158:161], v[204:207], v[82:85]
	s_barrier
	s_add_i32 s52, s26, 0x10000
	v_add_u32_e32 v145, 0x14000, v142
	v_lshl_add_u64 v[178:179], s[82:83], 0, v[134:135]
	s_mov_b32 m0, s52
	ds_read_b128 v[208:211], v145
	ds_read_b128 v[224:227], v145 offset:1024
	ds_read_b128 v[228:231], v145 offset:2048
	ds_read_b128 v[232:235], v145 offset:3072
	global_load_lds_dwordx4 v[178:179], off
	s_add_i32 m0, s52, 0x2000
	v_lshl_add_u64 v[212:213], s[82:83], 0, v[130:131]
	global_load_lds_dwordx4 v[212:213], off
	s_mov_b32 m0, s27
	v_lshl_add_u64 v[236:237], s[22:23], 0, v[136:137]
	s_waitcnt lgkmcnt(0)
	s_barrier
	v_mfma_f32_16x16x32_bf16 v[110:113], v[208:211], v[162:165], v[110:113]
	v_mfma_f32_16x16x32_bf16 v[106:109], v[228:231], v[162:165], v[106:109]
	v_mfma_f32_16x16x32_bf16 v[94:97], v[208:211], v[170:173], v[94:97]
	v_mfma_f32_16x16x32_bf16 v[90:93], v[228:231], v[170:173], v[90:93]
	v_mfma_f32_16x16x32_bf16 v[78:81], v[208:211], v[192:195], v[78:81]
	v_mfma_f32_16x16x32_bf16 v[74:77], v[228:231], v[192:195], v[74:77]
	v_mfma_f32_16x16x32_bf16 v[70:73], v[208:211], v[200:203], v[70:73]
	v_mfma_f32_16x16x32_bf16 v[66:69], v[228:231], v[200:203], v[66:69]
	v_mfma_f32_16x16x32_bf16 v[110:113], v[224:227], v[166:169], v[110:113]
	v_mfma_f32_16x16x32_bf16 v[106:109], v[232:235], v[166:169], v[106:109]
	v_mfma_f32_16x16x32_bf16 v[94:97], v[224:227], v[174:177], v[94:97]
	v_mfma_f32_16x16x32_bf16 v[90:93], v[232:235], v[174:177], v[90:93]
	v_mfma_f32_16x16x32_bf16 v[78:81], v[224:227], v[196:199], v[78:81]
	v_mfma_f32_16x16x32_bf16 v[74:77], v[232:235], v[196:199], v[74:77]
	v_mfma_f32_16x16x32_bf16 v[70:73], v[224:227], v[204:207], v[70:73]
	v_mfma_f32_16x16x32_bf16 v[66:69], v[232:235], v[204:207], v[66:69]
	s_barrier
	ds_read_b128 v[162:165], v144 offset:16384
	ds_read_b128 v[166:169], v144 offset:17408
	ds_read_b128 v[170:173], v144 offset:18432
	ds_read_b128 v[174:177], v144 offset:19456
	ds_read_b128 v[192:195], v144 offset:20480
	ds_read_b128 v[196:199], v144 offset:21504
	ds_read_b128 v[200:203], v144 offset:22528
	ds_read_b128 v[204:207], v144 offset:23552
	global_load_lds_dwordx4 v[236:237], off
	s_mov_b32 m0, s28
	v_lshl_add_u64 v[238:239], s[22:23], 0, v[132:133]
	global_load_lds_dwordx4 v[238:239], off
	s_waitcnt vmcnt(10)
	s_barrier
	s_waitcnt lgkmcnt(0)
	v_mfma_f32_16x16x32_bf16 v[62:65], v[146:149], v[162:165], v[62:65]
	v_mfma_f32_16x16x32_bf16 v[58:61], v[154:157], v[162:165], v[58:61]
	v_mfma_f32_16x16x32_bf16 v[54:57], v[146:149], v[170:173], v[54:57]
	v_mfma_f32_16x16x32_bf16 v[50:53], v[154:157], v[170:173], v[50:53]
	v_mfma_f32_16x16x32_bf16 v[38:41], v[146:149], v[192:195], v[38:41]
	v_mfma_f32_16x16x32_bf16 v[34:37], v[154:157], v[192:195], v[34:37]
	v_mfma_f32_16x16x32_bf16 v[22:25], v[146:149], v[200:203], v[22:25]
	v_mfma_f32_16x16x32_bf16 v[18:21], v[154:157], v[200:203], v[18:21]
	v_mfma_f32_16x16x32_bf16 v[62:65], v[150:153], v[166:169], v[62:65]
	v_mfma_f32_16x16x32_bf16 v[58:61], v[158:161], v[166:169], v[58:61]
	v_mfma_f32_16x16x32_bf16 v[54:57], v[150:153], v[174:177], v[54:57]
	v_mfma_f32_16x16x32_bf16 v[50:53], v[158:161], v[174:177], v[50:53]
	v_mfma_f32_16x16x32_bf16 v[38:41], v[150:153], v[196:199], v[38:41]
	v_mfma_f32_16x16x32_bf16 v[34:37], v[158:161], v[196:199], v[34:37]
	v_mfma_f32_16x16x32_bf16 v[22:25], v[150:153], v[204:207], v[22:25]
	v_mfma_f32_16x16x32_bf16 v[18:21], v[158:161], v[204:207], v[18:21]
	s_barrier
	s_add_u32 s52, s82, 0x20000
	s_addc_u32 s53, s83, 0
	s_add_i32 s54, s26, 0x14000
	s_mov_b32 m0, s54
	v_lshl_add_u64 v[146:147], s[52:53], 0, v[134:135]
	global_load_lds_dwordx4 v[146:147], off
	s_add_i32 m0, s54, 0x2000
	v_lshl_add_u64 v[146:147], s[52:53], 0, v[130:131]
	global_load_lds_dwordx4 v[146:147], off
	v_add_u32_e32 v145, 0x18000, v142
	ds_read_b128 v[146:149], v145
	ds_read_b128 v[150:153], v145 offset:1024
	ds_read_b128 v[154:157], v145 offset:2048
	ds_read_b128 v[158:161], v145 offset:3072
	s_add_i32 s52, 0, 0x18000
	s_waitcnt vmcnt(6)
	s_barrier
	v_mfma_f32_16x16x32_bf16 v[46:49], v[208:211], v[162:165], v[46:49]
	v_mfma_f32_16x16x32_bf16 v[42:45], v[228:231], v[162:165], v[42:45]
	v_mfma_f32_16x16x32_bf16 v[30:33], v[208:211], v[170:173], v[30:33]
	v_mfma_f32_16x16x32_bf16 v[26:29], v[228:231], v[170:173], v[26:29]
	v_mfma_f32_16x16x32_bf16 v[14:17], v[208:211], v[192:195], v[14:17]
	v_mfma_f32_16x16x32_bf16 v[10:13], v[228:231], v[192:195], v[10:13]
	v_mfma_f32_16x16x32_bf16 v[6:9], v[208:211], v[200:203], v[6:9]
	v_mfma_f32_16x16x32_bf16 v[2:5], v[228:231], v[200:203], v[2:5]
	v_mfma_f32_16x16x32_bf16 v[46:49], v[224:227], v[166:169], v[46:49]
	v_mfma_f32_16x16x32_bf16 v[42:45], v[232:235], v[166:169], v[42:45]
	v_mfma_f32_16x16x32_bf16 v[30:33], v[224:227], v[174:177], v[30:33]
	v_mfma_f32_16x16x32_bf16 v[26:29], v[232:235], v[174:177], v[26:29]
	v_mfma_f32_16x16x32_bf16 v[14:17], v[224:227], v[196:199], v[14:17]
	v_mfma_f32_16x16x32_bf16 v[10:13], v[232:235], v[196:199], v[10:13]
	v_mfma_f32_16x16x32_bf16 v[6:9], v[224:227], v[204:207], v[6:9]
	v_mfma_f32_16x16x32_bf16 v[2:5], v[232:235], v[204:207], v[2:5]
	s_barrier
	s_add_u32 s22, s22, 0x20000
	s_addc_u32 s23, s23, 0
	s_mov_b32 m0, s29
	v_lshl_add_u64 v[208:209], s[22:23], 0, v[136:137]
	ds_read_b128 v[162:165], v144 offset:32768
	ds_read_b128 v[166:169], v144 offset:33792
	ds_read_b128 v[170:173], v144 offset:34816
	ds_read_b128 v[174:177], v144 offset:35840
	ds_read_b128 v[192:195], v144 offset:36864
	ds_read_b128 v[196:199], v144 offset:37888
	ds_read_b128 v[200:203], v144 offset:38912
	ds_read_b128 v[204:207], v144 offset:39936
	global_load_lds_dwordx4 v[208:209], off
	s_mov_b32 m0, s36
	v_lshl_add_u64 v[208:209], s[22:23], 0, v[132:133]
	global_load_lds_dwordx4 v[208:209], off
	s_barrier
	s_waitcnt lgkmcnt(0)
	v_mfma_f32_16x16x32_bf16 v[126:129], v[146:149], v[162:165], v[126:129]
	v_mfma_f32_16x16x32_bf16 v[122:125], v[154:157], v[162:165], v[122:125]
	v_mfma_f32_16x16x32_bf16 v[118:121], v[146:149], v[170:173], v[118:121]
	v_mfma_f32_16x16x32_bf16 v[114:117], v[154:157], v[170:173], v[114:117]
	v_mfma_f32_16x16x32_bf16 v[102:105], v[146:149], v[192:195], v[102:105]
	v_mfma_f32_16x16x32_bf16 v[98:101], v[154:157], v[192:195], v[98:101]
	v_mfma_f32_16x16x32_bf16 v[86:89], v[146:149], v[200:203], v[86:89]
	v_mfma_f32_16x16x32_bf16 v[82:85], v[154:157], v[200:203], v[82:85]
	v_mfma_f32_16x16x32_bf16 v[126:129], v[150:153], v[166:169], v[126:129]
	v_mfma_f32_16x16x32_bf16 v[122:125], v[158:161], v[166:169], v[122:125]
	v_mfma_f32_16x16x32_bf16 v[118:121], v[150:153], v[174:177], v[118:121]
	v_mfma_f32_16x16x32_bf16 v[114:117], v[158:161], v[174:177], v[114:117]
	v_mfma_f32_16x16x32_bf16 v[102:105], v[150:153], v[196:199], v[102:105]
	v_mfma_f32_16x16x32_bf16 v[98:101], v[158:161], v[196:199], v[98:101]
	v_mfma_f32_16x16x32_bf16 v[86:89], v[150:153], v[204:207], v[86:89]
	v_mfma_f32_16x16x32_bf16 v[82:85], v[158:161], v[204:207], v[82:85]
	s_barrier
	s_add_i32 s53, 0, 0x1c000
	s_add_i32 s22, s52, s26
	v_add_u32_e32 v145, s53, v142
	v_lshl_add_u64 v[178:179], v[178:179], 0, s[78:79]
	s_mov_b32 m0, s22
	ds_read_b128 v[208:211], v145
	ds_read_b128 v[224:227], v145 offset:1024
	ds_read_b128 v[228:231], v145 offset:2048
	ds_read_b128 v[232:235], v145 offset:3072
	global_load_lds_dwordx4 v[178:179], off
	s_add_i32 m0, s22, 0x2000
	v_lshl_add_u64 v[178:179], v[212:213], 0, s[78:79]
	global_load_lds_dwordx4 v[178:179], off
	s_mov_b32 m0, s42
	v_lshl_add_u64 v[178:179], v[236:237], 0, s[78:79]
	s_waitcnt lgkmcnt(0)
	s_barrier
	v_mfma_f32_16x16x32_bf16 v[110:113], v[208:211], v[162:165], v[110:113]
	v_mfma_f32_16x16x32_bf16 v[106:109], v[228:231], v[162:165], v[106:109]
	v_mfma_f32_16x16x32_bf16 v[94:97], v[208:211], v[170:173], v[94:97]
	v_mfma_f32_16x16x32_bf16 v[90:93], v[228:231], v[170:173], v[90:93]
	v_mfma_f32_16x16x32_bf16 v[78:81], v[208:211], v[192:195], v[78:81]
	v_mfma_f32_16x16x32_bf16 v[74:77], v[228:231], v[192:195], v[74:77]
	v_mfma_f32_16x16x32_bf16 v[70:73], v[208:211], v[200:203], v[70:73]
	v_mfma_f32_16x16x32_bf16 v[66:69], v[228:231], v[200:203], v[66:69]
	v_mfma_f32_16x16x32_bf16 v[110:113], v[224:227], v[166:169], v[110:113]
	v_mfma_f32_16x16x32_bf16 v[106:109], v[232:235], v[166:169], v[106:109]
	v_mfma_f32_16x16x32_bf16 v[94:97], v[224:227], v[174:177], v[94:97]
	v_mfma_f32_16x16x32_bf16 v[90:93], v[232:235], v[174:177], v[90:93]
	v_mfma_f32_16x16x32_bf16 v[78:81], v[224:227], v[196:199], v[78:81]
	v_mfma_f32_16x16x32_bf16 v[74:77], v[232:235], v[196:199], v[74:77]
	v_mfma_f32_16x16x32_bf16 v[70:73], v[224:227], v[204:207], v[70:73]
	v_mfma_f32_16x16x32_bf16 v[66:69], v[232:235], v[204:207], v[66:69]
	s_barrier
	ds_read_b128 v[162:165], v144 offset:49152
	ds_read_b128 v[166:169], v144 offset:50176
	ds_read_b128 v[170:173], v144 offset:51200
	ds_read_b128 v[174:177], v144 offset:52224
	ds_read_b128 v[192:195], v144 offset:53248
	ds_read_b128 v[196:199], v144 offset:54272
	ds_read_b128 v[200:203], v144 offset:55296
	ds_read_b128 v[204:207], v144 offset:56320
	global_load_lds_dwordx4 v[178:179], off
	s_mov_b32 m0, s43
	v_lshl_add_u64 v[178:179], v[238:239], 0, s[78:79]
	global_load_lds_dwordx4 v[178:179], off
	s_waitcnt vmcnt(10)
	s_barrier
	s_waitcnt lgkmcnt(0)
	v_mfma_f32_16x16x32_bf16 v[62:65], v[146:149], v[162:165], v[62:65]
	v_mfma_f32_16x16x32_bf16 v[58:61], v[154:157], v[162:165], v[58:61]
	v_mfma_f32_16x16x32_bf16 v[54:57], v[146:149], v[170:173], v[54:57]
	v_mfma_f32_16x16x32_bf16 v[50:53], v[154:157], v[170:173], v[50:53]
	v_mfma_f32_16x16x32_bf16 v[38:41], v[146:149], v[192:195], v[38:41]
	v_mfma_f32_16x16x32_bf16 v[34:37], v[154:157], v[192:195], v[34:37]
	v_mfma_f32_16x16x32_bf16 v[22:25], v[146:149], v[200:203], v[22:25]
	v_mfma_f32_16x16x32_bf16 v[18:21], v[154:157], v[200:203], v[18:21]
	v_mfma_f32_16x16x32_bf16 v[62:65], v[150:153], v[166:169], v[62:65]
	v_mfma_f32_16x16x32_bf16 v[58:61], v[158:161], v[166:169], v[58:61]
	v_mfma_f32_16x16x32_bf16 v[54:57], v[150:153], v[174:177], v[54:57]
	v_mfma_f32_16x16x32_bf16 v[50:53], v[158:161], v[174:177], v[50:53]
	v_mfma_f32_16x16x32_bf16 v[38:41], v[150:153], v[196:199], v[38:41]
	v_mfma_f32_16x16x32_bf16 v[34:37], v[158:161], v[196:199], v[34:37]
	v_mfma_f32_16x16x32_bf16 v[22:25], v[150:153], v[204:207], v[22:25]
	v_mfma_f32_16x16x32_bf16 v[18:21], v[158:161], v[204:207], v[18:21]
	s_barrier
	s_add_u32 s22, s82, 0x20080
	s_addc_u32 s23, s83, 0
	s_add_i32 s52, s53, s26
	s_mov_b32 m0, s52
	v_lshl_add_u64 v[146:147], s[22:23], 0, v[134:135]
	global_load_lds_dwordx4 v[146:147], off
	s_add_i32 m0, s52, 0x2000
	v_lshl_add_u64 v[146:147], s[22:23], 0, v[130:131]
	global_load_lds_dwordx4 v[146:147], off
	v_add_u32_e32 v145, 0x10000, v142
	ds_read_b128 v[146:149], v145
	ds_read_b128 v[150:153], v145 offset:1024
	ds_read_b128 v[154:157], v145 offset:2048
	ds_read_b128 v[158:161], v145 offset:3072
	s_add_i32 s51, s51, 2
	s_add_u32 s20, s20, 0x100
	s_addc_u32 s21, s21, 0
	s_add_u32 s49, s49, 0x100
	s_addc_u32 s50, s50, 0
	s_cmp_gt_u32 s51, 5
	s_waitcnt vmcnt(6)
	s_barrier
	v_mfma_f32_16x16x32_bf16 v[46:49], v[208:211], v[162:165], v[46:49]
	v_mfma_f32_16x16x32_bf16 v[42:45], v[228:231], v[162:165], v[42:45]
	v_mfma_f32_16x16x32_bf16 v[30:33], v[208:211], v[170:173], v[30:33]
	v_mfma_f32_16x16x32_bf16 v[26:29], v[228:231], v[170:173], v[26:29]
	v_mfma_f32_16x16x32_bf16 v[14:17], v[208:211], v[192:195], v[14:17]
	v_mfma_f32_16x16x32_bf16 v[10:13], v[228:231], v[192:195], v[10:13]
	v_mfma_f32_16x16x32_bf16 v[6:9], v[208:211], v[200:203], v[6:9]
	v_mfma_f32_16x16x32_bf16 v[2:5], v[228:231], v[200:203], v[2:5]
	v_mfma_f32_16x16x32_bf16 v[46:49], v[224:227], v[166:169], v[46:49]
	v_mfma_f32_16x16x32_bf16 v[42:45], v[232:235], v[166:169], v[42:45]
	v_mfma_f32_16x16x32_bf16 v[30:33], v[224:227], v[174:177], v[30:33]
	v_mfma_f32_16x16x32_bf16 v[26:29], v[232:235], v[174:177], v[26:29]
	v_mfma_f32_16x16x32_bf16 v[14:17], v[224:227], v[196:199], v[14:17]
	v_mfma_f32_16x16x32_bf16 v[10:13], v[232:235], v[196:199], v[10:13]
	v_mfma_f32_16x16x32_bf16 v[6:9], v[224:227], v[204:207], v[6:9]
	v_mfma_f32_16x16x32_bf16 v[2:5], v[232:235], v[204:207], v[2:5]
	s_barrier
	s_cbranch_scc0 .LBB0_373
	s_waitcnt lgkmcnt(0)
	v_lshl_add_u32 v146, s46, 8, v1
	v_lshl_or_b32 v148, s45, 8, v143
	v_ashrrev_i32_e32 v147, 31, v146
	v_readlane_b32 s48, v254, 40
	v_ashrrev_i32_e32 v149, 31, v148
	v_lshlrev_b64 v[150:151], 14, v[146:147]
	v_readlane_b32 s62, v254, 54
	v_readlane_b32 s63, v254, 55
	v_lshlrev_b64 v[148:149], 1, v[148:149]
	s_mov_b32 s19, 0x200000
	v_lshl_add_u64 v[150:151], s[62:63], 0, v[150:151]
	v_lshl_add_u64 v[150:151], v[150:151], 0, v[148:149]
	s_mov_b64 s[20:21], 0x200000
	v_cvt_pk_bf16_f32 v62, v62, v63
	v_cvt_pk_bf16_f32 v63, v64, v65
	v_cvt_pk_bf16_f32 v64, v58, v59
	v_add_co_u32_e32 v58, vcc, s19, v150
	v_cvt_pk_bf16_f32 v70, v70, v71
	v_cvt_pk_bf16_f32 v71, v72, v73
	v_cvt_pk_bf16_f32 v72, v66, v67
	v_lshl_add_u64 v[66:67], v[150:151], 0, s[20:21]
	v_addc_co_u32_e32 v59, vcc, 0, v151, vcc
	v_cvt_pk_bf16_f32 v46, v46, v47
	v_cvt_pk_bf16_f32 v47, v48, v49
	v_cvt_pk_bf16_f32 v48, v42, v43
	v_cvt_pk_bf16_f32 v49, v44, v45
	s_mov_b32 s19, 0x240000
	v_cvt_pk_bf16_f32 v110, v110, v111
	v_cvt_pk_bf16_f32 v111, v112, v113
	v_cvt_pk_bf16_f32 v112, v106, v107
	v_or_b32_e32 v106, 16, v146
	global_store_dwordx4 v[66:67], v[46:49], off offset:256
	s_mov_b64 s[20:21], 0x240000
	v_ashrrev_i32_e32 v107, 31, v106
	v_add_co_u32_e32 v48, vcc, s19, v150
	v_cvt_pk_bf16_f32 v94, v94, v95
	v_cvt_pk_bf16_f32 v95, v96, v97
	v_cvt_pk_bf16_f32 v96, v90, v91
	v_or_b32_e32 v90, 32, v146
	v_lshl_add_u64 v[46:47], v[150:151], 0, s[20:21]
	v_addc_co_u32_e32 v49, vcc, 0, v151, vcc
	v_cvt_pk_bf16_f32 v30, v30, v31
	v_cvt_pk_bf16_f32 v31, v32, v33
	v_cvt_pk_bf16_f32 v32, v26, v27
	v_cvt_pk_bf16_f32 v33, v28, v29
	s_mov_b32 s19, 0x280000
	v_lshlrev_b64 v[106:107], 14, v[106:107]
	v_ashrrev_i32_e32 v91, 31, v90
	v_cvt_pk_bf16_f32 v78, v78, v79
	v_cvt_pk_bf16_f32 v79, v80, v81
	v_cvt_pk_bf16_f32 v80, v74, v75
	v_or_b32_e32 v74, 48, v146
	global_store_dwordx4 v[46:47], v[30:33], off offset:256
	s_mov_b64 s[20:21], 0x280000
	v_cvt_pk_bf16_f32 v113, v108, v109
	v_add_co_u32_e32 v32, vcc, s19, v150
	v_lshl_add_u64 v[106:107], s[62:63], 0, v[106:107]
	v_lshlrev_b64 v[90:91], 14, v[90:91]
	v_ashrrev_i32_e32 v75, 31, v74
	v_lshl_add_u64 v[30:31], v[150:151], 0, s[20:21]
	v_addc_co_u32_e32 v33, vcc, 0, v151, vcc
	v_cvt_pk_bf16_f32 v14, v14, v15
	v_cvt_pk_bf16_f32 v15, v16, v17
	v_cvt_pk_bf16_f32 v16, v10, v11
	v_cvt_pk_bf16_f32 v17, v12, v13
	s_mov_b32 s19, 0x2c0000
	global_store_dwordx4 v[150:151], v[110:113], off offset:256
	v_cvt_pk_bf16_f32 v97, v92, v93
	v_lshl_add_u64 v[90:91], s[62:63], 0, v[90:91]
	v_lshl_add_u64 v[110:111], v[106:107], 0, v[148:149]
	v_lshlrev_b64 v[74:75], 14, v[74:75]
	global_store_dwordx4 v[30:31], v[14:17], off offset:256
	global_store_dwordx4 v[110:111], v[94:97], off offset:256
	v_cvt_pk_bf16_f32 v81, v76, v77
	v_add_co_u32_e32 v16, vcc, s19, v150
	v_lshl_add_u64 v[94:95], v[90:91], 0, v[148:149]
	v_lshl_add_u64 v[74:75], s[62:63], 0, v[74:75]
	s_mov_b64 s[20:21], 0x2c0000
	v_addc_co_u32_e32 v17, vcc, 0, v151, vcc
	v_cvt_pk_bf16_f32 v126, v126, v127
	v_cvt_pk_bf16_f32 v127, v128, v129
	v_cvt_pk_bf16_f32 v128, v122, v123
	v_cvt_pk_bf16_f32 v129, v124, v125
	v_cvt_pk_bf16_f32 v106, v118, v119
	v_cvt_pk_bf16_f32 v107, v120, v121
	v_cvt_pk_bf16_f32 v108, v114, v115
	v_cvt_pk_bf16_f32 v109, v116, v117
	v_cvt_pk_bf16_f32 v90, v102, v103
	v_cvt_pk_bf16_f32 v91, v104, v105
	v_cvt_pk_bf16_f32 v92, v98, v99
	v_cvt_pk_bf16_f32 v93, v100, v101
	global_store_dwordx4 v[94:95], v[78:81], off offset:256
	v_cvt_pk_bf16_f32 v76, v82, v83
	v_cvt_pk_bf16_f32 v77, v84, v85
	v_lshl_add_u64 v[78:79], v[74:75], 0, v[148:149]
	v_cvt_pk_bf16_f32 v74, v86, v87
	v_cvt_pk_bf16_f32 v75, v88, v89
	v_cvt_pk_bf16_f32 v73, v68, v69
	v_cvt_pk_bf16_f32 v65, v60, v61
	v_cvt_pk_bf16_f32 v42, v54, v55
	v_cvt_pk_bf16_f32 v43, v56, v57
	v_cvt_pk_bf16_f32 v44, v50, v51
	v_cvt_pk_bf16_f32 v45, v52, v53
	v_cvt_pk_bf16_f32 v26, v38, v39
	v_cvt_pk_bf16_f32 v27, v40, v41
	v_cvt_pk_bf16_f32 v28, v34, v35
	v_cvt_pk_bf16_f32 v29, v36, v37
	v_lshl_add_u64 v[14:15], v[150:151], 0, s[20:21]
	v_cvt_pk_bf16_f32 v10, v22, v23
	v_cvt_pk_bf16_f32 v11, v24, v25
	v_cvt_pk_bf16_f32 v12, v18, v19
	v_cvt_pk_bf16_f32 v13, v20, v21
	v_cvt_pk_bf16_f32 v6, v6, v7
	v_cvt_pk_bf16_f32 v7, v8, v9
	v_cvt_pk_bf16_f32 v8, v2, v3
	v_cvt_pk_bf16_f32 v9, v4, v5
	s_and_b64 vcc, exec, s[0:1]
	s_mov_b32 s45, s18
	s_mov_b32 s46, s30
	s_mov_b64 s[22:23], s[80:81]
	s_mov_b64 s[20:21], s[38:39]
	s_mov_b32 s64, 0x800000
	s_movk_i32 s65, 0x1fff
	v_readlane_b32 s49, v254, 41
	v_readlane_b32 s50, v254, 42
	v_readlane_b32 s51, v254, 43
	v_readlane_b32 s52, v254, 44
	v_readlane_b32 s53, v254, 45
	v_readlane_b32 s54, v254, 46
	v_readlane_b32 s55, v254, 47
	v_readlane_b32 s56, v254, 48
	v_readlane_b32 s57, v254, 49
	v_readlane_b32 s58, v254, 50
	v_readlane_b32 s59, v254, 51
	v_readlane_b32 s60, v254, 52
	v_readlane_b32 s61, v254, 53
	global_store_dwordx4 v[150:151], v[126:129], off
	global_store_dwordx4 v[110:111], v[106:109], off
	global_store_dwordx4 v[94:95], v[90:93], off
	global_store_dwordx4 v[78:79], v[74:77], off
	global_store_dwordx4 v[78:79], v[70:73], off offset:256
	global_store_dwordx4 v[58:59], v[62:65], off
	global_store_dwordx4 v[48:49], v[42:45], off
	global_store_dwordx4 v[32:33], v[26:29], off
	global_store_dwordx4 v[16:17], v[10:13], off
	global_store_dwordx4 v[14:15], v[6:9], off offset:256
	s_cbranch_vccz .LBB0_366
	s_waitcnt vmcnt(0)
	v_readlane_b32 s44, v255, 30
	s_mov_b32 s66, s90
	s_cmpk_gt_u32 s25, 0xff
	v_readlane_b32 s45, v255, 31
	v_readlane_b32 s42, v255, 32
	s_cbranch_scc1 .LBB0_377
	s_barrier

.LBB0_386:
	s_add_u32 s20, s18, 0xfffe0080
	s_addc_u32 s21, s19, -1
	s_cmp_eq_u32 s49, 4
	s_cselect_b32 s23, s44, s21
	s_cselect_b32 s22, s45, s20
	s_cselect_b32 s21, s39, s48
	s_cselect_b32 s20, s46, s47
	v_lshl_add_u64 v[178:179], s[18:19], 0, v[146:147]
	s_add_i32 m0, s90, 0xc000
	ds_read_b128 v[162:165], v156
	ds_read_b128 v[166:169], v156 offset:1024
	ds_read_b128 v[170:173], v156 offset:2048
	ds_read_b128 v[174:177], v156 offset:3072
	ds_read_b128 v[192:195], v156 offset:4096
	ds_read_b128 v[196:199], v156 offset:5120
	ds_read_b128 v[200:203], v156 offset:6144
	ds_read_b128 v[204:207], v156 offset:7168
	global_load_lds_dwordx4 v[178:179], off
	s_add_i32 m0, s90, 0xe000
	v_lshl_add_u64 v[178:179], s[18:19], 0, v[148:149]
	global_load_lds_dwordx4 v[178:179], off
	s_barrier
	s_waitcnt lgkmcnt(0)
	v_mfma_f32_16x16x32_bf16 v[126:129], v[130:133], v[162:165], v[126:129]
	v_mfma_f32_16x16x32_bf16 v[122:125], v[150:153], v[162:165], v[122:125]
	v_mfma_f32_16x16x32_bf16 v[118:121], v[130:133], v[170:173], v[118:121]
	v_mfma_f32_16x16x32_bf16 v[110:113], v[150:153], v[170:173], v[110:113]
	v_mfma_f32_16x16x32_bf16 v[102:105], v[130:133], v[192:195], v[102:105]
	v_mfma_f32_16x16x32_bf16 v[94:97], v[150:153], v[192:195], v[94:97]
	v_mfma_f32_16x16x32_bf16 v[86:89], v[130:133], v[200:203], v[86:89]
	v_mfma_f32_16x16x32_bf16 v[78:81], v[150:153], v[200:203], v[78:81]
	v_mfma_f32_16x16x32_bf16 v[126:129], v[134:137], v[166:169], v[126:129]
	v_mfma_f32_16x16x32_bf16 v[122:125], v[158:161], v[166:169], v[122:125]
	v_mfma_f32_16x16x32_bf16 v[118:121], v[134:137], v[174:177], v[118:121]
	v_mfma_f32_16x16x32_bf16 v[110:113], v[158:161], v[174:177], v[110:113]
	v_mfma_f32_16x16x32_bf16 v[102:105], v[134:137], v[196:199], v[102:105]
	v_mfma_f32_16x16x32_bf16 v[94:97], v[158:161], v[196:199], v[94:97]
	v_mfma_f32_16x16x32_bf16 v[86:89], v[134:137], v[204:207], v[86:89]
	v_mfma_f32_16x16x32_bf16 v[78:81], v[158:161], v[204:207], v[78:81]
	s_barrier
	s_add_i32 s50, s36, 0x10000
	v_add_u32_e32 v157, 0x14000, v154
	v_lshl_add_u64 v[178:179], s[20:21], 0, v[142:143]
	s_mov_b32 m0, s50
	ds_read_b128 v[208:211], v157
	ds_read_b128 v[224:227], v157 offset:1024
	ds_read_b128 v[228:231], v157 offset:2048
	ds_read_b128 v[232:235], v157 offset:3072
	global_load_lds_dwordx4 v[178:179], off
	s_add_i32 m0, s50, 0x2000
	v_lshl_add_u64 v[212:213], s[20:21], 0, v[138:139]
	global_load_lds_dwordx4 v[212:213], off
	s_mov_b32 m0, s90
	v_lshl_add_u64 v[236:237], s[22:23], 0, v[144:145]
	s_waitcnt lgkmcnt(0)
	s_barrier
	v_mfma_f32_16x16x32_bf16 v[114:117], v[208:211], v[162:165], v[114:117]
	v_mfma_f32_16x16x32_bf16 v[106:109], v[228:231], v[162:165], v[106:109]
	v_mfma_f32_16x16x32_bf16 v[98:101], v[208:211], v[170:173], v[98:101]
	v_mfma_f32_16x16x32_bf16 v[90:93], v[228:231], v[170:173], v[90:93]
	v_mfma_f32_16x16x32_bf16 v[82:85], v[208:211], v[192:195], v[82:85]
	v_mfma_f32_16x16x32_bf16 v[74:77], v[228:231], v[192:195], v[74:77]
	v_mfma_f32_16x16x32_bf16 v[70:73], v[208:211], v[200:203], v[70:73]
	v_mfma_f32_16x16x32_bf16 v[66:69], v[228:231], v[200:203], v[66:69]
	v_mfma_f32_16x16x32_bf16 v[114:117], v[224:227], v[166:169], v[114:117]
	v_mfma_f32_16x16x32_bf16 v[106:109], v[232:235], v[166:169], v[106:109]
	v_mfma_f32_16x16x32_bf16 v[98:101], v[224:227], v[174:177], v[98:101]
	v_mfma_f32_16x16x32_bf16 v[90:93], v[232:235], v[174:177], v[90:93]
	v_mfma_f32_16x16x32_bf16 v[82:85], v[224:227], v[196:199], v[82:85]
	v_mfma_f32_16x16x32_bf16 v[74:77], v[232:235], v[196:199], v[74:77]
	v_mfma_f32_16x16x32_bf16 v[70:73], v[224:227], v[204:207], v[70:73]
	v_mfma_f32_16x16x32_bf16 v[66:69], v[232:235], v[204:207], v[66:69]
	s_barrier
	ds_read_b128 v[162:165], v156 offset:16384
	ds_read_b128 v[166:169], v156 offset:17408
	ds_read_b128 v[170:173], v156 offset:18432
	ds_read_b128 v[174:177], v156 offset:19456
	ds_read_b128 v[192:195], v156 offset:20480
	ds_read_b128 v[196:199], v156 offset:21504
	ds_read_b128 v[200:203], v156 offset:22528
	ds_read_b128 v[204:207], v156 offset:23552
	global_load_lds_dwordx4 v[236:237], off
	s_mov_b32 m0, s91
	v_lshl_add_u64 v[238:239], s[22:23], 0, v[140:141]
	global_load_lds_dwordx4 v[238:239], off
	s_waitcnt vmcnt(10)
	s_barrier
	s_waitcnt lgkmcnt(0)
	v_mfma_f32_16x16x32_bf16 v[62:65], v[130:133], v[162:165], v[62:65]
	v_mfma_f32_16x16x32_bf16 v[58:61], v[150:153], v[162:165], v[58:61]
	v_mfma_f32_16x16x32_bf16 v[54:57], v[130:133], v[170:173], v[54:57]
	v_mfma_f32_16x16x32_bf16 v[46:49], v[150:153], v[170:173], v[46:49]
	v_mfma_f32_16x16x32_bf16 v[38:41], v[130:133], v[192:195], v[38:41]
	v_mfma_f32_16x16x32_bf16 v[30:33], v[150:153], v[192:195], v[30:33]
	v_mfma_f32_16x16x32_bf16 v[22:25], v[130:133], v[200:203], v[22:25]
	v_mfma_f32_16x16x32_bf16 v[14:17], v[150:153], v[200:203], v[14:17]
	v_mfma_f32_16x16x32_bf16 v[62:65], v[134:137], v[166:169], v[62:65]
	v_mfma_f32_16x16x32_bf16 v[58:61], v[158:161], v[166:169], v[58:61]
	v_mfma_f32_16x16x32_bf16 v[54:57], v[134:137], v[174:177], v[54:57]
	v_mfma_f32_16x16x32_bf16 v[46:49], v[158:161], v[174:177], v[46:49]
	v_mfma_f32_16x16x32_bf16 v[38:41], v[134:137], v[196:199], v[38:41]
	v_mfma_f32_16x16x32_bf16 v[30:33], v[158:161], v[196:199], v[30:33]
	v_mfma_f32_16x16x32_bf16 v[22:25], v[134:137], v[204:207], v[22:25]
	v_mfma_f32_16x16x32_bf16 v[14:17], v[158:161], v[204:207], v[14:17]
	s_barrier
	s_add_u32 s50, s20, 0x20000
	s_addc_u32 s51, s21, 0
	s_add_i32 s52, s36, 0x14000
	s_mov_b32 m0, s52
	v_lshl_add_u64 v[130:131], s[50:51], 0, v[142:143]
	global_load_lds_dwordx4 v[130:131], off
	s_add_i32 m0, s52, 0x2000
	v_lshl_add_u64 v[130:131], s[50:51], 0, v[138:139]
	global_load_lds_dwordx4 v[130:131], off
	v_add_u32_e32 v157, 0x18000, v154
	ds_read_b128 v[130:133], v157
	ds_read_b128 v[134:137], v157 offset:1024
	ds_read_b128 v[150:153], v157 offset:2048
	ds_read_b128 v[158:161], v157 offset:3072
	s_add_i32 s50, 0, 0x18000
	s_waitcnt vmcnt(6)
	s_barrier
	v_mfma_f32_16x16x32_bf16 v[50:53], v[208:211], v[162:165], v[50:53]
	v_mfma_f32_16x16x32_bf16 v[42:45], v[228:231], v[162:165], v[42:45]
	v_mfma_f32_16x16x32_bf16 v[34:37], v[208:211], v[170:173], v[34:37]
	v_mfma_f32_16x16x32_bf16 v[26:29], v[228:231], v[170:173], v[26:29]
	v_mfma_f32_16x16x32_bf16 v[18:21], v[208:211], v[192:195], v[18:21]
	v_mfma_f32_16x16x32_bf16 v[10:13], v[228:231], v[192:195], v[10:13]
	v_mfma_f32_16x16x32_bf16 v[6:9], v[208:211], v[200:203], v[6:9]
	v_mfma_f32_16x16x32_bf16 v[2:5], v[228:231], v[200:203], v[2:5]
	v_mfma_f32_16x16x32_bf16 v[50:53], v[224:227], v[166:169], v[50:53]
	v_mfma_f32_16x16x32_bf16 v[42:45], v[232:235], v[166:169], v[42:45]
	v_mfma_f32_16x16x32_bf16 v[34:37], v[224:227], v[174:177], v[34:37]
	v_mfma_f32_16x16x32_bf16 v[26:29], v[232:235], v[174:177], v[26:29]
	v_mfma_f32_16x16x32_bf16 v[18:21], v[224:227], v[196:199], v[18:21]
	v_mfma_f32_16x16x32_bf16 v[10:13], v[232:235], v[196:199], v[10:13]
	v_mfma_f32_16x16x32_bf16 v[6:9], v[224:227], v[204:207], v[6:9]
	v_mfma_f32_16x16x32_bf16 v[2:5], v[232:235], v[204:207], v[2:5]
	s_barrier
	s_add_u32 s22, s22, 0x20000
	s_addc_u32 s23, s23, 0
	s_mov_b32 m0, s42
	v_lshl_add_u64 v[208:209], s[22:23], 0, v[144:145]
	ds_read_b128 v[162:165], v156 offset:32768
	ds_read_b128 v[166:169], v156 offset:33792
	ds_read_b128 v[170:173], v156 offset:34816
	ds_read_b128 v[174:177], v156 offset:35840
	ds_read_b128 v[192:195], v156 offset:36864
	ds_read_b128 v[196:199], v156 offset:37888
	ds_read_b128 v[200:203], v156 offset:38912
	ds_read_b128 v[204:207], v156 offset:39936
	global_load_lds_dwordx4 v[208:209], off
	s_mov_b32 m0, s43
	v_lshl_add_u64 v[208:209], s[22:23], 0, v[140:141]
	global_load_lds_dwordx4 v[208:209], off
	s_barrier
	s_waitcnt lgkmcnt(0)
	v_mfma_f32_16x16x32_bf16 v[126:129], v[130:133], v[162:165], v[126:129]
	v_mfma_f32_16x16x32_bf16 v[122:125], v[150:153], v[162:165], v[122:125]
	v_mfma_f32_16x16x32_bf16 v[118:121], v[130:133], v[170:173], v[118:121]
	v_mfma_f32_16x16x32_bf16 v[110:113], v[150:153], v[170:173], v[110:113]
	v_mfma_f32_16x16x32_bf16 v[102:105], v[130:133], v[192:195], v[102:105]
	v_mfma_f32_16x16x32_bf16 v[94:97], v[150:153], v[192:195], v[94:97]
	v_mfma_f32_16x16x32_bf16 v[86:89], v[130:133], v[200:203], v[86:89]
	v_mfma_f32_16x16x32_bf16 v[78:81], v[150:153], v[200:203], v[78:81]
	v_mfma_f32_16x16x32_bf16 v[126:129], v[134:137], v[166:169], v[126:129]
	v_mfma_f32_16x16x32_bf16 v[122:125], v[158:161], v[166:169], v[122:125]
	v_mfma_f32_16x16x32_bf16 v[118:121], v[134:137], v[174:177], v[118:121]
	v_mfma_f32_16x16x32_bf16 v[110:113], v[158:161], v[174:177], v[110:113]
	v_mfma_f32_16x16x32_bf16 v[102:105], v[134:137], v[196:199], v[102:105]
	v_mfma_f32_16x16x32_bf16 v[94:97], v[158:161], v[196:199], v[94:97]
	v_mfma_f32_16x16x32_bf16 v[86:89], v[134:137], v[204:207], v[86:89]
	v_mfma_f32_16x16x32_bf16 v[78:81], v[158:161], v[204:207], v[78:81]
	s_barrier
	s_add_i32 s23, s50, s36
	v_add_u32_e32 v157, 0x1c000, v154
	v_lshl_add_u64 v[178:179], v[178:179], 0, s[78:79]
	s_mov_b32 m0, s23
	ds_read_b128 v[208:211], v157
	ds_read_b128 v[224:227], v157 offset:1024
	ds_read_b128 v[228:231], v157 offset:2048
	ds_read_b128 v[232:235], v157 offset:3072
	global_load_lds_dwordx4 v[178:179], off
	s_add_i32 m0, s23, 0x2000
	v_lshl_add_u64 v[178:179], v[212:213], 0, s[78:79]
	global_load_lds_dwordx4 v[178:179], off
	s_mov_b32 m0, s25
	v_lshl_add_u64 v[178:179], v[236:237], 0, s[78:79]
	s_waitcnt lgkmcnt(0)
	s_barrier
	v_mfma_f32_16x16x32_bf16 v[114:117], v[208:211], v[162:165], v[114:117]
	v_mfma_f32_16x16x32_bf16 v[106:109], v[228:231], v[162:165], v[106:109]
	v_mfma_f32_16x16x32_bf16 v[98:101], v[208:211], v[170:173], v[98:101]
	v_mfma_f32_16x16x32_bf16 v[90:93], v[228:231], v[170:173], v[90:93]
	v_mfma_f32_16x16x32_bf16 v[82:85], v[208:211], v[192:195], v[82:85]
	v_mfma_f32_16x16x32_bf16 v[74:77], v[228:231], v[192:195], v[74:77]
	v_mfma_f32_16x16x32_bf16 v[70:73], v[208:211], v[200:203], v[70:73]
	v_mfma_f32_16x16x32_bf16 v[66:69], v[228:231], v[200:203], v[66:69]
	v_mfma_f32_16x16x32_bf16 v[114:117], v[224:227], v[166:169], v[114:117]
	v_mfma_f32_16x16x32_bf16 v[106:109], v[232:235], v[166:169], v[106:109]
	v_mfma_f32_16x16x32_bf16 v[98:101], v[224:227], v[174:177], v[98:101]
	v_mfma_f32_16x16x32_bf16 v[90:93], v[232:235], v[174:177], v[90:93]
	v_mfma_f32_16x16x32_bf16 v[82:85], v[224:227], v[196:199], v[82:85]
	v_mfma_f32_16x16x32_bf16 v[74:77], v[232:235], v[196:199], v[74:77]
	v_mfma_f32_16x16x32_bf16 v[70:73], v[224:227], v[204:207], v[70:73]
	v_mfma_f32_16x16x32_bf16 v[66:69], v[232:235], v[204:207], v[66:69]
	s_barrier
	ds_read_b128 v[162:165], v156 offset:49152
	ds_read_b128 v[166:169], v156 offset:50176
	ds_read_b128 v[170:173], v156 offset:51200
	ds_read_b128 v[174:177], v156 offset:52224
	ds_read_b128 v[192:195], v156 offset:53248
	ds_read_b128 v[196:199], v156 offset:54272
	ds_read_b128 v[200:203], v156 offset:55296
	ds_read_b128 v[204:207], v156 offset:56320
	global_load_lds_dwordx4 v[178:179], off
	s_mov_b32 m0, s26
	v_lshl_add_u64 v[178:179], v[238:239], 0, s[78:79]
	global_load_lds_dwordx4 v[178:179], off
	s_waitcnt vmcnt(10)
	s_barrier
	s_waitcnt lgkmcnt(0)
	v_mfma_f32_16x16x32_bf16 v[62:65], v[130:133], v[162:165], v[62:65]
	v_mfma_f32_16x16x32_bf16 v[58:61], v[150:153], v[162:165], v[58:61]
	v_mfma_f32_16x16x32_bf16 v[54:57], v[130:133], v[170:173], v[54:57]
	v_mfma_f32_16x16x32_bf16 v[46:49], v[150:153], v[170:173], v[46:49]
	v_mfma_f32_16x16x32_bf16 v[38:41], v[130:133], v[192:195], v[38:41]
	v_mfma_f32_16x16x32_bf16 v[30:33], v[150:153], v[192:195], v[30:33]
	v_mfma_f32_16x16x32_bf16 v[22:25], v[130:133], v[200:203], v[22:25]
	v_mfma_f32_16x16x32_bf16 v[14:17], v[150:153], v[200:203], v[14:17]
	v_mfma_f32_16x16x32_bf16 v[62:65], v[134:137], v[166:169], v[62:65]
	v_mfma_f32_16x16x32_bf16 v[58:61], v[158:161], v[166:169], v[58:61]
	v_mfma_f32_16x16x32_bf16 v[54:57], v[134:137], v[174:177], v[54:57]
	v_mfma_f32_16x16x32_bf16 v[46:49], v[158:161], v[174:177], v[46:49]
	v_mfma_f32_16x16x32_bf16 v[38:41], v[134:137], v[196:199], v[38:41]
	v_mfma_f32_16x16x32_bf16 v[30:33], v[158:161], v[196:199], v[30:33]
	v_mfma_f32_16x16x32_bf16 v[22:25], v[134:137], v[204:207], v[22:25]
	v_mfma_f32_16x16x32_bf16 v[14:17], v[158:161], v[204:207], v[14:17]
	s_barrier
	s_add_u32 s20, s20, 0x20080
	s_addc_u32 s21, s21, 0
	s_add_i32 s22, s36, 0x1c000
	s_mov_b32 m0, s22
	v_lshl_add_u64 v[130:131], s[20:21], 0, v[142:143]
	global_load_lds_dwordx4 v[130:131], off
	s_add_i32 m0, s22, 0x2000
	v_lshl_add_u64 v[130:131], s[20:21], 0, v[138:139]
	global_load_lds_dwordx4 v[130:131], off
	v_add_u32_e32 v157, 0x10000, v154
	ds_read_b128 v[130:133], v157
	ds_read_b128 v[134:137], v157 offset:1024
	ds_read_b128 v[150:153], v157 offset:2048
	ds_read_b128 v[158:161], v157 offset:3072
	s_add_i32 s49, s49, 2
	s_add_u32 s18, s18, 0x100
	s_addc_u32 s19, s19, 0
	s_add_u32 s47, s47, 0x100
	s_addc_u32 s48, s48, 0
	s_cmp_gt_u32 s49, 5
	s_waitcnt vmcnt(6)
	s_barrier
	v_mfma_f32_16x16x32_bf16 v[50:53], v[208:211], v[162:165], v[50:53]
	v_mfma_f32_16x16x32_bf16 v[42:45], v[228:231], v[162:165], v[42:45]
	v_mfma_f32_16x16x32_bf16 v[34:37], v[208:211], v[170:173], v[34:37]
	v_mfma_f32_16x16x32_bf16 v[26:29], v[228:231], v[170:173], v[26:29]
	v_mfma_f32_16x16x32_bf16 v[18:21], v[208:211], v[192:195], v[18:21]
	v_mfma_f32_16x16x32_bf16 v[10:13], v[228:231], v[192:195], v[10:13]
	v_mfma_f32_16x16x32_bf16 v[6:9], v[208:211], v[200:203], v[6:9]
	v_mfma_f32_16x16x32_bf16 v[2:5], v[228:231], v[200:203], v[2:5]
	v_mfma_f32_16x16x32_bf16 v[50:53], v[224:227], v[166:169], v[50:53]
	v_mfma_f32_16x16x32_bf16 v[42:45], v[232:235], v[166:169], v[42:45]
	v_mfma_f32_16x16x32_bf16 v[34:37], v[224:227], v[174:177], v[34:37]
	v_mfma_f32_16x16x32_bf16 v[26:29], v[232:235], v[174:177], v[26:29]
	v_mfma_f32_16x16x32_bf16 v[18:21], v[224:227], v[196:199], v[18:21]
	v_mfma_f32_16x16x32_bf16 v[10:13], v[232:235], v[196:199], v[10:13]
	v_mfma_f32_16x16x32_bf16 v[6:9], v[224:227], v[204:207], v[6:9]
	v_mfma_f32_16x16x32_bf16 v[2:5], v[232:235], v[204:207], v[2:5]
	s_barrier
	s_cbranch_scc0 .LBB0_386
	s_waitcnt lgkmcnt(0)
	v_lshl_add_u32 v164, s29, 8, v1
	v_lshl_or_b32 v150, s28, 8, v155
	s_mov_b64 s[18:19], -1
	s_cmp_lt_i32 s28, 8
	v_or_b32_e32 v163, 16, v164
	v_or_b32_e32 v162, 32, v164
	v_or_b32_e32 v161, 48, v164
	v_add_u32_e32 v160, 0x80, v164
	v_add_u32_e32 v159, 0x90, v164
	v_add_u32_e32 v158, 0xa0, v164
	v_add_u32_e32 v157, 0xb0, v164
	s_cbranch_scc1 .LBB0_389
	v_lshlrev_b32_e32 v130, 7, v164
	v_readlane_b32 s4, v255, 4
	v_and_b32_e32 v132, 0x3e780, v130
	v_mov_b32_e32 v133, v0
	v_readlane_b32 s5, v255, 5
	v_readlane_b32 s6, v255, 6
	v_readlane_b32 s7, v255, 7
	v_lshlrev_b32_e32 v130, 1, v150
	v_lshl_add_u64 v[134:135], s[4:5], 0, v[132:133]
	v_and_b32_e32 v130, 0x70, v130
	v_mov_b32_e32 v131, v0
	v_lshl_add_u64 v[132:133], s[6:7], 0, v[132:133]
	v_lshl_add_u64 v[152:153], v[132:133], 0, v[130:131]
	v_lshl_add_u64 v[136:137], v[134:135], 0, v[130:131]
	global_load_dwordx4 v[170:173], v[152:153], off
	global_load_dwordx4 v[166:169], v[136:137], off
	v_readlane_b32 s8, v255, 8
	v_readlane_b32 s9, v255, 9
	v_mov_b32_e32 v151, v0
	v_lshlrev_b64 v[134:135], 1, v[150:151]
	v_mov_b64_e32 v[132:133], s[8:9]
	v_mad_i64_i32 v[174:175], s[18:19], v164, s24, v[132:133]
	v_lshl_add_u64 v[174:175], v[174:175], 0, v[134:135]
	v_readlane_b32 s10, v255, 10
	v_readlane_b32 s11, v255, 11
	s_waitcnt vmcnt(0)
	v_pk_mul_f32 v[172:173], v[172:173], s[86:87] op_sel_hi:[1,0]
	v_pk_mul_f32 v[170:171], v[170:171], s[86:87] op_sel_hi:[1,0]
	v_pk_mul_f32 v[168:169], v[168:169], s[86:87] op_sel_hi:[1,0]
	v_pk_mul_f32 v[166:167], v[166:167], s[86:87] op_sel_hi:[1,0]
	v_pk_mul_f32 v[176:177], v[124:125], v[172:173]
	v_pk_mul_f32 v[178:179], v[122:123], v[170:171]
	v_pk_mul_f32 v[172:173], v[128:129], v[172:173]
	v_pk_mul_f32 v[170:171], v[126:127], v[170:171]
	v_pk_fma_f32 v[176:177], v[128:129], v[168:169], v[176:177] neg_lo:[0,0,1] neg_hi:[0,0,1]
	v_pk_fma_f32 v[178:179], v[126:127], v[166:167], v[178:179] neg_lo:[0,0,1] neg_hi:[0,0,1]
	v_pk_fma_f32 v[172:173], v[124:125], v[168:169], v[172:173]
	v_pk_fma_f32 v[168:169], v[122:123], v[166:167], v[170:171]
	v_cvt_pk_bf16_f32 v166, v178, v179
	v_cvt_pk_bf16_f32 v167, v176, v177
	v_cvt_pk_bf16_f32 v168, v168, v169
	v_cvt_pk_bf16_f32 v169, v172, v173
	global_store_dwordx4 v[174:175], v[166:169], off
	global_load_dwordx4 v[166:169], v[136:137], off
	s_nop 0
	global_load_dwordx4 v[170:173], v[152:153], off
	v_lshlrev_b32_e32 v136, 7, v163
	v_mov_b32_e32 v137, v0
	v_and_b32_e32 v136, 0x3ef80, v136
	v_lshl_add_u64 v[152:153], s[4:5], 0, v[136:137]
	v_lshl_add_u64 v[136:137], s[6:7], 0, v[136:137]
	v_lshl_add_u64 v[136:137], v[136:137], 0, v[130:131]
	v_lshl_add_u64 v[152:153], v[152:153], 0, v[130:131]
	s_waitcnt vmcnt(0)
	v_pk_mul_f32 v[168:169], v[168:169], s[86:87] op_sel_hi:[1,0]
	v_pk_mul_f32 v[172:173], v[172:173], s[86:87] op_sel_hi:[1,0]
	v_pk_mul_f32 v[170:171], v[170:171], s[86:87] op_sel_hi:[1,0]
	v_pk_mul_f32 v[166:167], v[166:167], s[86:87] op_sel_hi:[1,0]
	v_pk_mul_f32 v[176:177], v[108:109], v[172:173]
	v_pk_mul_f32 v[178:179], v[106:107], v[170:171]
	v_pk_mul_f32 v[172:173], v[116:117], v[172:173]
	v_pk_mul_f32 v[170:171], v[114:115], v[170:171]
	v_pk_fma_f32 v[176:177], v[116:117], v[168:169], v[176:177] neg_lo:[0,0,1] neg_hi:[0,0,1]
	v_pk_fma_f32 v[178:179], v[114:115], v[166:167], v[178:179] neg_lo:[0,0,1] neg_hi:[0,0,1]
	v_pk_fma_f32 v[172:173], v[108:109], v[168:169], v[172:173]
	v_pk_fma_f32 v[168:169], v[106:107], v[166:167], v[170:171]
	v_cvt_pk_bf16_f32 v166, v178, v179
	v_cvt_pk_bf16_f32 v167, v176, v177
	v_cvt_pk_bf16_f32 v168, v168, v169
	v_cvt_pk_bf16_f32 v169, v172, v173
	global_store_dwordx4 v[174:175], v[166:169], off offset:256
	global_load_dwordx4 v[170:173], v[136:137], off
	v_mad_i64_i32 v[174:175], s[18:19], v163, s24, v[132:133]
	global_load_dwordx4 v[166:169], v[152:153], off
	v_lshl_add_u64 v[174:175], v[174:175], 0, v[134:135]
	s_waitcnt vmcnt(0)
	v_pk_mul_f32 v[172:173], v[172:173], s[86:87] op_sel_hi:[1,0]
	v_pk_mul_f32 v[170:171], v[170:171], s[86:87] op_sel_hi:[1,0]
	v_pk_mul_f32 v[176:177], v[112:113], v[172:173]
	v_pk_mul_f32 v[168:169], v[168:169], s[86:87] op_sel_hi:[1,0]
	v_pk_mul_f32 v[166:167], v[166:167], s[86:87] op_sel_hi:[1,0]
	v_pk_mul_f32 v[178:179], v[110:111], v[170:171]
	v_pk_mul_f32 v[172:173], v[120:121], v[172:173]
	v_pk_mul_f32 v[170:171], v[118:119], v[170:171]
	v_pk_fma_f32 v[176:177], v[120:121], v[168:169], v[176:177] neg_lo:[0,0,1] neg_hi:[0,0,1]
	v_pk_fma_f32 v[178:179], v[118:119], v[166:167], v[178:179] neg_lo:[0,0,1] neg_hi:[0,0,1]
	v_pk_fma_f32 v[172:173], v[112:113], v[168:169], v[172:173]
	v_pk_fma_f32 v[168:169], v[110:111], v[166:167], v[170:171]
	v_cvt_pk_bf16_f32 v166, v178, v179
	v_cvt_pk_bf16_f32 v167, v176, v177
	v_cvt_pk_bf16_f32 v168, v168, v169
	v_cvt_pk_bf16_f32 v169, v172, v173
	global_store_dwordx4 v[174:175], v[166:169], off
	global_load_dwordx4 v[166:169], v[152:153], off
	s_nop 0
	global_load_dwordx4 v[170:173], v[136:137], off
	v_lshlrev_b32_e32 v136, 7, v162
	v_mov_b32_e32 v137, v0
	v_and_b32_e32 v136, 0x3f780, v136
	v_lshl_add_u64 v[152:153], s[4:5], 0, v[136:137]
	v_lshl_add_u64 v[136:137], s[6:7], 0, v[136:137]
	v_lshl_add_u64 v[136:137], v[136:137], 0, v[130:131]
	v_lshl_add_u64 v[152:153], v[152:153], 0, v[130:131]
	s_waitcnt vmcnt(0)
	v_pk_mul_f32 v[168:169], v[168:169], s[86:87] op_sel_hi:[1,0]
	v_pk_mul_f32 v[172:173], v[172:173], s[86:87] op_sel_hi:[1,0]
	v_pk_mul_f32 v[170:171], v[170:171], s[86:87] op_sel_hi:[1,0]
	v_pk_mul_f32 v[166:167], v[166:167], s[86:87] op_sel_hi:[1,0]
	v_pk_mul_f32 v[176:177], v[92:93], v[172:173]
	v_pk_mul_f32 v[178:179], v[90:91], v[170:171]
	v_pk_mul_f32 v[172:173], v[100:101], v[172:173]
	v_pk_mul_f32 v[170:171], v[98:99], v[170:171]
	v_pk_fma_f32 v[176:177], v[100:101], v[168:169], v[176:177] neg_lo:[0,0,1] neg_hi:[0,0,1]
	v_pk_fma_f32 v[178:179], v[98:99], v[166:167], v[178:179] neg_lo:[0,0,1] neg_hi:[0,0,1]
	v_pk_fma_f32 v[172:173], v[92:93], v[168:169], v[172:173]
	v_pk_fma_f32 v[168:169], v[90:91], v[166:167], v[170:171]
	v_cvt_pk_bf16_f32 v166, v178, v179
	v_cvt_pk_bf16_f32 v167, v176, v177
	v_cvt_pk_bf16_f32 v168, v168, v169
	v_cvt_pk_bf16_f32 v169, v172, v173
	global_store_dwordx4 v[174:175], v[166:169], off offset:256
	global_load_dwordx4 v[170:173], v[136:137], off
	v_mad_i64_i32 v[174:175], s[18:19], v162, s24, v[132:133]
	global_load_dwordx4 v[166:169], v[152:153], off
	v_lshl_add_u64 v[174:175], v[174:175], 0, v[134:135]
	s_waitcnt vmcnt(0)
	v_pk_mul_f32 v[172:173], v[172:173], s[86:87] op_sel_hi:[1,0]
	v_pk_mul_f32 v[170:171], v[170:171], s[86:87] op_sel_hi:[1,0]
	v_pk_mul_f32 v[176:177], v[96:97], v[172:173]
	v_pk_mul_f32 v[168:169], v[168:169], s[86:87] op_sel_hi:[1,0]
	v_pk_mul_f32 v[166:167], v[166:167], s[86:87] op_sel_hi:[1,0]
	v_pk_mul_f32 v[178:179], v[94:95], v[170:171]
	v_pk_mul_f32 v[172:173], v[104:105], v[172:173]
	v_pk_mul_f32 v[170:171], v[102:103], v[170:171]
	v_pk_fma_f32 v[176:177], v[104:105], v[168:169], v[176:177] neg_lo:[0,0,1] neg_hi:[0,0,1]
	v_pk_fma_f32 v[178:179], v[102:103], v[166:167], v[178:179] neg_lo:[0,0,1] neg_hi:[0,0,1]
	v_pk_fma_f32 v[172:173], v[96:97], v[168:169], v[172:173]
	v_pk_fma_f32 v[168:169], v[94:95], v[166:167], v[170:171]
	v_cvt_pk_bf16_f32 v166, v178, v179
	v_cvt_pk_bf16_f32 v167, v176, v177
	v_cvt_pk_bf16_f32 v168, v168, v169
	v_cvt_pk_bf16_f32 v169, v172, v173
	global_store_dwordx4 v[174:175], v[166:169], off
	global_load_dwordx4 v[166:169], v[152:153], off
	s_nop 0
	global_load_dwordx4 v[170:173], v[136:137], off
	v_lshlrev_b32_e32 v136, 7, v161
	v_mov_b32_e32 v137, v0
	v_and_b32_e32 v136, 0x3ff80, v136
	v_lshl_add_u64 v[152:153], s[4:5], 0, v[136:137]
	v_lshl_add_u64 v[136:137], s[6:7], 0, v[136:137]
	v_lshl_add_u64 v[136:137], v[136:137], 0, v[130:131]
	v_lshl_add_u64 v[152:153], v[152:153], 0, v[130:131]
	s_waitcnt vmcnt(0)
	v_pk_mul_f32 v[168:169], v[168:169], s[86:87] op_sel_hi:[1,0]
	v_pk_mul_f32 v[172:173], v[172:173], s[86:87] op_sel_hi:[1,0]
	v_pk_mul_f32 v[170:171], v[170:171], s[86:87] op_sel_hi:[1,0]
	v_pk_mul_f32 v[166:167], v[166:167], s[86:87] op_sel_hi:[1,0]
	v_pk_mul_f32 v[176:177], v[76:77], v[172:173]
	v_pk_mul_f32 v[178:179], v[74:75], v[170:171]
	v_pk_mul_f32 v[172:173], v[84:85], v[172:173]
	v_pk_mul_f32 v[170:171], v[82:83], v[170:171]
	v_pk_fma_f32 v[176:177], v[84:85], v[168:169], v[176:177] neg_lo:[0,0,1] neg_hi:[0,0,1]
	v_pk_fma_f32 v[178:179], v[82:83], v[166:167], v[178:179] neg_lo:[0,0,1] neg_hi:[0,0,1]
	v_pk_fma_f32 v[172:173], v[76:77], v[168:169], v[172:173]
	v_pk_fma_f32 v[168:169], v[74:75], v[166:167], v[170:171]
	v_cvt_pk_bf16_f32 v166, v178, v179
	v_cvt_pk_bf16_f32 v167, v176, v177
	v_cvt_pk_bf16_f32 v168, v168, v169
	v_cvt_pk_bf16_f32 v169, v172, v173
	global_store_dwordx4 v[174:175], v[166:169], off offset:256
	global_load_dwordx4 v[170:173], v[136:137], off
	v_mad_i64_i32 v[174:175], s[18:19], v161, s24, v[132:133]
	global_load_dwordx4 v[166:169], v[152:153], off
	v_lshl_add_u64 v[174:175], v[174:175], 0, v[134:135]
	s_waitcnt vmcnt(0)
	v_pk_mul_f32 v[172:173], v[172:173], s[86:87] op_sel_hi:[1,0]
	v_pk_mul_f32 v[170:171], v[170:171], s[86:87] op_sel_hi:[1,0]
	v_pk_mul_f32 v[176:177], v[80:81], v[172:173]
	v_pk_mul_f32 v[168:169], v[168:169], s[86:87] op_sel_hi:[1,0]
	v_pk_mul_f32 v[166:167], v[166:167], s[86:87] op_sel_hi:[1,0]
	v_pk_mul_f32 v[178:179], v[78:79], v[170:171]
	v_pk_mul_f32 v[172:173], v[88:89], v[172:173]
	v_pk_mul_f32 v[170:171], v[86:87], v[170:171]
	v_pk_fma_f32 v[176:177], v[88:89], v[168:169], v[176:177] neg_lo:[0,0,1] neg_hi:[0,0,1]
	v_pk_fma_f32 v[178:179], v[86:87], v[166:167], v[178:179] neg_lo:[0,0,1] neg_hi:[0,0,1]
	v_pk_fma_f32 v[172:173], v[80:81], v[168:169], v[172:173]
	v_pk_fma_f32 v[168:169], v[78:79], v[166:167], v[170:171]
	v_cvt_pk_bf16_f32 v166, v178, v179
	v_cvt_pk_bf16_f32 v167, v176, v177
	v_cvt_pk_bf16_f32 v168, v168, v169
	v_cvt_pk_bf16_f32 v169, v172, v173
	global_store_dwordx4 v[174:175], v[166:169], off
	global_load_dwordx4 v[166:169], v[152:153], off
	s_nop 0
	global_load_dwordx4 v[170:173], v[136:137], off
	v_lshlrev_b32_e32 v136, 7, v160
	v_mov_b32_e32 v137, v0
	v_and_b32_e32 v136, 0x3e780, v136
	v_lshl_add_u64 v[152:153], s[4:5], 0, v[136:137]
	v_lshl_add_u64 v[136:137], s[6:7], 0, v[136:137]
	v_lshl_add_u64 v[136:137], v[136:137], 0, v[130:131]
	v_lshl_add_u64 v[152:153], v[152:153], 0, v[130:131]
	s_waitcnt vmcnt(0)
	v_pk_mul_f32 v[168:169], v[168:169], s[86:87] op_sel_hi:[1,0]
	v_pk_mul_f32 v[172:173], v[172:173], s[86:87] op_sel_hi:[1,0]
	v_pk_mul_f32 v[170:171], v[170:171], s[86:87] op_sel_hi:[1,0]
	v_pk_mul_f32 v[166:167], v[166:167], s[86:87] op_sel_hi:[1,0]
	v_pk_mul_f32 v[176:177], v[68:69], v[172:173]
	v_pk_mul_f32 v[178:179], v[66:67], v[170:171]
	v_pk_mul_f32 v[172:173], v[72:73], v[172:173]
	v_pk_mul_f32 v[170:171], v[70:71], v[170:171]
	v_pk_fma_f32 v[176:177], v[72:73], v[168:169], v[176:177] neg_lo:[0,0,1] neg_hi:[0,0,1]
	v_pk_fma_f32 v[178:179], v[70:71], v[166:167], v[178:179] neg_lo:[0,0,1] neg_hi:[0,0,1]
	v_pk_fma_f32 v[172:173], v[68:69], v[168:169], v[172:173]
	v_pk_fma_f32 v[168:169], v[66:67], v[166:167], v[170:171]
	v_cvt_pk_bf16_f32 v166, v178, v179
	v_cvt_pk_bf16_f32 v167, v176, v177
	v_cvt_pk_bf16_f32 v168, v168, v169
	v_cvt_pk_bf16_f32 v169, v172, v173
	global_store_dwordx4 v[174:175], v[166:169], off offset:256
	global_load_dwordx4 v[170:173], v[136:137], off
	v_mad_i64_i32 v[174:175], s[18:19], v160, s24, v[132:133]
	global_load_dwordx4 v[166:169], v[152:153], off
	v_lshl_add_u64 v[174:175], v[174:175], 0, v[134:135]
	s_waitcnt vmcnt(0)
	v_pk_mul_f32 v[172:173], v[172:173], s[86:87] op_sel_hi:[1,0]
	v_pk_mul_f32 v[170:171], v[170:171], s[86:87] op_sel_hi:[1,0]
	v_pk_mul_f32 v[176:177], v[60:61], v[172:173]
	v_pk_mul_f32 v[168:169], v[168:169], s[86:87] op_sel_hi:[1,0]
	v_pk_mul_f32 v[166:167], v[166:167], s[86:87] op_sel_hi:[1,0]
	v_pk_mul_f32 v[178:179], v[58:59], v[170:171]
	v_pk_mul_f32 v[172:173], v[64:65], v[172:173]
	v_pk_mul_f32 v[170:171], v[62:63], v[170:171]
	v_pk_fma_f32 v[176:177], v[64:65], v[168:169], v[176:177] neg_lo:[0,0,1] neg_hi:[0,0,1]
	v_pk_fma_f32 v[178:179], v[62:63], v[166:167], v[178:179] neg_lo:[0,0,1] neg_hi:[0,0,1]
	v_pk_fma_f32 v[172:173], v[60:61], v[168:169], v[172:173]
	v_pk_fma_f32 v[168:169], v[58:59], v[166:167], v[170:171]
	v_cvt_pk_bf16_f32 v166, v178, v179
	v_cvt_pk_bf16_f32 v167, v176, v177
	v_cvt_pk_bf16_f32 v168, v168, v169
	v_cvt_pk_bf16_f32 v169, v172, v173
	global_store_dwordx4 v[174:175], v[166:169], off
	global_load_dwordx4 v[166:169], v[152:153], off
	s_nop 0
	global_load_dwordx4 v[170:173], v[136:137], off
	v_lshlrev_b32_e32 v136, 7, v159
	v_mov_b32_e32 v137, v0
	v_and_b32_e32 v136, 0x3ef80, v136
	v_lshl_add_u64 v[152:153], s[4:5], 0, v[136:137]
	v_lshl_add_u64 v[136:137], s[6:7], 0, v[136:137]
	v_lshl_add_u64 v[136:137], v[136:137], 0, v[130:131]
	v_lshl_add_u64 v[152:153], v[152:153], 0, v[130:131]
	s_waitcnt vmcnt(0)
	v_pk_mul_f32 v[168:169], v[168:169], s[86:87] op_sel_hi:[1,0]
	v_pk_mul_f32 v[172:173], v[172:173], s[86:87] op_sel_hi:[1,0]
	v_pk_mul_f32 v[170:171], v[170:171], s[86:87] op_sel_hi:[1,0]
	v_pk_mul_f32 v[166:167], v[166:167], s[86:87] op_sel_hi:[1,0]
	v_pk_mul_f32 v[176:177], v[44:45], v[172:173]
	v_pk_mul_f32 v[178:179], v[42:43], v[170:171]
	v_pk_mul_f32 v[172:173], v[52:53], v[172:173]
	v_pk_mul_f32 v[170:171], v[50:51], v[170:171]
	v_pk_fma_f32 v[176:177], v[52:53], v[168:169], v[176:177] neg_lo:[0,0,1] neg_hi:[0,0,1]
	v_pk_fma_f32 v[178:179], v[50:51], v[166:167], v[178:179] neg_lo:[0,0,1] neg_hi:[0,0,1]
	v_pk_fma_f32 v[172:173], v[44:45], v[168:169], v[172:173]
	v_pk_fma_f32 v[168:169], v[42:43], v[166:167], v[170:171]
	v_cvt_pk_bf16_f32 v166, v178, v179
	v_cvt_pk_bf16_f32 v167, v176, v177
	v_cvt_pk_bf16_f32 v168, v168, v169
	v_cvt_pk_bf16_f32 v169, v172, v173
	global_store_dwordx4 v[174:175], v[166:169], off offset:256
	global_load_dwordx4 v[170:173], v[136:137], off
	v_mad_i64_i32 v[174:175], s[18:19], v159, s24, v[132:133]
	global_load_dwordx4 v[166:169], v[152:153], off
	v_lshl_add_u64 v[174:175], v[174:175], 0, v[134:135]
	s_waitcnt vmcnt(0)
	v_pk_mul_f32 v[172:173], v[172:173], s[86:87] op_sel_hi:[1,0]
	v_pk_mul_f32 v[170:171], v[170:171], s[86:87] op_sel_hi:[1,0]
	v_pk_mul_f32 v[176:177], v[48:49], v[172:173]
	v_pk_mul_f32 v[168:169], v[168:169], s[86:87] op_sel_hi:[1,0]
	v_pk_mul_f32 v[166:167], v[166:167], s[86:87] op_sel_hi:[1,0]
	v_pk_mul_f32 v[178:179], v[46:47], v[170:171]
	v_pk_mul_f32 v[172:173], v[56:57], v[172:173]
	v_pk_mul_f32 v[170:171], v[54:55], v[170:171]
	v_pk_fma_f32 v[176:177], v[56:57], v[168:169], v[176:177] neg_lo:[0,0,1] neg_hi:[0,0,1]
	v_pk_fma_f32 v[178:179], v[54:55], v[166:167], v[178:179] neg_lo:[0,0,1] neg_hi:[0,0,1]
	v_pk_fma_f32 v[172:173], v[48:49], v[168:169], v[172:173]
	v_pk_fma_f32 v[168:169], v[46:47], v[166:167], v[170:171]
	v_cvt_pk_bf16_f32 v166, v178, v179
	v_cvt_pk_bf16_f32 v167, v176, v177
	v_cvt_pk_bf16_f32 v168, v168, v169
	v_cvt_pk_bf16_f32 v169, v172, v173
	global_store_dwordx4 v[174:175], v[166:169], off
	global_load_dwordx4 v[166:169], v[152:153], off
	s_nop 0
	global_load_dwordx4 v[170:173], v[136:137], off
	v_lshlrev_b32_e32 v136, 7, v158
	v_mov_b32_e32 v137, v0
	v_and_b32_e32 v136, 0x3f780, v136
	v_lshl_add_u64 v[152:153], s[4:5], 0, v[136:137]
	v_lshl_add_u64 v[136:137], s[6:7], 0, v[136:137]
	v_lshl_add_u64 v[136:137], v[136:137], 0, v[130:131]
	v_lshl_add_u64 v[152:153], v[152:153], 0, v[130:131]
	s_waitcnt vmcnt(0)
	v_pk_mul_f32 v[168:169], v[168:169], s[86:87] op_sel_hi:[1,0]
	v_pk_mul_f32 v[172:173], v[172:173], s[86:87] op_sel_hi:[1,0]
	v_pk_mul_f32 v[170:171], v[170:171], s[86:87] op_sel_hi:[1,0]
	v_pk_mul_f32 v[166:167], v[166:167], s[86:87] op_sel_hi:[1,0]
	v_pk_mul_f32 v[176:177], v[28:29], v[172:173]
	v_pk_mul_f32 v[178:179], v[26:27], v[170:171]
	v_pk_mul_f32 v[172:173], v[36:37], v[172:173]
	v_pk_mul_f32 v[170:171], v[34:35], v[170:171]
	v_pk_fma_f32 v[176:177], v[36:37], v[168:169], v[176:177] neg_lo:[0,0,1] neg_hi:[0,0,1]
	v_pk_fma_f32 v[178:179], v[34:35], v[166:167], v[178:179] neg_lo:[0,0,1] neg_hi:[0,0,1]
	v_pk_fma_f32 v[172:173], v[28:29], v[168:169], v[172:173]
	v_pk_fma_f32 v[168:169], v[26:27], v[166:167], v[170:171]
	v_cvt_pk_bf16_f32 v166, v178, v179
	v_cvt_pk_bf16_f32 v167, v176, v177
	v_cvt_pk_bf16_f32 v168, v168, v169
	v_cvt_pk_bf16_f32 v169, v172, v173
	global_store_dwordx4 v[174:175], v[166:169], off offset:256
	global_load_dwordx4 v[170:173], v[136:137], off
	v_mad_i64_i32 v[174:175], s[18:19], v158, s24, v[132:133]
	global_load_dwordx4 v[166:169], v[152:153], off
	v_lshl_add_u64 v[174:175], v[174:175], 0, v[134:135]
	s_waitcnt vmcnt(0)
	v_pk_mul_f32 v[172:173], v[172:173], s[86:87] op_sel_hi:[1,0]
	v_pk_mul_f32 v[170:171], v[170:171], s[86:87] op_sel_hi:[1,0]
	v_pk_mul_f32 v[176:177], v[32:33], v[172:173]
	v_pk_mul_f32 v[168:169], v[168:169], s[86:87] op_sel_hi:[1,0]
	v_pk_mul_f32 v[166:167], v[166:167], s[86:87] op_sel_hi:[1,0]
	v_pk_mul_f32 v[178:179], v[30:31], v[170:171]
	v_pk_mul_f32 v[172:173], v[40:41], v[172:173]
	v_pk_mul_f32 v[170:171], v[38:39], v[170:171]
	v_pk_fma_f32 v[176:177], v[40:41], v[168:169], v[176:177] neg_lo:[0,0,1] neg_hi:[0,0,1]
	v_pk_fma_f32 v[178:179], v[38:39], v[166:167], v[178:179] neg_lo:[0,0,1] neg_hi:[0,0,1]
	v_pk_fma_f32 v[172:173], v[32:33], v[168:169], v[172:173]
	v_pk_fma_f32 v[168:169], v[30:31], v[166:167], v[170:171]
	v_cvt_pk_bf16_f32 v166, v178, v179
	v_cvt_pk_bf16_f32 v167, v176, v177
	v_cvt_pk_bf16_f32 v168, v168, v169
	v_cvt_pk_bf16_f32 v169, v172, v173
	global_store_dwordx4 v[174:175], v[166:169], off
	global_load_dwordx4 v[166:169], v[152:153], off
	s_nop 0
	global_load_dwordx4 v[170:173], v[136:137], off
	v_lshlrev_b32_e32 v136, 7, v157
	v_mov_b32_e32 v137, v0
	v_and_b32_e32 v136, 0x3ff80, v136
	v_lshl_add_u64 v[152:153], s[4:5], 0, v[136:137]
	v_lshl_add_u64 v[176:177], v[152:153], 0, v[130:131]
	v_lshl_add_u64 v[136:137], s[6:7], 0, v[136:137]
	v_lshl_add_u64 v[136:137], v[136:137], 0, v[130:131]
	v_mad_i64_i32 v[130:131], s[18:19], v157, s24, v[132:133]
	s_mov_b64 s[18:19], 0
	s_waitcnt vmcnt(0)
	v_pk_mul_f32 v[152:153], v[168:169], s[86:87] op_sel_hi:[1,0]
	v_pk_mul_f32 v[168:169], v[172:173], s[86:87] op_sel_hi:[1,0]
	v_pk_mul_f32 v[170:171], v[170:171], s[86:87] op_sel_hi:[1,0]
	v_pk_mul_f32 v[166:167], v[166:167], s[86:87] op_sel_hi:[1,0]
	v_pk_mul_f32 v[172:173], v[12:13], v[168:169]
	v_pk_mul_f32 v[178:179], v[10:11], v[170:171]
	v_pk_mul_f32 v[168:169], v[20:21], v[168:169]
	v_pk_mul_f32 v[170:171], v[18:19], v[170:171]
	v_pk_fma_f32 v[172:173], v[20:21], v[152:153], v[172:173] neg_lo:[0,0,1] neg_hi:[0,0,1]
	v_pk_fma_f32 v[178:179], v[18:19], v[166:167], v[178:179] neg_lo:[0,0,1] neg_hi:[0,0,1]
	v_pk_fma_f32 v[152:153], v[12:13], v[152:153], v[168:169]
	v_pk_fma_f32 v[168:169], v[10:11], v[166:167], v[170:171]
	v_cvt_pk_bf16_f32 v166, v178, v179
	v_cvt_pk_bf16_f32 v167, v172, v173
	v_cvt_pk_bf16_f32 v168, v168, v169
	v_cvt_pk_bf16_f32 v169, v152, v153
	global_store_dwordx4 v[174:175], v[166:169], off offset:256
	global_load_dwordx4 v[166:169], v[176:177], off
	v_lshl_add_u64 v[152:153], v[130:131], 0, v[134:135]
	global_load_dwordx4 v[170:173], v[136:137], off
	s_waitcnt vmcnt(0)
	v_pk_mul_f32 v[132:133], v[166:167], s[86:87] op_sel_hi:[1,0]
	v_pk_mul_f32 v[130:131], v[168:169], s[86:87] op_sel_hi:[1,0]
	v_pk_mul_f32 v[134:135], v[172:173], s[86:87] op_sel_hi:[1,0]
	v_pk_mul_f32 v[166:167], v[170:171], s[86:87] op_sel_hi:[1,0]
	v_pk_mul_f32 v[168:169], v[16:17], v[134:135]
	v_pk_mul_f32 v[170:171], v[14:15], v[166:167]
	v_pk_mul_f32 v[134:135], v[24:25], v[134:135]
	v_pk_mul_f32 v[166:167], v[22:23], v[166:167]
	v_pk_fma_f32 v[168:169], v[24:25], v[130:131], v[168:169] neg_lo:[0,0,1] neg_hi:[0,0,1]
	v_pk_fma_f32 v[170:171], v[22:23], v[132:133], v[170:171] neg_lo:[0,0,1] neg_hi:[0,0,1]
	v_pk_fma_f32 v[134:135], v[16:17], v[130:131], v[134:135]
	v_pk_fma_f32 v[132:133], v[14:15], v[132:133], v[166:167]
	v_cvt_pk_bf16_f32 v130, v170, v171
	v_cvt_pk_bf16_f32 v131, v168, v169
	v_cvt_pk_bf16_f32 v132, v132, v133
	v_cvt_pk_bf16_f32 v133, v134, v135
	global_store_dwordx4 v[152:153], v[130:133], off
	global_load_dwordx4 v[130:133], v[176:177], off
	s_nop 0
	global_load_dwordx4 v[134:137], v[136:137], off
	s_waitcnt vmcnt(0)
	v_pk_mul_f32 v[166:167], v[132:133], s[86:87] op_sel_hi:[1,0]
	v_pk_mul_f32 v[168:169], v[130:131], s[86:87] op_sel_hi:[1,0]
	v_pk_mul_f32 v[130:131], v[136:137], s[86:87] op_sel_hi:[1,0]
	v_pk_mul_f32 v[132:133], v[134:135], s[86:87] op_sel_hi:[1,0]
	v_pk_mul_f32 v[134:135], v[4:5], v[130:131]
	v_pk_mul_f32 v[136:137], v[2:3], v[132:133]
	v_pk_mul_f32 v[170:171], v[8:9], v[130:131]
	v_pk_mul_f32 v[172:173], v[6:7], v[132:133]
	v_pk_fma_f32 v[132:133], v[8:9], v[166:167], v[134:135] neg_lo:[0,0,1] neg_hi:[0,0,1]
	v_pk_fma_f32 v[130:131], v[6:7], v[168:169], v[136:137] neg_lo:[0,0,1] neg_hi:[0,0,1]
	v_pk_fma_f32 v[136:137], v[4:5], v[166:167], v[170:171]
	v_pk_fma_f32 v[134:135], v[2:3], v[168:169], v[172:173]

.LBB0_526:
	s_add_u32 s20, s18, 0xfff80080
	s_addc_u32 s21, s19, -1
	s_cmp_eq_u32 s55, 28
	s_cselect_b32 s23, s39, s21
	s_cselect_b32 s22, s51, s20
	s_cselect_b32 s21, s31, s54
	s_cselect_b32 s20, s52, s53
	v_lshl_add_u64 v[152:153], s[18:19], 0, v[140:141]
	s_add_i32 m0, s29, 0xc000
	ds_read_b128 v[164:167], v154
	ds_read_b128 v[168:171], v154 offset:1024
	ds_read_b128 v[172:175], v154 offset:2048
	ds_read_b128 v[176:179], v154 offset:3072
	ds_read_b128 v[192:195], v154 offset:4096
	ds_read_b128 v[196:199], v154 offset:5120
	ds_read_b128 v[200:203], v154 offset:6144
	ds_read_b128 v[204:207], v154 offset:7168
	global_load_lds_dwordx4 v[152:153], off
	s_add_i32 m0, s29, 0xe000
	v_lshl_add_u64 v[152:153], s[18:19], 0, v[142:143]
	global_load_lds_dwordx4 v[152:153], off
	s_barrier
	s_waitcnt lgkmcnt(0)
	v_mfma_f32_16x16x32_bf16 v[126:129], v[144:147], v[164:167], v[126:129]
	v_mfma_f32_16x16x32_bf16 v[122:125], v[156:159], v[164:167], v[122:125]
	v_mfma_f32_16x16x32_bf16 v[118:121], v[144:147], v[172:175], v[118:121]
	v_mfma_f32_16x16x32_bf16 v[114:117], v[156:159], v[172:175], v[114:117]
	v_mfma_f32_16x16x32_bf16 v[102:105], v[144:147], v[192:195], v[102:105]
	v_mfma_f32_16x16x32_bf16 v[98:101], v[156:159], v[192:195], v[98:101]
	v_mfma_f32_16x16x32_bf16 v[86:89], v[144:147], v[200:203], v[86:89]
	v_mfma_f32_16x16x32_bf16 v[82:85], v[156:159], v[200:203], v[82:85]
	v_mfma_f32_16x16x32_bf16 v[126:129], v[148:151], v[168:171], v[126:129]
	v_mfma_f32_16x16x32_bf16 v[122:125], v[160:163], v[168:171], v[122:125]
	v_mfma_f32_16x16x32_bf16 v[118:121], v[148:151], v[176:179], v[118:121]
	v_mfma_f32_16x16x32_bf16 v[114:117], v[160:163], v[176:179], v[114:117]
	v_mfma_f32_16x16x32_bf16 v[102:105], v[148:151], v[196:199], v[102:105]
	v_mfma_f32_16x16x32_bf16 v[98:101], v[160:163], v[196:199], v[98:101]
	v_mfma_f32_16x16x32_bf16 v[86:89], v[148:151], v[204:207], v[86:89]
	v_mfma_f32_16x16x32_bf16 v[82:85], v[160:163], v[204:207], v[82:85]
	s_barrier
	v_add_u32_e32 v152, 0x14000, v139
	s_add_i32 s56, s28, 0x10000
	ds_read_b128 v[208:211], v152
	ds_read_b128 v[224:227], v152 offset:1024
	ds_read_b128 v[228:231], v152 offset:2048
	ds_read_b128 v[232:235], v152 offset:3072
	v_lshl_add_u64 v[152:153], s[20:21], 0, v[134:135]
	s_mov_b32 m0, s56
	v_lshl_add_u64 v[212:213], s[20:21], 0, v[130:131]
	global_load_lds_dwordx4 v[152:153], off
	s_add_i32 m0, s56, 0x2000
	s_nop 0
	global_load_lds_dwordx4 v[212:213], off
	s_mov_b32 m0, s29
	v_lshl_add_u64 v[236:237], s[22:23], 0, v[136:137]
	s_waitcnt lgkmcnt(0)
	s_barrier
	v_mfma_f32_16x16x32_bf16 v[110:113], v[208:211], v[164:167], v[110:113]
	v_mfma_f32_16x16x32_bf16 v[106:109], v[228:231], v[164:167], v[106:109]
	v_mfma_f32_16x16x32_bf16 v[94:97], v[208:211], v[172:175], v[94:97]
	v_mfma_f32_16x16x32_bf16 v[90:93], v[228:231], v[172:175], v[90:93]
	v_mfma_f32_16x16x32_bf16 v[78:81], v[208:211], v[192:195], v[78:81]
	v_mfma_f32_16x16x32_bf16 v[74:77], v[228:231], v[192:195], v[74:77]
	v_mfma_f32_16x16x32_bf16 v[70:73], v[208:211], v[200:203], v[70:73]
	v_mfma_f32_16x16x32_bf16 v[66:69], v[228:231], v[200:203], v[66:69]
	v_mfma_f32_16x16x32_bf16 v[110:113], v[224:227], v[168:171], v[110:113]
	v_mfma_f32_16x16x32_bf16 v[106:109], v[232:235], v[168:171], v[106:109]
	v_mfma_f32_16x16x32_bf16 v[94:97], v[224:227], v[176:179], v[94:97]
	v_mfma_f32_16x16x32_bf16 v[90:93], v[232:235], v[176:179], v[90:93]
	v_mfma_f32_16x16x32_bf16 v[78:81], v[224:227], v[196:199], v[78:81]
	v_mfma_f32_16x16x32_bf16 v[74:77], v[232:235], v[196:199], v[74:77]
	v_mfma_f32_16x16x32_bf16 v[70:73], v[224:227], v[204:207], v[70:73]
	v_mfma_f32_16x16x32_bf16 v[66:69], v[232:235], v[204:207], v[66:69]
	s_barrier
	ds_read_b128 v[164:167], v154 offset:16384
	ds_read_b128 v[168:171], v154 offset:17408
	ds_read_b128 v[172:175], v154 offset:18432
	ds_read_b128 v[176:179], v154 offset:19456
	ds_read_b128 v[192:195], v154 offset:20480
	ds_read_b128 v[196:199], v154 offset:21504
	ds_read_b128 v[200:203], v154 offset:22528
	ds_read_b128 v[204:207], v154 offset:23552
	global_load_lds_dwordx4 v[236:237], off
	s_mov_b32 m0, s44
	v_lshl_add_u64 v[238:239], s[22:23], 0, v[132:133]
	global_load_lds_dwordx4 v[238:239], off
	s_waitcnt vmcnt(10)
	s_barrier
	s_waitcnt lgkmcnt(0)
	v_mfma_f32_16x16x32_bf16 v[62:65], v[144:147], v[164:167], v[62:65]
	v_mfma_f32_16x16x32_bf16 v[58:61], v[156:159], v[164:167], v[58:61]
	v_mfma_f32_16x16x32_bf16 v[54:57], v[144:147], v[172:175], v[54:57]
	v_mfma_f32_16x16x32_bf16 v[50:53], v[156:159], v[172:175], v[50:53]
	v_mfma_f32_16x16x32_bf16 v[38:41], v[144:147], v[192:195], v[38:41]
	v_mfma_f32_16x16x32_bf16 v[34:37], v[156:159], v[192:195], v[34:37]
	v_mfma_f32_16x16x32_bf16 v[22:25], v[144:147], v[200:203], v[22:25]
	v_mfma_f32_16x16x32_bf16 v[18:21], v[156:159], v[200:203], v[18:21]
	v_mfma_f32_16x16x32_bf16 v[62:65], v[148:151], v[168:171], v[62:65]
	v_mfma_f32_16x16x32_bf16 v[58:61], v[160:163], v[168:171], v[58:61]
	v_mfma_f32_16x16x32_bf16 v[54:57], v[148:151], v[176:179], v[54:57]
	v_mfma_f32_16x16x32_bf16 v[50:53], v[160:163], v[176:179], v[50:53]
	v_mfma_f32_16x16x32_bf16 v[38:41], v[148:151], v[196:199], v[38:41]
	v_mfma_f32_16x16x32_bf16 v[34:37], v[160:163], v[196:199], v[34:37]
	v_mfma_f32_16x16x32_bf16 v[22:25], v[148:151], v[204:207], v[22:25]
	v_mfma_f32_16x16x32_bf16 v[18:21], v[160:163], v[204:207], v[18:21]
	s_barrier
	s_add_u32 s56, s20, 0x80000
	s_addc_u32 s57, s21, 0
	s_add_i32 s58, s28, 0x14000
	s_mov_b32 m0, s58
	v_lshl_add_u64 v[144:145], s[56:57], 0, v[134:135]
	global_load_lds_dwordx4 v[144:145], off
	s_add_i32 m0, s58, 0x2000
	v_lshl_add_u64 v[144:145], s[56:57], 0, v[130:131]
	global_load_lds_dwordx4 v[144:145], off
	v_add_u32_e32 v155, 0x18000, v139
	ds_read_b128 v[144:147], v155
	ds_read_b128 v[148:151], v155 offset:1024
	ds_read_b128 v[156:159], v155 offset:2048
	ds_read_b128 v[160:163], v155 offset:3072
	s_add_i32 s56, 0, 0x18000
	s_waitcnt vmcnt(6)
	s_barrier
	v_mfma_f32_16x16x32_bf16 v[46:49], v[208:211], v[164:167], v[46:49]
	v_mfma_f32_16x16x32_bf16 v[42:45], v[228:231], v[164:167], v[42:45]
	v_mfma_f32_16x16x32_bf16 v[30:33], v[208:211], v[172:175], v[30:33]
	v_mfma_f32_16x16x32_bf16 v[26:29], v[228:231], v[172:175], v[26:29]
	v_mfma_f32_16x16x32_bf16 v[14:17], v[208:211], v[192:195], v[14:17]
	v_mfma_f32_16x16x32_bf16 v[10:13], v[228:231], v[192:195], v[10:13]
	v_mfma_f32_16x16x32_bf16 v[6:9], v[208:211], v[200:203], v[6:9]
	v_mfma_f32_16x16x32_bf16 v[2:5], v[228:231], v[200:203], v[2:5]
	v_mfma_f32_16x16x32_bf16 v[46:49], v[224:227], v[168:171], v[46:49]
	v_mfma_f32_16x16x32_bf16 v[42:45], v[232:235], v[168:171], v[42:45]
	v_mfma_f32_16x16x32_bf16 v[30:33], v[224:227], v[176:179], v[30:33]
	v_mfma_f32_16x16x32_bf16 v[26:29], v[232:235], v[176:179], v[26:29]
	v_mfma_f32_16x16x32_bf16 v[14:17], v[224:227], v[196:199], v[14:17]
	v_mfma_f32_16x16x32_bf16 v[10:13], v[232:235], v[196:199], v[10:13]
	v_mfma_f32_16x16x32_bf16 v[6:9], v[224:227], v[204:207], v[6:9]
	v_mfma_f32_16x16x32_bf16 v[2:5], v[232:235], v[204:207], v[2:5]
	s_barrier
	s_add_u32 s22, s22, 0x80000
	s_addc_u32 s23, s23, 0
	s_mov_b32 m0, s45
	v_lshl_add_u64 v[208:209], s[22:23], 0, v[136:137]
	ds_read_b128 v[164:167], v154 offset:32768
	ds_read_b128 v[168:171], v154 offset:33792
	ds_read_b128 v[172:175], v154 offset:34816
	ds_read_b128 v[176:179], v154 offset:35840
	ds_read_b128 v[192:195], v154 offset:36864
	ds_read_b128 v[196:199], v154 offset:37888
	ds_read_b128 v[200:203], v154 offset:38912
	ds_read_b128 v[204:207], v154 offset:39936
	global_load_lds_dwordx4 v[208:209], off
	s_mov_b32 m0, s46
	v_lshl_add_u64 v[208:209], s[22:23], 0, v[132:133]
	global_load_lds_dwordx4 v[208:209], off
	s_barrier
	s_waitcnt lgkmcnt(0)
	v_mfma_f32_16x16x32_bf16 v[126:129], v[144:147], v[164:167], v[126:129]
	v_mfma_f32_16x16x32_bf16 v[122:125], v[156:159], v[164:167], v[122:125]
	v_mfma_f32_16x16x32_bf16 v[118:121], v[144:147], v[172:175], v[118:121]
	v_mfma_f32_16x16x32_bf16 v[114:117], v[156:159], v[172:175], v[114:117]
	v_mfma_f32_16x16x32_bf16 v[102:105], v[144:147], v[192:195], v[102:105]
	v_mfma_f32_16x16x32_bf16 v[98:101], v[156:159], v[192:195], v[98:101]
	v_mfma_f32_16x16x32_bf16 v[86:89], v[144:147], v[200:203], v[86:89]
	v_mfma_f32_16x16x32_bf16 v[82:85], v[156:159], v[200:203], v[82:85]
	v_mfma_f32_16x16x32_bf16 v[126:129], v[148:151], v[168:171], v[126:129]
	v_mfma_f32_16x16x32_bf16 v[122:125], v[160:163], v[168:171], v[122:125]
	v_mfma_f32_16x16x32_bf16 v[118:121], v[148:151], v[176:179], v[118:121]
	v_mfma_f32_16x16x32_bf16 v[114:117], v[160:163], v[176:179], v[114:117]
	v_mfma_f32_16x16x32_bf16 v[102:105], v[148:151], v[196:199], v[102:105]
	v_mfma_f32_16x16x32_bf16 v[98:101], v[160:163], v[196:199], v[98:101]
	v_mfma_f32_16x16x32_bf16 v[86:89], v[148:151], v[204:207], v[86:89]
	v_mfma_f32_16x16x32_bf16 v[82:85], v[160:163], v[204:207], v[82:85]
	s_barrier
	s_add_i32 s23, s56, s28
	v_add_u32_e32 v155, 0x1c000, v139
	v_lshl_add_u64 v[152:153], v[152:153], 0, s[78:79]
	s_mov_b32 m0, s23
	ds_read_b128 v[208:211], v155
	ds_read_b128 v[224:227], v155 offset:1024
	ds_read_b128 v[228:231], v155 offset:2048
	ds_read_b128 v[232:235], v155 offset:3072
	global_load_lds_dwordx4 v[152:153], off
	s_add_i32 m0, s23, 0x2000
	v_lshl_add_u64 v[152:153], v[212:213], 0, s[78:79]
	global_load_lds_dwordx4 v[152:153], off
	s_mov_b32 m0, s47
	v_lshl_add_u64 v[152:153], v[236:237], 0, s[78:79]
	s_waitcnt lgkmcnt(0)
	s_barrier
	v_mfma_f32_16x16x32_bf16 v[110:113], v[208:211], v[164:167], v[110:113]
	v_mfma_f32_16x16x32_bf16 v[106:109], v[228:231], v[164:167], v[106:109]
	v_mfma_f32_16x16x32_bf16 v[94:97], v[208:211], v[172:175], v[94:97]
	v_mfma_f32_16x16x32_bf16 v[90:93], v[228:231], v[172:175], v[90:93]
	v_mfma_f32_16x16x32_bf16 v[78:81], v[208:211], v[192:195], v[78:81]
	v_mfma_f32_16x16x32_bf16 v[74:77], v[228:231], v[192:195], v[74:77]
	v_mfma_f32_16x16x32_bf16 v[70:73], v[208:211], v[200:203], v[70:73]
	v_mfma_f32_16x16x32_bf16 v[66:69], v[228:231], v[200:203], v[66:69]
	v_mfma_f32_16x16x32_bf16 v[110:113], v[224:227], v[168:171], v[110:113]
	v_mfma_f32_16x16x32_bf16 v[106:109], v[232:235], v[168:171], v[106:109]
	v_mfma_f32_16x16x32_bf16 v[94:97], v[224:227], v[176:179], v[94:97]
	v_mfma_f32_16x16x32_bf16 v[90:93], v[232:235], v[176:179], v[90:93]
	v_mfma_f32_16x16x32_bf16 v[78:81], v[224:227], v[196:199], v[78:81]
	v_mfma_f32_16x16x32_bf16 v[74:77], v[232:235], v[196:199], v[74:77]
	v_mfma_f32_16x16x32_bf16 v[70:73], v[224:227], v[204:207], v[70:73]
	v_mfma_f32_16x16x32_bf16 v[66:69], v[232:235], v[204:207], v[66:69]
	s_barrier
	ds_read_b128 v[164:167], v154 offset:49152
	ds_read_b128 v[168:171], v154 offset:50176
	ds_read_b128 v[172:175], v154 offset:51200
	ds_read_b128 v[176:179], v154 offset:52224
	ds_read_b128 v[192:195], v154 offset:53248
	ds_read_b128 v[196:199], v154 offset:54272
	ds_read_b128 v[200:203], v154 offset:55296
	ds_read_b128 v[204:207], v154 offset:56320
	global_load_lds_dwordx4 v[152:153], off
	s_mov_b32 m0, s48
	v_lshl_add_u64 v[152:153], v[238:239], 0, s[78:79]
	global_load_lds_dwordx4 v[152:153], off
	s_waitcnt vmcnt(10)
	s_barrier
	s_waitcnt lgkmcnt(0)
	v_mfma_f32_16x16x32_bf16 v[62:65], v[144:147], v[164:167], v[62:65]
	v_mfma_f32_16x16x32_bf16 v[58:61], v[156:159], v[164:167], v[58:61]
	v_mfma_f32_16x16x32_bf16 v[54:57], v[144:147], v[172:175], v[54:57]
	v_mfma_f32_16x16x32_bf16 v[50:53], v[156:159], v[172:175], v[50:53]
	v_mfma_f32_16x16x32_bf16 v[38:41], v[144:147], v[192:195], v[38:41]
	v_mfma_f32_16x16x32_bf16 v[34:37], v[156:159], v[192:195], v[34:37]
	v_mfma_f32_16x16x32_bf16 v[22:25], v[144:147], v[200:203], v[22:25]
	v_mfma_f32_16x16x32_bf16 v[18:21], v[156:159], v[200:203], v[18:21]
	v_mfma_f32_16x16x32_bf16 v[62:65], v[148:151], v[168:171], v[62:65]
	v_mfma_f32_16x16x32_bf16 v[58:61], v[160:163], v[168:171], v[58:61]
	v_mfma_f32_16x16x32_bf16 v[54:57], v[148:151], v[176:179], v[54:57]
	v_mfma_f32_16x16x32_bf16 v[50:53], v[160:163], v[176:179], v[50:53]
	v_mfma_f32_16x16x32_bf16 v[38:41], v[148:151], v[196:199], v[38:41]
	v_mfma_f32_16x16x32_bf16 v[34:37], v[160:163], v[196:199], v[34:37]
	v_mfma_f32_16x16x32_bf16 v[22:25], v[148:151], v[204:207], v[22:25]
	v_mfma_f32_16x16x32_bf16 v[18:21], v[160:163], v[204:207], v[18:21]
	s_barrier
	s_add_u32 s20, s20, 0x80080
	s_addc_u32 s21, s21, 0
	s_add_i32 s22, s28, 0x1c000
	s_mov_b32 m0, s22
	v_lshl_add_u64 v[144:145], s[20:21], 0, v[134:135]
	global_load_lds_dwordx4 v[144:145], off
	s_add_i32 m0, s22, 0x2000
	v_lshl_add_u64 v[144:145], s[20:21], 0, v[130:131]
	global_load_lds_dwordx4 v[144:145], off
	v_add_u32_e32 v152, 0x10000, v139
	ds_read_b128 v[144:147], v152
	ds_read_b128 v[148:151], v152 offset:1024
	ds_read_b128 v[156:159], v152 offset:2048
	ds_read_b128 v[160:163], v152 offset:3072
	s_add_i32 s55, s55, 2
	s_add_u32 s18, s18, 0x100
	s_addc_u32 s19, s19, 0
	s_add_u32 s53, s53, 0x100
	s_addc_u32 s54, s54, 0
	s_cmp_gt_u32 s55, 29
	s_waitcnt vmcnt(6)
	s_barrier
	v_mfma_f32_16x16x32_bf16 v[46:49], v[208:211], v[164:167], v[46:49]
	v_mfma_f32_16x16x32_bf16 v[42:45], v[228:231], v[164:167], v[42:45]
	v_mfma_f32_16x16x32_bf16 v[30:33], v[208:211], v[172:175], v[30:33]
	v_mfma_f32_16x16x32_bf16 v[26:29], v[228:231], v[172:175], v[26:29]
	v_mfma_f32_16x16x32_bf16 v[14:17], v[208:211], v[192:195], v[14:17]
	v_mfma_f32_16x16x32_bf16 v[10:13], v[228:231], v[192:195], v[10:13]
	v_mfma_f32_16x16x32_bf16 v[6:9], v[208:211], v[200:203], v[6:9]
	v_mfma_f32_16x16x32_bf16 v[2:5], v[228:231], v[200:203], v[2:5]
	v_mfma_f32_16x16x32_bf16 v[46:49], v[224:227], v[168:171], v[46:49]
	v_mfma_f32_16x16x32_bf16 v[42:45], v[232:235], v[168:171], v[42:45]
	v_mfma_f32_16x16x32_bf16 v[30:33], v[224:227], v[176:179], v[30:33]
	v_mfma_f32_16x16x32_bf16 v[26:29], v[232:235], v[176:179], v[26:29]
	v_mfma_f32_16x16x32_bf16 v[14:17], v[224:227], v[196:199], v[14:17]
	v_mfma_f32_16x16x32_bf16 v[10:13], v[232:235], v[196:199], v[10:13]
	v_mfma_f32_16x16x32_bf16 v[6:9], v[224:227], v[204:207], v[6:9]
	v_mfma_f32_16x16x32_bf16 v[2:5], v[232:235], v[204:207], v[2:5]
	s_barrier
	s_cbranch_scc0 .LBB0_526
	s_waitcnt lgkmcnt(0)
	v_lshl_add_u32 v152, s36, 8, v1
	v_or_b32_e32 v150, 16, v152
	v_or_b32_e32 v148, 32, v152
	v_or_b32_e32 v146, 48, v152
	s_mov_b64 s[18:19], -1
	s_cmp_lt_i32 s50, 8
	v_ashrrev_i32_e32 v153, 31, v152
	v_lshlrev_b32_e32 v144, 1, v138
	v_ashrrev_i32_e32 v151, 31, v150
	v_ashrrev_i32_e32 v149, 31, v148
	v_ashrrev_i32_e32 v147, 31, v146
	s_cbranch_scc1 .LBB0_529
	s_lshl_b32 s18, s50, 7
	s_add_i32 s36, s18, 0xfffffc00
	v_lshlrev_b64 v[156:157], 12, v[152:153]
	v_lshl_add_u64 v[156:157], s[72:73], 0, v[156:157]
	s_lshl_b64 s[18:19], s[36:37], 1
	v_lshl_add_u64 v[156:157], v[156:157], 0, s[18:19]
	v_mov_b32_e32 v145, v0
	v_lshl_add_u64 v[160:161], v[156:157], 0, v[144:145]
	v_pk_mul_f32 v[158:159], v[128:129], v[112:113]
	v_pk_mul_f32 v[156:157], v[126:127], v[110:111]
	v_pk_mul_f32 v[162:163], v[124:125], v[108:109]
	v_pk_mul_f32 v[164:165], v[122:123], v[106:107]
	v_cvt_pk_bf16_f32 v156, v156, v157
	v_cvt_pk_bf16_f32 v157, v158, v159
	v_cvt_pk_bf16_f32 v158, v164, v165
	v_cvt_pk_bf16_f32 v159, v162, v163
	global_store_dwordx4 v[160:161], v[156:159], off
	v_pk_mul_f32 v[164:165], v[116:117], v[92:93]
	v_pk_mul_f32 v[166:167], v[114:115], v[90:91]
	v_lshlrev_b64 v[156:157], 12, v[150:151]
	v_lshl_add_u64 v[156:157], s[72:73], 0, v[156:157]
	v_lshl_add_u64 v[156:157], v[156:157], 0, s[18:19]
	v_lshl_add_u64 v[162:163], v[156:157], 0, v[144:145]
	v_pk_mul_f32 v[158:159], v[120:121], v[96:97]
	v_pk_mul_f32 v[156:157], v[118:119], v[94:95]
	s_nop 0
	v_cvt_pk_bf16_f32 v156, v156, v157
	v_cvt_pk_bf16_f32 v157, v158, v159
	v_cvt_pk_bf16_f32 v158, v166, v167
	v_cvt_pk_bf16_f32 v159, v164, v165
	global_store_dwordx4 v[162:163], v[156:159], off
	v_pk_mul_f32 v[164:165], v[100:101], v[76:77]
	v_pk_mul_f32 v[166:167], v[98:99], v[74:75]
	v_lshlrev_b64 v[156:157], 12, v[148:149]
	v_lshl_add_u64 v[156:157], s[72:73], 0, v[156:157]
	v_lshl_add_u64 v[156:157], v[156:157], 0, s[18:19]
	v_lshl_add_u64 v[162:163], v[156:157], 0, v[144:145]
	v_pk_mul_f32 v[158:159], v[104:105], v[80:81]
	v_pk_mul_f32 v[156:157], v[102:103], v[78:79]
	s_nop 0
	v_cvt_pk_bf16_f32 v156, v156, v157
	v_cvt_pk_bf16_f32 v157, v158, v159
	v_cvt_pk_bf16_f32 v158, v166, v167
	v_cvt_pk_bf16_f32 v159, v164, v165
	global_store_dwordx4 v[162:163], v[156:159], off
	v_pk_mul_f32 v[164:165], v[84:85], v[68:69]
	v_pk_mul_f32 v[166:167], v[82:83], v[66:67]
	v_lshlrev_b64 v[156:157], 12, v[146:147]
	v_lshl_add_u64 v[156:157], s[72:73], 0, v[156:157]
	v_lshl_add_u64 v[156:157], v[156:157], 0, s[18:19]
	v_lshl_add_u64 v[162:163], v[156:157], 0, v[144:145]
	v_pk_mul_f32 v[158:159], v[88:89], v[72:73]
	v_pk_mul_f32 v[156:157], v[86:87], v[70:71]
	s_mov_b32 s18, 0x80000
	v_cvt_pk_bf16_f32 v156, v156, v157
	v_cvt_pk_bf16_f32 v157, v158, v159
	v_cvt_pk_bf16_f32 v158, v166, v167
	v_cvt_pk_bf16_f32 v159, v164, v165
	global_store_dwordx4 v[162:163], v[156:159], off
	v_pk_mul_f32 v[162:163], v[60:61], v[44:45]
	v_pk_mul_f32 v[164:165], v[58:59], v[42:43]
	v_pk_mul_f32 v[158:159], v[64:65], v[48:49]
	v_pk_mul_f32 v[156:157], v[62:63], v[46:47]
	s_nop 0
	v_cvt_pk_bf16_f32 v156, v156, v157
	v_cvt_pk_bf16_f32 v157, v158, v159
	v_cvt_pk_bf16_f32 v159, v162, v163
	v_add_co_u32_e32 v162, vcc, s18, v160
	v_cvt_pk_bf16_f32 v158, v164, v165
	s_nop 0
	v_addc_co_u32_e32 v163, vcc, 0, v161, vcc
	global_store_dwordx4 v[162:163], v[156:159], off
	v_pk_mul_f32 v[162:163], v[52:53], v[28:29]
	s_mov_b32 s18, 0x90000
	v_pk_mul_f32 v[158:159], v[56:57], v[32:33]
	v_pk_mul_f32 v[156:157], v[54:55], v[30:31]
	v_pk_mul_f32 v[164:165], v[50:51], v[26:27]
	v_cvt_pk_bf16_f32 v156, v156, v157
	v_cvt_pk_bf16_f32 v157, v158, v159
	v_cvt_pk_bf16_f32 v159, v162, v163
	v_add_co_u32_e32 v162, vcc, s18, v160
	v_cvt_pk_bf16_f32 v158, v164, v165
	s_nop 0
	v_addc_co_u32_e32 v163, vcc, 0, v161, vcc
	global_store_dwordx4 v[162:163], v[156:159], off
	v_pk_mul_f32 v[162:163], v[36:37], v[12:13]
	s_mov_b32 s18, 0xa0000
	v_pk_mul_f32 v[158:159], v[40:41], v[16:17]
	v_pk_mul_f32 v[156:157], v[38:39], v[14:15]
	v_pk_mul_f32 v[164:165], v[34:35], v[10:11]
	v_cvt_pk_bf16_f32 v156, v156, v157
	v_cvt_pk_bf16_f32 v157, v158, v159
	v_cvt_pk_bf16_f32 v159, v162, v163
	v_add_co_u32_e32 v162, vcc, s18, v160
	v_cvt_pk_bf16_f32 v158, v164, v165
	s_nop 0
	v_addc_co_u32_e32 v163, vcc, 0, v161, vcc
	global_store_dwordx4 v[162:163], v[156:159], off
	v_pk_mul_f32 v[162:163], v[20:21], v[4:5]
	v_pk_mul_f32 v[164:165], v[18:19], v[2:3]
	v_pk_mul_f32 v[158:159], v[24:25], v[8:9]
	v_pk_mul_f32 v[156:157], v[22:23], v[6:7]
	v_add_co_u32_e32 v160, vcc, 0xb0000, v160
	v_cvt_pk_bf16_f32 v156, v156, v157
	v_cvt_pk_bf16_f32 v157, v158, v159
	v_cvt_pk_bf16_f32 v158, v164, v165
	v_cvt_pk_bf16_f32 v159, v162, v163
	v_addc_co_u32_e32 v161, vcc, 0, v161, vcc
	s_mov_b64 s[18:19], 0
	global_store_dwordx4 v[160:161], v[156:159], off

.LBB0_649:
	s_add_u32 s18, s38, vcc_lo
	s_addc_u32 s19, s39, vcc_hi
	s_add_u32 s18, s18, 0x100
	s_addc_u32 s19, s19, 0
	s_add_u32 s57, s50, vcc_lo
	s_addc_u32 s58, s51, vcc_hi
	s_add_i32 s59, 0, 0x10000
	s_cmpk_eq_i32 vcc_lo, 0xf00
	s_cselect_b32 s23, s52, s19
	s_cselect_b32 s22, s53, s18
	s_cselect_b32 s19, s54, s58
	s_cselect_b32 s18, s55, s57
	v_lshl_add_u64 v[162:163], v[142:143], 0, vcc
	s_add_i32 m0, s28, 0xc000
	ds_read_b128 v[170:173], v148
	ds_read_b128 v[174:177], v148 offset:1024
	ds_read_b128 v[192:195], v148 offset:2048
	ds_read_b128 v[196:199], v148 offset:3072
	ds_read_b128 v[200:203], v148 offset:4096
	ds_read_b128 v[204:207], v148 offset:5120
	ds_read_b128 v[208:211], v148 offset:6144
	ds_read_b128 v[224:227], v148 offset:7168
	global_load_lds_dwordx4 v[162:163], off
	s_add_i32 m0, s28, 0xe000
	v_lshl_add_u64 v[162:163], v[144:145], 0, vcc
	global_load_lds_dwordx4 v[162:163], off
	s_barrier
	s_waitcnt lgkmcnt(0)
	v_mfma_f32_16x16x32_bf16 v[90:93], v[150:153], v[170:173], v[90:93]
	v_mfma_f32_16x16x32_bf16 v[94:97], v[158:161], v[170:173], v[94:97]
	v_mfma_f32_16x16x32_bf16 v[102:105], v[150:153], v[192:195], v[102:105]
	v_mfma_f32_16x16x32_bf16 v[106:109], v[158:161], v[192:195], v[106:109]
	v_mfma_f32_16x16x32_bf16 v[114:117], v[150:153], v[200:203], v[114:117]
	v_mfma_f32_16x16x32_bf16 v[118:121], v[158:161], v[200:203], v[118:121]
	v_mfma_f32_16x16x32_bf16 v[122:125], v[150:153], v[208:211], v[122:125]
	v_mfma_f32_16x16x32_bf16 v[126:129], v[158:161], v[208:211], v[126:129]
	v_mfma_f32_16x16x32_bf16 v[90:93], v[154:157], v[174:177], v[90:93]
	v_mfma_f32_16x16x32_bf16 v[94:97], v[166:169], v[174:177], v[94:97]
	v_mfma_f32_16x16x32_bf16 v[102:105], v[154:157], v[196:199], v[102:105]
	v_mfma_f32_16x16x32_bf16 v[106:109], v[166:169], v[196:199], v[106:109]
	v_mfma_f32_16x16x32_bf16 v[114:117], v[154:157], v[204:207], v[114:117]
	v_mfma_f32_16x16x32_bf16 v[118:121], v[166:169], v[204:207], v[118:121]
	v_mfma_f32_16x16x32_bf16 v[122:125], v[154:157], v[224:227], v[122:125]
	v_mfma_f32_16x16x32_bf16 v[126:129], v[166:169], v[224:227], v[126:129]
	s_barrier
	s_add_i32 s58, s59, s85
	v_add_u32_e32 v149, 0x14000, v147
	v_lshl_add_u64 v[162:163], s[18:19], 0, v[134:135]
	s_mov_b32 m0, s58
	ds_read_b128 v[228:231], v149
	ds_read_b128 v[232:235], v149 offset:1024
	ds_read_b128 v[236:239], v149 offset:2048
	ds_read_b128 v[240:243], v149 offset:3072
	global_load_lds_dwordx4 v[162:163], off
	s_add_i32 m0, s58, 0x2000
	v_lshl_add_u64 v[178:179], s[18:19], 0, v[130:131]
	global_load_lds_dwordx4 v[178:179], off
	s_mov_b32 m0, s28
	v_lshl_add_u64 v[212:213], s[22:23], 0, v[136:137]
	s_waitcnt lgkmcnt(0)
	s_barrier
	v_mfma_f32_16x16x32_bf16 v[10:13], v[228:231], v[170:173], v[10:13]
	v_mfma_f32_16x16x32_bf16 v[14:17], v[236:239], v[170:173], v[14:17]
	v_mfma_f32_16x16x32_bf16 v[26:29], v[228:231], v[192:195], v[26:29]
	v_mfma_f32_16x16x32_bf16 v[38:41], v[236:239], v[192:195], v[38:41]
	v_mfma_f32_16x16x32_bf16 v[58:61], v[228:231], v[200:203], v[58:61]
	v_mfma_f32_16x16x32_bf16 v[62:65], v[236:239], v[200:203], v[62:65]
	v_mfma_f32_16x16x32_bf16 v[74:77], v[228:231], v[208:211], v[74:77]
	v_mfma_f32_16x16x32_bf16 v[78:81], v[236:239], v[208:211], v[78:81]
	v_mfma_f32_16x16x32_bf16 v[10:13], v[232:235], v[174:177], v[10:13]
	v_mfma_f32_16x16x32_bf16 v[14:17], v[240:243], v[174:177], v[14:17]
	v_mfma_f32_16x16x32_bf16 v[26:29], v[232:235], v[196:199], v[26:29]
	v_mfma_f32_16x16x32_bf16 v[38:41], v[240:243], v[196:199], v[38:41]
	v_mfma_f32_16x16x32_bf16 v[58:61], v[232:235], v[204:207], v[58:61]
	v_mfma_f32_16x16x32_bf16 v[62:65], v[240:243], v[204:207], v[62:65]
	v_mfma_f32_16x16x32_bf16 v[74:77], v[232:235], v[224:227], v[74:77]
	v_mfma_f32_16x16x32_bf16 v[78:81], v[240:243], v[224:227], v[78:81]
	s_barrier
	ds_read_b128 v[170:173], v148 offset:16384
	ds_read_b128 v[174:177], v148 offset:17408
	ds_read_b128 v[192:195], v148 offset:18432
	ds_read_b128 v[196:199], v148 offset:19456
	ds_read_b128 v[200:203], v148 offset:20480
	ds_read_b128 v[204:207], v148 offset:21504
	ds_read_b128 v[208:211], v148 offset:22528
	ds_read_b128 v[224:227], v148 offset:23552
	global_load_lds_dwordx4 v[212:213], off
	s_mov_b32 m0, s29
	v_lshl_add_u64 v[244:245], s[22:23], 0, v[132:133]
	global_load_lds_dwordx4 v[244:245], off
	s_waitcnt vmcnt(10)
	s_barrier
	s_waitcnt lgkmcnt(0)
	v_mfma_f32_16x16x32_bf16 v[110:113], v[150:153], v[170:173], v[110:113]
	v_mfma_f32_16x16x32_bf16 v[98:101], v[158:161], v[170:173], v[98:101]
	v_mfma_f32_16x16x32_bf16 v[82:85], v[150:153], v[192:195], v[82:85]
	v_mfma_f32_16x16x32_bf16 v[66:69], v[158:161], v[192:195], v[66:69]
	v_mfma_f32_16x16x32_bf16 v[50:53], v[150:153], v[200:203], v[50:53]
	v_mfma_f32_16x16x32_bf16 v[42:45], v[158:161], v[200:203], v[42:45]
	v_mfma_f32_16x16x32_bf16 v[30:33], v[150:153], v[208:211], v[30:33]
	v_mfma_f32_16x16x32_bf16 v[18:21], v[158:161], v[208:211], v[18:21]
	v_mfma_f32_16x16x32_bf16 v[110:113], v[154:157], v[174:177], v[110:113]
	v_mfma_f32_16x16x32_bf16 v[98:101], v[166:169], v[174:177], v[98:101]
	v_mfma_f32_16x16x32_bf16 v[82:85], v[154:157], v[196:199], v[82:85]
	v_mfma_f32_16x16x32_bf16 v[66:69], v[166:169], v[196:199], v[66:69]
	v_mfma_f32_16x16x32_bf16 v[50:53], v[154:157], v[204:207], v[50:53]
	v_mfma_f32_16x16x32_bf16 v[42:45], v[166:169], v[204:207], v[42:45]
	v_mfma_f32_16x16x32_bf16 v[30:33], v[154:157], v[224:227], v[30:33]
	v_mfma_f32_16x16x32_bf16 v[18:21], v[166:169], v[224:227], v[18:21]
	s_barrier
	s_add_u32 s58, s18, 0x80000
	s_addc_u32 s59, s19, 0
	s_add_i32 s57, s85, 0x14000
	s_mov_b32 m0, s57
	v_lshl_add_u64 v[150:151], s[58:59], 0, v[134:135]
	global_load_lds_dwordx4 v[150:151], off
	s_add_i32 m0, s57, 0x2000
	v_lshl_add_u64 v[150:151], s[58:59], 0, v[130:131]
	global_load_lds_dwordx4 v[150:151], off
	v_add_u32_e32 v149, 0x18000, v147
	ds_read_b128 v[150:153], v149
	ds_read_b128 v[154:157], v149 offset:1024
	ds_read_b128 v[158:161], v149 offset:2048
	ds_read_b128 v[166:169], v149 offset:3072
	s_add_i32 s57, 0, 0x18000
	s_waitcnt vmcnt(6)
	s_barrier
	v_mfma_f32_16x16x32_bf16 v[86:89], v[228:231], v[170:173], v[86:89]
	v_mfma_f32_16x16x32_bf16 v[70:73], v[236:239], v[170:173], v[70:73]
	v_mfma_f32_16x16x32_bf16 v[54:57], v[228:231], v[192:195], v[54:57]
	v_mfma_f32_16x16x32_bf16 v[46:49], v[236:239], v[192:195], v[46:49]
	v_mfma_f32_16x16x32_bf16 v[34:37], v[228:231], v[200:203], v[34:37]
	v_mfma_f32_16x16x32_bf16 v[22:25], v[236:239], v[200:203], v[22:25]
	v_mfma_f32_16x16x32_bf16 v[6:9], v[228:231], v[208:211], v[6:9]
	v_mfma_f32_16x16x32_bf16 v[2:5], v[236:239], v[208:211], v[2:5]
	v_mfma_f32_16x16x32_bf16 v[86:89], v[232:235], v[174:177], v[86:89]
	v_mfma_f32_16x16x32_bf16 v[70:73], v[240:243], v[174:177], v[70:73]
	v_mfma_f32_16x16x32_bf16 v[54:57], v[232:235], v[196:199], v[54:57]
	v_mfma_f32_16x16x32_bf16 v[46:49], v[240:243], v[196:199], v[46:49]
	v_mfma_f32_16x16x32_bf16 v[34:37], v[232:235], v[204:207], v[34:37]
	v_mfma_f32_16x16x32_bf16 v[22:25], v[240:243], v[204:207], v[22:25]
	v_mfma_f32_16x16x32_bf16 v[6:9], v[232:235], v[224:227], v[6:9]
	v_mfma_f32_16x16x32_bf16 v[2:5], v[240:243], v[224:227], v[2:5]
	s_barrier
	s_add_u32 s22, s22, 0x80000
	s_addc_u32 s23, s23, 0
	s_mov_b32 m0, s97
	v_lshl_add_u64 v[228:229], s[22:23], 0, v[136:137]
	ds_read_b128 v[170:173], v148 offset:32768
	ds_read_b128 v[174:177], v148 offset:33792
	ds_read_b128 v[192:195], v148 offset:34816
	ds_read_b128 v[196:199], v148 offset:35840
	ds_read_b128 v[200:203], v148 offset:36864
	ds_read_b128 v[204:207], v148 offset:37888
	ds_read_b128 v[208:211], v148 offset:38912
	ds_read_b128 v[224:227], v148 offset:39936
	global_load_lds_dwordx4 v[228:229], off
	s_mov_b32 m0, s44
	v_lshl_add_u64 v[228:229], s[22:23], 0, v[132:133]
	global_load_lds_dwordx4 v[228:229], off
	s_barrier
	s_waitcnt lgkmcnt(0)
	v_mfma_f32_16x16x32_bf16 v[90:93], v[150:153], v[170:173], v[90:93]
	v_mfma_f32_16x16x32_bf16 v[94:97], v[158:161], v[170:173], v[94:97]
	v_mfma_f32_16x16x32_bf16 v[102:105], v[150:153], v[192:195], v[102:105]
	v_mfma_f32_16x16x32_bf16 v[106:109], v[158:161], v[192:195], v[106:109]
	v_mfma_f32_16x16x32_bf16 v[114:117], v[150:153], v[200:203], v[114:117]
	v_mfma_f32_16x16x32_bf16 v[118:121], v[158:161], v[200:203], v[118:121]
	v_mfma_f32_16x16x32_bf16 v[122:125], v[150:153], v[208:211], v[122:125]
	v_mfma_f32_16x16x32_bf16 v[126:129], v[158:161], v[208:211], v[126:129]
	v_mfma_f32_16x16x32_bf16 v[90:93], v[154:157], v[174:177], v[90:93]
	v_mfma_f32_16x16x32_bf16 v[94:97], v[166:169], v[174:177], v[94:97]
	v_mfma_f32_16x16x32_bf16 v[102:105], v[154:157], v[196:199], v[102:105]
	v_mfma_f32_16x16x32_bf16 v[106:109], v[166:169], v[196:199], v[106:109]
	v_mfma_f32_16x16x32_bf16 v[114:117], v[154:157], v[204:207], v[114:117]
	v_mfma_f32_16x16x32_bf16 v[118:121], v[166:169], v[204:207], v[118:121]
	v_mfma_f32_16x16x32_bf16 v[122:125], v[154:157], v[224:227], v[122:125]
	v_mfma_f32_16x16x32_bf16 v[126:129], v[166:169], v[224:227], v[126:129]
	s_barrier
	s_add_i32 s23, s57, s85
	v_add_u32_e32 v149, 0x1c000, v147
	v_lshl_add_u64 v[162:163], v[162:163], 0, s[78:79]
	s_mov_b32 m0, s23
	ds_read_b128 v[228:231], v149
	ds_read_b128 v[232:235], v149 offset:1024
	ds_read_b128 v[236:239], v149 offset:2048
	ds_read_b128 v[240:243], v149 offset:3072
	global_load_lds_dwordx4 v[162:163], off
	s_add_i32 m0, s23, 0x2000
	v_lshl_add_u64 v[162:163], v[178:179], 0, s[78:79]
	global_load_lds_dwordx4 v[162:163], off
	s_mov_b32 m0, s46
	v_lshl_add_u64 v[162:163], v[212:213], 0, s[78:79]
	s_waitcnt lgkmcnt(0)
	s_barrier
	v_mfma_f32_16x16x32_bf16 v[10:13], v[228:231], v[170:173], v[10:13]
	v_mfma_f32_16x16x32_bf16 v[14:17], v[236:239], v[170:173], v[14:17]
	v_mfma_f32_16x16x32_bf16 v[26:29], v[228:231], v[192:195], v[26:29]
	v_mfma_f32_16x16x32_bf16 v[38:41], v[236:239], v[192:195], v[38:41]
	v_mfma_f32_16x16x32_bf16 v[58:61], v[228:231], v[200:203], v[58:61]
	v_mfma_f32_16x16x32_bf16 v[62:65], v[236:239], v[200:203], v[62:65]
	v_mfma_f32_16x16x32_bf16 v[74:77], v[228:231], v[208:211], v[74:77]
	v_mfma_f32_16x16x32_bf16 v[78:81], v[236:239], v[208:211], v[78:81]
	v_mfma_f32_16x16x32_bf16 v[10:13], v[232:235], v[174:177], v[10:13]
	v_mfma_f32_16x16x32_bf16 v[14:17], v[240:243], v[174:177], v[14:17]
	v_mfma_f32_16x16x32_bf16 v[26:29], v[232:235], v[196:199], v[26:29]
	v_mfma_f32_16x16x32_bf16 v[38:41], v[240:243], v[196:199], v[38:41]
	v_mfma_f32_16x16x32_bf16 v[58:61], v[232:235], v[204:207], v[58:61]
	v_mfma_f32_16x16x32_bf16 v[62:65], v[240:243], v[204:207], v[62:65]
	v_mfma_f32_16x16x32_bf16 v[74:77], v[232:235], v[224:227], v[74:77]
	v_mfma_f32_16x16x32_bf16 v[78:81], v[240:243], v[224:227], v[78:81]
	s_barrier
	ds_read_b128 v[170:173], v148 offset:49152
	ds_read_b128 v[174:177], v148 offset:50176
	ds_read_b128 v[192:195], v148 offset:51200
	ds_read_b128 v[196:199], v148 offset:52224
	ds_read_b128 v[200:203], v148 offset:53248
	ds_read_b128 v[204:207], v148 offset:54272
	ds_read_b128 v[208:211], v148 offset:55296
	ds_read_b128 v[224:227], v148 offset:56320
	global_load_lds_dwordx4 v[162:163], off
	s_mov_b32 m0, s47
	v_lshl_add_u64 v[162:163], v[244:245], 0, s[78:79]
	global_load_lds_dwordx4 v[162:163], off
	s_waitcnt vmcnt(10)
	s_barrier
	s_waitcnt lgkmcnt(0)
	v_mfma_f32_16x16x32_bf16 v[110:113], v[150:153], v[170:173], v[110:113]
	v_mfma_f32_16x16x32_bf16 v[98:101], v[158:161], v[170:173], v[98:101]
	v_mfma_f32_16x16x32_bf16 v[82:85], v[150:153], v[192:195], v[82:85]
	v_mfma_f32_16x16x32_bf16 v[66:69], v[158:161], v[192:195], v[66:69]
	v_mfma_f32_16x16x32_bf16 v[50:53], v[150:153], v[200:203], v[50:53]
	v_mfma_f32_16x16x32_bf16 v[42:45], v[158:161], v[200:203], v[42:45]
	v_mfma_f32_16x16x32_bf16 v[30:33], v[150:153], v[208:211], v[30:33]
	v_mfma_f32_16x16x32_bf16 v[18:21], v[158:161], v[208:211], v[18:21]
	v_mfma_f32_16x16x32_bf16 v[110:113], v[154:157], v[174:177], v[110:113]
	v_mfma_f32_16x16x32_bf16 v[98:101], v[166:169], v[174:177], v[98:101]
	v_mfma_f32_16x16x32_bf16 v[82:85], v[154:157], v[196:199], v[82:85]
	v_mfma_f32_16x16x32_bf16 v[66:69], v[166:169], v[196:199], v[66:69]
	v_mfma_f32_16x16x32_bf16 v[50:53], v[154:157], v[204:207], v[50:53]
	v_mfma_f32_16x16x32_bf16 v[42:45], v[166:169], v[204:207], v[42:45]
	v_mfma_f32_16x16x32_bf16 v[30:33], v[154:157], v[224:227], v[30:33]
	v_mfma_f32_16x16x32_bf16 v[18:21], v[166:169], v[224:227], v[18:21]
	s_barrier
	s_add_u32 s18, s18, 0x80080
	s_addc_u32 s19, s19, 0
	s_add_i32 s22, s85, 0x1c000
	s_mov_b32 m0, s22
	v_lshl_add_u64 v[150:151], s[18:19], 0, v[134:135]
	global_load_lds_dwordx4 v[150:151], off
	s_add_i32 m0, s22, 0x2000
	v_lshl_add_u64 v[150:151], s[18:19], 0, v[130:131]
	global_load_lds_dwordx4 v[150:151], off
	v_add_u32_e32 v149, 0x10000, v147
	ds_read_b128 v[150:153], v149
	ds_read_b128 v[154:157], v149 offset:1024
	ds_read_b128 v[158:161], v149 offset:2048
	ds_read_b128 v[166:169], v149 offset:3072
	s_add_i32 s56, s56, 2
	s_add_u32 vcc_lo, vcc_lo, 0x100
	s_addc_u32 vcc_hi, vcc_hi, 0
	s_cmp_gt_u32 s56, 29
	s_waitcnt vmcnt(6)
	s_barrier
	v_mfma_f32_16x16x32_bf16 v[86:89], v[228:231], v[170:173], v[86:89]
	v_mfma_f32_16x16x32_bf16 v[70:73], v[236:239], v[170:173], v[70:73]
	v_mfma_f32_16x16x32_bf16 v[54:57], v[228:231], v[192:195], v[54:57]
	v_mfma_f32_16x16x32_bf16 v[46:49], v[236:239], v[192:195], v[46:49]
	v_mfma_f32_16x16x32_bf16 v[34:37], v[228:231], v[200:203], v[34:37]
	v_mfma_f32_16x16x32_bf16 v[22:25], v[236:239], v[200:203], v[22:25]
	v_mfma_f32_16x16x32_bf16 v[6:9], v[228:231], v[208:211], v[6:9]
	v_mfma_f32_16x16x32_bf16 v[2:5], v[236:239], v[208:211], v[2:5]
	v_mfma_f32_16x16x32_bf16 v[86:89], v[232:235], v[174:177], v[86:89]
	v_mfma_f32_16x16x32_bf16 v[70:73], v[240:243], v[174:177], v[70:73]
	v_mfma_f32_16x16x32_bf16 v[54:57], v[232:235], v[196:199], v[54:57]
	v_mfma_f32_16x16x32_bf16 v[46:49], v[240:243], v[196:199], v[46:49]
	v_mfma_f32_16x16x32_bf16 v[34:37], v[232:235], v[204:207], v[34:37]
	v_mfma_f32_16x16x32_bf16 v[22:25], v[240:243], v[204:207], v[22:25]
	v_mfma_f32_16x16x32_bf16 v[6:9], v[232:235], v[224:227], v[6:9]
	v_mfma_f32_16x16x32_bf16 v[2:5], v[240:243], v[224:227], v[2:5]
	s_barrier
	s_cbranch_scc0 .LBB0_649
	s_waitcnt lgkmcnt(0)
	s_add_u32 s18, s50, 0xffffff00
	s_addc_u32 s19, s51, -1
	s_andn2_b64 vcc, exec, s[42:43]
	s_cbranch_vccnz .LBB0_652
	v_mov_b32_e32 v2, 0
	s_mov_b32 s84, s80
	s_mov_b32 s25, s82
	s_mov_b64 s[38:39], s[20:21]
	s_mov_b32 s48, s49
	v_mov_b32_e32 v3, v2
	v_mov_b32_e32 v4, v2
	v_mov_b32_e32 v5, v2
	v_mov_b32_e32 v6, v2
	v_mov_b32_e32 v7, v2
	v_mov_b32_e32 v8, v2
	v_mov_b32_e32 v9, v2
	v_mov_b32_e32 v22, v2
	v_mov_b32_e32 v23, v2
	v_mov_b32_e32 v24, v2
	v_mov_b32_e32 v25, v2
	v_mov_b32_e32 v34, v2
	v_mov_b32_e32 v35, v2
	v_mov_b32_e32 v36, v2
	v_mov_b32_e32 v37, v2
	v_mov_b32_e32 v46, v2
	v_mov_b32_e32 v47, v2
	v_mov_b32_e32 v48, v2
	v_mov_b32_e32 v49, v2
	v_mov_b32_e32 v54, v2
	v_mov_b32_e32 v55, v2
	v_mov_b32_e32 v56, v2
	v_mov_b32_e32 v57, v2
	v_mov_b32_e32 v70, v2
	v_mov_b32_e32 v71, v2
	v_mov_b32_e32 v72, v2
	v_mov_b32_e32 v73, v2
	v_mov_b32_e32 v86, v2
	v_mov_b32_e32 v87, v2
	v_mov_b32_e32 v88, v2
	v_mov_b32_e32 v89, v2
	v_mov_b32_e32 v18, v2
	v_mov_b32_e32 v19, v2
	v_mov_b32_e32 v20, v2
	v_mov_b32_e32 v21, v2
	v_mov_b32_e32 v30, v2
	v_mov_b32_e32 v31, v2
	v_mov_b32_e32 v32, v2
	v_mov_b32_e32 v33, v2
	v_mov_b32_e32 v42, v2
	v_mov_b32_e32 v43, v2
	v_mov_b32_e32 v44, v2
	v_mov_b32_e32 v45, v2
	v_mov_b32_e32 v50, v2
	v_mov_b32_e32 v51, v2
	v_mov_b32_e32 v52, v2
	v_mov_b32_e32 v53, v2
	v_mov_b32_e32 v66, v2
	v_mov_b32_e32 v67, v2
	v_mov_b32_e32 v68, v2
	v_mov_b32_e32 v69, v2
	v_mov_b32_e32 v82, v2
	v_mov_b32_e32 v83, v2
	v_mov_b32_e32 v84, v2
	v_mov_b32_e32 v85, v2
	v_mov_b32_e32 v98, v2
	v_mov_b32_e32 v99, v2
	v_mov_b32_e32 v100, v2
	v_mov_b32_e32 v101, v2
	v_mov_b32_e32 v110, v2
	v_mov_b32_e32 v111, v2
	v_mov_b32_e32 v112, v2
	v_mov_b32_e32 v113, v2
	v_mov_b32_e32 v78, v2
	v_mov_b32_e32 v79, v2
	v_mov_b32_e32 v80, v2
	v_mov_b32_e32 v81, v2
	v_mov_b32_e32 v74, v2
	v_mov_b32_e32 v75, v2
	v_mov_b32_e32 v76, v2
	v_mov_b32_e32 v77, v2
	v_mov_b32_e32 v62, v2
	v_mov_b32_e32 v63, v2
	v_mov_b32_e32 v64, v2
	v_mov_b32_e32 v65, v2
	v_mov_b32_e32 v58, v2
	v_mov_b32_e32 v59, v2
	v_mov_b32_e32 v60, v2
	v_mov_b32_e32 v61, v2
	v_mov_b32_e32 v38, v2
	v_mov_b32_e32 v39, v2
	v_mov_b32_e32 v40, v2
	v_mov_b32_e32 v41, v2
	v_mov_b32_e32 v26, v2
	v_mov_b32_e32 v27, v2
	v_mov_b32_e32 v28, v2
	v_mov_b32_e32 v29, v2
	v_mov_b32_e32 v14, v2
	v_mov_b32_e32 v15, v2
	v_mov_b32_e32 v16, v2
	v_mov_b32_e32 v17, v2
	v_mov_b32_e32 v10, v2
	v_mov_b32_e32 v11, v2
	v_mov_b32_e32 v12, v2
	v_mov_b32_e32 v13, v2
	v_mov_b32_e32 v126, v2
	v_mov_b32_e32 v127, v2
	v_mov_b32_e32 v128, v2
	v_mov_b32_e32 v129, v2
	v_mov_b32_e32 v122, v2
	v_mov_b32_e32 v123, v2
	v_mov_b32_e32 v124, v2
	v_mov_b32_e32 v125, v2
	v_mov_b32_e32 v118, v2
	v_mov_b32_e32 v119, v2
	v_mov_b32_e32 v120, v2
	v_mov_b32_e32 v121, v2
	v_mov_b32_e32 v114, v2
	v_mov_b32_e32 v115, v2
	v_mov_b32_e32 v116, v2
	v_mov_b32_e32 v117, v2
	v_mov_b32_e32 v106, v2
	v_mov_b32_e32 v107, v2
	v_mov_b32_e32 v108, v2
	v_mov_b32_e32 v109, v2
	v_mov_b32_e32 v102, v2
	v_mov_b32_e32 v103, v2
	v_mov_b32_e32 v104, v2
	v_mov_b32_e32 v105, v2
	v_mov_b32_e32 v94, v2
	v_mov_b32_e32 v95, v2
	v_mov_b32_e32 v96, v2
	v_mov_b32_e32 v97, v2
	v_mov_b32_e32 v90, v2
	v_mov_b32_e32 v91, v2
	v_mov_b32_e32 v92, v2
	v_mov_b32_e32 v93, v2
	s_andn2_b64 vcc, exec, s[0:1]
	s_cbranch_vccnz .LBB0_653
	s_branch .LBB0_654

.LBB0_749:
	s_add_u32 s20, s18, 0xfff80080
	s_addc_u32 s21, s19, -1
	s_cmp_eq_u32 s57, 28
	s_cselect_b32 s23, s39, s21
	s_cselect_b32 s22, s53, s20
	s_cselect_b32 s21, s31, s56
	s_cselect_b32 s20, s54, s55
	v_lshl_add_u64 v[212:213], s[18:19], 0, v[154:155]
	s_add_i32 m0, s44, 0xc000
	ds_read_b128 v[176:179], v158
	ds_read_b128 v[192:195], v158 offset:1024
	ds_read_b128 v[196:199], v158 offset:2048
	ds_read_b128 v[200:203], v158 offset:3072
	ds_read_b128 v[204:207], v158 offset:4096
	ds_read_b128 v[208:211], v158 offset:5120
	ds_read_b128 v[224:227], v158 offset:6144
	ds_read_b128 v[228:231], v158 offset:7168
	global_load_lds_dwordx4 v[212:213], off
	s_add_i32 m0, s44, 0xe000
	v_lshl_add_u64 v[212:213], s[18:19], 0, v[156:157]
	global_load_lds_dwordx4 v[212:213], off
	s_barrier
	s_waitcnt lgkmcnt(0)
	v_mfma_f32_16x16x32_bf16 v[126:129], v[160:163], v[176:179], v[126:129]
	v_mfma_f32_16x16x32_bf16 v[122:125], v[168:171], v[176:179], v[122:125]
	v_mfma_f32_16x16x32_bf16 v[110:113], v[160:163], v[196:199], v[110:113]
	v_mfma_f32_16x16x32_bf16 v[106:109], v[168:171], v[196:199], v[106:109]
	v_mfma_f32_16x16x32_bf16 v[94:97], v[160:163], v[204:207], v[94:97]
	v_mfma_f32_16x16x32_bf16 v[90:93], v[168:171], v[204:207], v[90:93]
	v_mfma_f32_16x16x32_bf16 v[78:81], v[160:163], v[224:227], v[78:81]
	v_mfma_f32_16x16x32_bf16 v[74:77], v[168:171], v[224:227], v[74:77]
	v_mfma_f32_16x16x32_bf16 v[126:129], v[164:167], v[192:195], v[126:129]
	v_mfma_f32_16x16x32_bf16 v[122:125], v[172:175], v[192:195], v[122:125]
	v_mfma_f32_16x16x32_bf16 v[110:113], v[164:167], v[200:203], v[110:113]
	v_mfma_f32_16x16x32_bf16 v[106:109], v[172:175], v[200:203], v[106:109]
	v_mfma_f32_16x16x32_bf16 v[94:97], v[164:167], v[208:211], v[94:97]
	v_mfma_f32_16x16x32_bf16 v[90:93], v[172:175], v[208:211], v[90:93]
	v_mfma_f32_16x16x32_bf16 v[78:81], v[164:167], v[228:231], v[78:81]
	v_mfma_f32_16x16x32_bf16 v[74:77], v[172:175], v[228:231], v[74:77]
	s_barrier
	s_add_i32 s58, s29, 0x10000
	v_add_u32_e32 v159, 0x14000, v1
	v_lshl_add_u64 v[212:213], s[20:21], 0, v[134:135]
	s_mov_b32 m0, s58
	ds_read_b128 v[232:235], v159
	ds_read_b128 v[236:239], v159 offset:1024
	ds_read_b128 v[240:243], v159 offset:2048
	ds_read_b128 v[244:247], v159 offset:3072
	global_load_lds_dwordx4 v[212:213], off
	s_add_i32 m0, s58, 0x2000
	v_lshl_add_u64 v[248:249], s[20:21], 0, v[130:131]
	global_load_lds_dwordx4 v[248:249], off
	s_mov_b32 m0, s44
	v_lshl_add_u64 v[250:251], s[22:23], 0, v[136:137]
	s_waitcnt lgkmcnt(0)
	s_barrier
	v_mfma_f32_16x16x32_bf16 v[118:121], v[232:235], v[176:179], v[118:121]
	v_mfma_f32_16x16x32_bf16 v[114:117], v[240:243], v[176:179], v[114:117]
	v_mfma_f32_16x16x32_bf16 v[102:105], v[232:235], v[196:199], v[102:105]
	v_mfma_f32_16x16x32_bf16 v[98:101], v[240:243], v[196:199], v[98:101]
	v_mfma_f32_16x16x32_bf16 v[86:89], v[232:235], v[204:207], v[86:89]
	v_mfma_f32_16x16x32_bf16 v[82:85], v[240:243], v[204:207], v[82:85]
	v_mfma_f32_16x16x32_bf16 v[70:73], v[232:235], v[224:227], v[70:73]
	v_mfma_f32_16x16x32_bf16 v[66:69], v[240:243], v[224:227], v[66:69]
	v_mfma_f32_16x16x32_bf16 v[118:121], v[236:239], v[192:195], v[118:121]
	v_mfma_f32_16x16x32_bf16 v[114:117], v[244:247], v[192:195], v[114:117]
	v_mfma_f32_16x16x32_bf16 v[102:105], v[236:239], v[200:203], v[102:105]
	v_mfma_f32_16x16x32_bf16 v[98:101], v[244:247], v[200:203], v[98:101]
	v_mfma_f32_16x16x32_bf16 v[86:89], v[236:239], v[208:211], v[86:89]
	v_mfma_f32_16x16x32_bf16 v[82:85], v[244:247], v[208:211], v[82:85]
	v_mfma_f32_16x16x32_bf16 v[70:73], v[236:239], v[228:231], v[70:73]
	v_mfma_f32_16x16x32_bf16 v[66:69], v[244:247], v[228:231], v[66:69]
	s_barrier
	ds_read_b128 v[176:179], v158 offset:16384
	ds_read_b128 v[192:195], v158 offset:17408
	ds_read_b128 v[196:199], v158 offset:18432
	ds_read_b128 v[200:203], v158 offset:19456
	ds_read_b128 v[204:207], v158 offset:20480
	ds_read_b128 v[208:211], v158 offset:21504
	ds_read_b128 v[224:227], v158 offset:22528
	ds_read_b128 v[228:231], v158 offset:23552
	global_load_lds_dwordx4 v[250:251], off
	s_mov_b32 m0, s45
	v_lshl_add_u64 v[222:223], s[22:23], 0, v[132:133]
	global_load_lds_dwordx4 v[222:223], off
	s_waitcnt vmcnt(10)
	s_barrier
	s_waitcnt lgkmcnt(0)
	v_mfma_f32_16x16x32_bf16 v[62:65], v[160:163], v[176:179], v[62:65]
	v_mfma_f32_16x16x32_bf16 v[58:61], v[168:171], v[176:179], v[58:61]
	v_mfma_f32_16x16x32_bf16 v[46:49], v[160:163], v[196:199], v[46:49]
	v_mfma_f32_16x16x32_bf16 v[42:45], v[168:171], v[196:199], v[42:45]
	v_mfma_f32_16x16x32_bf16 v[30:33], v[160:163], v[204:207], v[30:33]
	v_mfma_f32_16x16x32_bf16 v[26:29], v[168:171], v[204:207], v[26:29]
	v_mfma_f32_16x16x32_bf16 v[14:17], v[160:163], v[224:227], v[14:17]
	v_mfma_f32_16x16x32_bf16 v[10:13], v[168:171], v[224:227], v[10:13]
	v_mfma_f32_16x16x32_bf16 v[62:65], v[164:167], v[192:195], v[62:65]
	v_mfma_f32_16x16x32_bf16 v[58:61], v[172:175], v[192:195], v[58:61]
	v_mfma_f32_16x16x32_bf16 v[46:49], v[164:167], v[200:203], v[46:49]
	v_mfma_f32_16x16x32_bf16 v[42:45], v[172:175], v[200:203], v[42:45]
	v_mfma_f32_16x16x32_bf16 v[30:33], v[164:167], v[208:211], v[30:33]
	v_mfma_f32_16x16x32_bf16 v[26:29], v[172:175], v[208:211], v[26:29]
	v_mfma_f32_16x16x32_bf16 v[14:17], v[164:167], v[228:231], v[14:17]
	v_mfma_f32_16x16x32_bf16 v[10:13], v[172:175], v[228:231], v[10:13]
	s_barrier
	s_add_u32 s58, s20, 0x80000
	s_addc_u32 s59, s21, 0
	s_add_i32 s82, s29, 0x14000
	s_mov_b32 m0, s82
	v_lshl_add_u64 v[160:161], s[58:59], 0, v[134:135]
	global_load_lds_dwordx4 v[160:161], off
	s_add_i32 m0, s82, 0x2000
	v_lshl_add_u64 v[160:161], s[58:59], 0, v[130:131]
	global_load_lds_dwordx4 v[160:161], off
	v_add_u32_e32 v159, 0x18000, v1
	ds_read_b128 v[160:163], v159
	ds_read_b128 v[164:167], v159 offset:1024
	ds_read_b128 v[168:171], v159 offset:2048
	ds_read_b128 v[172:175], v159 offset:3072
	s_add_i32 s58, 0, 0x18000
	s_waitcnt vmcnt(6)
	s_barrier
	v_mfma_f32_16x16x32_bf16 v[54:57], v[232:235], v[176:179], v[54:57]
	v_mfma_f32_16x16x32_bf16 v[50:53], v[240:243], v[176:179], v[50:53]
	v_mfma_f32_16x16x32_bf16 v[38:41], v[232:235], v[196:199], v[38:41]
	v_mfma_f32_16x16x32_bf16 v[34:37], v[240:243], v[196:199], v[34:37]
	v_mfma_f32_16x16x32_bf16 v[22:25], v[232:235], v[204:207], v[22:25]
	v_mfma_f32_16x16x32_bf16 v[18:21], v[240:243], v[204:207], v[18:21]
	v_mfma_f32_16x16x32_bf16 v[6:9], v[232:235], v[224:227], v[6:9]
	v_mfma_f32_16x16x32_bf16 v[2:5], v[240:243], v[224:227], v[2:5]
	v_mfma_f32_16x16x32_bf16 v[54:57], v[236:239], v[192:195], v[54:57]
	v_mfma_f32_16x16x32_bf16 v[50:53], v[244:247], v[192:195], v[50:53]
	v_mfma_f32_16x16x32_bf16 v[38:41], v[236:239], v[200:203], v[38:41]
	v_mfma_f32_16x16x32_bf16 v[34:37], v[244:247], v[200:203], v[34:37]
	v_mfma_f32_16x16x32_bf16 v[22:25], v[236:239], v[208:211], v[22:25]
	v_mfma_f32_16x16x32_bf16 v[18:21], v[244:247], v[208:211], v[18:21]
	v_mfma_f32_16x16x32_bf16 v[6:9], v[236:239], v[228:231], v[6:9]
	v_mfma_f32_16x16x32_bf16 v[2:5], v[244:247], v[228:231], v[2:5]
	s_barrier
	s_add_u32 s22, s22, 0x80000
	s_addc_u32 s23, s23, 0
	s_mov_b32 m0, s46
	v_lshl_add_u64 v[232:233], s[22:23], 0, v[136:137]
	ds_read_b128 v[176:179], v158 offset:32768
	ds_read_b128 v[192:195], v158 offset:33792
	ds_read_b128 v[196:199], v158 offset:34816
	ds_read_b128 v[200:203], v158 offset:35840
	ds_read_b128 v[204:207], v158 offset:36864
	ds_read_b128 v[208:211], v158 offset:37888
	ds_read_b128 v[224:227], v158 offset:38912
	ds_read_b128 v[228:231], v158 offset:39936
	global_load_lds_dwordx4 v[232:233], off
	s_mov_b32 m0, s47
	v_lshl_add_u64 v[232:233], s[22:23], 0, v[132:133]
	global_load_lds_dwordx4 v[232:233], off
	s_barrier
	s_waitcnt lgkmcnt(0)
	v_mfma_f32_16x16x32_bf16 v[126:129], v[160:163], v[176:179], v[126:129]
	v_mfma_f32_16x16x32_bf16 v[122:125], v[168:171], v[176:179], v[122:125]
	v_mfma_f32_16x16x32_bf16 v[110:113], v[160:163], v[196:199], v[110:113]
	v_mfma_f32_16x16x32_bf16 v[106:109], v[168:171], v[196:199], v[106:109]
	v_mfma_f32_16x16x32_bf16 v[94:97], v[160:163], v[204:207], v[94:97]
	v_mfma_f32_16x16x32_bf16 v[90:93], v[168:171], v[204:207], v[90:93]
	v_mfma_f32_16x16x32_bf16 v[78:81], v[160:163], v[224:227], v[78:81]
	v_mfma_f32_16x16x32_bf16 v[74:77], v[168:171], v[224:227], v[74:77]
	v_mfma_f32_16x16x32_bf16 v[126:129], v[164:167], v[192:195], v[126:129]
	v_mfma_f32_16x16x32_bf16 v[122:125], v[172:175], v[192:195], v[122:125]
	v_mfma_f32_16x16x32_bf16 v[110:113], v[164:167], v[200:203], v[110:113]
	v_mfma_f32_16x16x32_bf16 v[106:109], v[172:175], v[200:203], v[106:109]
	v_mfma_f32_16x16x32_bf16 v[94:97], v[164:167], v[208:211], v[94:97]
	v_mfma_f32_16x16x32_bf16 v[90:93], v[172:175], v[208:211], v[90:93]
	v_mfma_f32_16x16x32_bf16 v[78:81], v[164:167], v[228:231], v[78:81]
	v_mfma_f32_16x16x32_bf16 v[74:77], v[172:175], v[228:231], v[74:77]
	s_barrier
	s_add_i32 s23, s58, s29
	v_add_u32_e32 v159, 0x1c000, v1
	v_lshl_add_u64 v[212:213], v[212:213], 0, s[78:79]
	s_mov_b32 m0, s23
	ds_read_b128 v[232:235], v159
	ds_read_b128 v[236:239], v159 offset:1024
	ds_read_b128 v[240:243], v159 offset:2048
	ds_read_b128 v[244:247], v159 offset:3072
	global_load_lds_dwordx4 v[212:213], off
	s_add_i32 m0, s23, 0x2000
	v_lshl_add_u64 v[212:213], v[248:249], 0, s[78:79]
	global_load_lds_dwordx4 v[212:213], off
	s_mov_b32 m0, s48
	v_lshl_add_u64 v[212:213], v[250:251], 0, s[78:79]
	s_waitcnt lgkmcnt(0)
	s_barrier
	v_mfma_f32_16x16x32_bf16 v[118:121], v[232:235], v[176:179], v[118:121]
	v_mfma_f32_16x16x32_bf16 v[114:117], v[240:243], v[176:179], v[114:117]
	v_mfma_f32_16x16x32_bf16 v[102:105], v[232:235], v[196:199], v[102:105]
	v_mfma_f32_16x16x32_bf16 v[98:101], v[240:243], v[196:199], v[98:101]
	v_mfma_f32_16x16x32_bf16 v[86:89], v[232:235], v[204:207], v[86:89]
	v_mfma_f32_16x16x32_bf16 v[82:85], v[240:243], v[204:207], v[82:85]
	v_mfma_f32_16x16x32_bf16 v[70:73], v[232:235], v[224:227], v[70:73]
	v_mfma_f32_16x16x32_bf16 v[66:69], v[240:243], v[224:227], v[66:69]
	v_mfma_f32_16x16x32_bf16 v[118:121], v[236:239], v[192:195], v[118:121]
	v_mfma_f32_16x16x32_bf16 v[114:117], v[244:247], v[192:195], v[114:117]
	v_mfma_f32_16x16x32_bf16 v[102:105], v[236:239], v[200:203], v[102:105]
	v_mfma_f32_16x16x32_bf16 v[98:101], v[244:247], v[200:203], v[98:101]
	v_mfma_f32_16x16x32_bf16 v[86:89], v[236:239], v[208:211], v[86:89]
	v_mfma_f32_16x16x32_bf16 v[82:85], v[244:247], v[208:211], v[82:85]
	v_mfma_f32_16x16x32_bf16 v[70:73], v[236:239], v[228:231], v[70:73]
	v_mfma_f32_16x16x32_bf16 v[66:69], v[244:247], v[228:231], v[66:69]
	s_barrier
	ds_read_b128 v[176:179], v158 offset:49152
	ds_read_b128 v[192:195], v158 offset:50176
	ds_read_b128 v[196:199], v158 offset:51200
	ds_read_b128 v[200:203], v158 offset:52224
	ds_read_b128 v[204:207], v158 offset:53248
	ds_read_b128 v[208:211], v158 offset:54272
	ds_read_b128 v[224:227], v158 offset:55296
	ds_read_b128 v[228:231], v158 offset:56320
	global_load_lds_dwordx4 v[212:213], off
	s_mov_b32 m0, s49
	v_lshl_add_u64 v[212:213], v[222:223], 0, s[78:79]
	global_load_lds_dwordx4 v[212:213], off
	s_waitcnt vmcnt(10)
	s_barrier
	s_waitcnt lgkmcnt(0)
	v_mfma_f32_16x16x32_bf16 v[62:65], v[160:163], v[176:179], v[62:65]
	v_mfma_f32_16x16x32_bf16 v[58:61], v[168:171], v[176:179], v[58:61]
	v_mfma_f32_16x16x32_bf16 v[46:49], v[160:163], v[196:199], v[46:49]
	v_mfma_f32_16x16x32_bf16 v[42:45], v[168:171], v[196:199], v[42:45]
	v_mfma_f32_16x16x32_bf16 v[30:33], v[160:163], v[204:207], v[30:33]
	v_mfma_f32_16x16x32_bf16 v[26:29], v[168:171], v[204:207], v[26:29]
	v_mfma_f32_16x16x32_bf16 v[14:17], v[160:163], v[224:227], v[14:17]
	v_mfma_f32_16x16x32_bf16 v[10:13], v[168:171], v[224:227], v[10:13]
	v_mfma_f32_16x16x32_bf16 v[62:65], v[164:167], v[192:195], v[62:65]
	v_mfma_f32_16x16x32_bf16 v[58:61], v[172:175], v[192:195], v[58:61]
	v_mfma_f32_16x16x32_bf16 v[46:49], v[164:167], v[200:203], v[46:49]
	v_mfma_f32_16x16x32_bf16 v[42:45], v[172:175], v[200:203], v[42:45]
	v_mfma_f32_16x16x32_bf16 v[30:33], v[164:167], v[208:211], v[30:33]
	v_mfma_f32_16x16x32_bf16 v[26:29], v[172:175], v[208:211], v[26:29]
	v_mfma_f32_16x16x32_bf16 v[14:17], v[164:167], v[228:231], v[14:17]
	v_mfma_f32_16x16x32_bf16 v[10:13], v[172:175], v[228:231], v[10:13]
	s_barrier
	s_add_u32 s20, s20, 0x80080
	s_addc_u32 s21, s21, 0
	s_add_i32 s22, s29, 0x1c000
	s_mov_b32 m0, s22
	v_lshl_add_u64 v[160:161], s[20:21], 0, v[134:135]
	global_load_lds_dwordx4 v[160:161], off
	s_add_i32 m0, s22, 0x2000
	v_lshl_add_u64 v[160:161], s[20:21], 0, v[130:131]
	global_load_lds_dwordx4 v[160:161], off
	v_add_u32_e32 v159, 0x10000, v1
	ds_read_b128 v[160:163], v159
	ds_read_b128 v[164:167], v159 offset:1024
	ds_read_b128 v[168:171], v159 offset:2048
	ds_read_b128 v[172:175], v159 offset:3072
	s_add_i32 s57, s57, 2
	s_add_u32 s18, s18, 0x100
	s_addc_u32 s19, s19, 0
	s_add_u32 s55, s55, 0x100
	s_addc_u32 s56, s56, 0
	s_cmp_gt_u32 s57, 29
	s_waitcnt vmcnt(6)
	s_barrier
	v_mfma_f32_16x16x32_bf16 v[54:57], v[232:235], v[176:179], v[54:57]
	v_mfma_f32_16x16x32_bf16 v[50:53], v[240:243], v[176:179], v[50:53]
	v_mfma_f32_16x16x32_bf16 v[38:41], v[232:235], v[196:199], v[38:41]
	v_mfma_f32_16x16x32_bf16 v[34:37], v[240:243], v[196:199], v[34:37]
	v_mfma_f32_16x16x32_bf16 v[22:25], v[232:235], v[204:207], v[22:25]
	v_mfma_f32_16x16x32_bf16 v[18:21], v[240:243], v[204:207], v[18:21]
	v_mfma_f32_16x16x32_bf16 v[6:9], v[232:235], v[224:227], v[6:9]
	v_mfma_f32_16x16x32_bf16 v[2:5], v[240:243], v[224:227], v[2:5]
	v_mfma_f32_16x16x32_bf16 v[54:57], v[236:239], v[192:195], v[54:57]
	v_mfma_f32_16x16x32_bf16 v[50:53], v[244:247], v[192:195], v[50:53]
	v_mfma_f32_16x16x32_bf16 v[38:41], v[236:239], v[200:203], v[38:41]
	v_mfma_f32_16x16x32_bf16 v[34:37], v[244:247], v[200:203], v[34:37]
	v_mfma_f32_16x16x32_bf16 v[22:25], v[236:239], v[208:211], v[22:25]
	v_mfma_f32_16x16x32_bf16 v[18:21], v[244:247], v[208:211], v[18:21]
	v_mfma_f32_16x16x32_bf16 v[6:9], v[236:239], v[228:231], v[6:9]
	v_mfma_f32_16x16x32_bf16 v[2:5], v[244:247], v[228:231], v[2:5]
	s_barrier
	s_cbranch_scc0 .LBB0_749
	s_waitcnt lgkmcnt(0)
	s_lshl_b32 s18, s52, 5
	s_add_i32 s18, s18, s51
	v_max_f32_e32 v122, 0, v122
	v_max_f32_e32 v123, 0, v123
	s_ashr_i32 s19, s18, 31
	v_pk_mul_f32 v[162:163], v[122:123], v[122:123]
	v_max_f32_e32 v123, v124, v124
	s_lshl_b64 s[18:19], s[18:19], 17
	v_max_f32_e32 v122, v128, v128
	v_max_f32_e32 v124, 0, v123
	v_max_f32_e32 v123, v129, v129
	s_add_u32 s18, s68, s18
	v_max_f32_e32 v126, 0, v126
	v_max_f32_e32 v127, 0, v127
	v_max_f32_e32 v122, 0, v122
	v_max_f32_e32 v123, 0, v123
	v_max_f32_e32 v125, 0, v125
	s_addc_u32 s19, s69, s19
	v_pk_mul_f32 v[126:127], v[126:127], v[126:127]
	v_pk_mul_f32 v[128:129], v[122:123], v[122:123]
	v_pk_mul_f32 v[164:165], v[124:125], v[124:125]
	v_lshl_add_u64 v[160:161], v[138:139], 1, s[18:19]
	v_cvt_pk_bf16_f32 v122, v126, v127
	v_cvt_pk_bf16_f32 v123, v128, v129
	v_cvt_pk_bf16_f32 v124, v162, v163
	v_cvt_pk_bf16_f32 v125, v164, v165
	v_max_f32_e32 v114, 0, v114
	v_max_f32_e32 v115, 0, v115
	global_store_dwordx4 v[160:161], v[122:125], off
	v_max_f32_e32 v118, v118, v118
	v_max_f32_e32 v119, v119, v119
	v_pk_mul_f32 v[122:123], v[114:115], v[114:115]
	v_max_f32_e32 v115, v116, v116
	v_max_f32_e32 v114, v120, v120
	v_max_f32_e32 v116, 0, v115
	v_max_f32_e32 v115, v121, v121
	v_max_f32_e32 v118, 0, v118
	v_max_f32_e32 v119, 0, v119
	v_max_f32_e32 v114, 0, v114
	v_max_f32_e32 v115, 0, v115
	v_max_f32_e32 v117, 0, v117
	v_pk_mul_f32 v[118:119], v[118:119], v[118:119]
	v_pk_mul_f32 v[120:121], v[114:115], v[114:115]
	v_pk_mul_f32 v[124:125], v[116:117], v[116:117]
	v_cvt_pk_bf16_f32 v114, v118, v119
	v_cvt_pk_bf16_f32 v115, v120, v121
	v_cvt_pk_bf16_f32 v116, v122, v123
	v_cvt_pk_bf16_f32 v117, v124, v125
	v_max_f32_e32 v106, 0, v106
	v_max_f32_e32 v107, 0, v107
	global_store_dwordx4 v[160:161], v[114:117], off offset:256
	v_max_f32_e32 v110, v110, v110
	v_max_f32_e32 v111, v111, v111
	v_pk_mul_f32 v[116:117], v[106:107], v[106:107]
	v_max_f32_e32 v107, v108, v108
	v_max_f32_e32 v106, v112, v112
	v_max_f32_e32 v108, 0, v107
	v_max_f32_e32 v107, v113, v113
	v_max_f32_e32 v110, 0, v110
	v_max_f32_e32 v111, 0, v111
	v_max_f32_e32 v106, 0, v106
	v_max_f32_e32 v107, 0, v107
	v_max_f32_e32 v109, 0, v109
	v_pk_mul_f32 v[110:111], v[110:111], v[110:111]
	v_pk_mul_f32 v[112:113], v[106:107], v[106:107]
	v_pk_mul_f32 v[118:119], v[108:109], v[108:109]
	v_lshl_add_u64 v[114:115], v[140:141], 1, s[18:19]
	v_cvt_pk_bf16_f32 v106, v110, v111
	v_cvt_pk_bf16_f32 v107, v112, v113
	v_cvt_pk_bf16_f32 v108, v116, v117
	v_cvt_pk_bf16_f32 v109, v118, v119
	v_max_f32_e32 v98, 0, v98
	v_max_f32_e32 v99, 0, v99
	global_store_dwordx4 v[114:115], v[106:109], off
	v_max_f32_e32 v102, v102, v102
	v_max_f32_e32 v103, v103, v103
	v_pk_mul_f32 v[106:107], v[98:99], v[98:99]
	v_max_f32_e32 v99, v100, v100
	v_max_f32_e32 v98, v104, v104
	v_max_f32_e32 v100, 0, v99
	v_max_f32_e32 v99, v105, v105
	v_max_f32_e32 v102, 0, v102
	v_max_f32_e32 v103, 0, v103
	v_max_f32_e32 v98, 0, v98
	v_max_f32_e32 v99, 0, v99
	v_max_f32_e32 v101, 0, v101
	v_pk_mul_f32 v[102:103], v[102:103], v[102:103]
	v_pk_mul_f32 v[104:105], v[98:99], v[98:99]
	v_pk_mul_f32 v[108:109], v[100:101], v[100:101]
	v_cvt_pk_bf16_f32 v98, v102, v103
	v_cvt_pk_bf16_f32 v99, v104, v105
	v_cvt_pk_bf16_f32 v100, v106, v107
	v_cvt_pk_bf16_f32 v101, v108, v109
	v_max_f32_e32 v90, 0, v90
	v_max_f32_e32 v91, 0, v91
	global_store_dwordx4 v[114:115], v[98:101], off offset:256
	v_max_f32_e32 v94, v94, v94
	v_max_f32_e32 v95, v95, v95
	v_pk_mul_f32 v[100:101], v[90:91], v[90:91]
	v_max_f32_e32 v91, v92, v92
	v_max_f32_e32 v90, v96, v96
	v_max_f32_e32 v92, 0, v91
	v_max_f32_e32 v91, v97, v97
	v_max_f32_e32 v94, 0, v94
	v_max_f32_e32 v95, 0, v95
	v_max_f32_e32 v90, 0, v90
	v_max_f32_e32 v91, 0, v91
	v_max_f32_e32 v93, 0, v93
	v_pk_mul_f32 v[94:95], v[94:95], v[94:95]
	v_pk_mul_f32 v[96:97], v[90:91], v[90:91]
	v_pk_mul_f32 v[102:103], v[92:93], v[92:93]
	v_lshl_add_u64 v[98:99], v[142:143], 1, s[18:19]
	v_cvt_pk_bf16_f32 v90, v94, v95
	v_cvt_pk_bf16_f32 v91, v96, v97
	v_cvt_pk_bf16_f32 v92, v100, v101
	v_cvt_pk_bf16_f32 v93, v102, v103
	v_max_f32_e32 v82, 0, v82
	v_max_f32_e32 v83, 0, v83
	global_store_dwordx4 v[98:99], v[90:93], off
	v_max_f32_e32 v86, v86, v86
	v_max_f32_e32 v87, v87, v87
	v_pk_mul_f32 v[90:91], v[82:83], v[82:83]
	v_max_f32_e32 v83, v84, v84
	v_max_f32_e32 v82, v88, v88
	v_max_f32_e32 v84, 0, v83
	v_max_f32_e32 v83, v89, v89
	v_max_f32_e32 v86, 0, v86
	v_max_f32_e32 v87, 0, v87
	v_max_f32_e32 v82, 0, v82
	v_max_f32_e32 v83, 0, v83
	v_max_f32_e32 v85, 0, v85
	v_pk_mul_f32 v[86:87], v[86:87], v[86:87]
	v_pk_mul_f32 v[88:89], v[82:83], v[82:83]
	v_pk_mul_f32 v[92:93], v[84:85], v[84:85]
	v_cvt_pk_bf16_f32 v82, v86, v87
	v_cvt_pk_bf16_f32 v83, v88, v89
	v_cvt_pk_bf16_f32 v84, v90, v91
	v_cvt_pk_bf16_f32 v85, v92, v93
	v_max_f32_e32 v74, 0, v74
	v_max_f32_e32 v75, 0, v75
	global_store_dwordx4 v[98:99], v[82:85], off offset:256
	v_max_f32_e32 v78, v78, v78
	v_max_f32_e32 v79, v79, v79
	v_pk_mul_f32 v[84:85], v[74:75], v[74:75]
	v_max_f32_e32 v75, v76, v76
	v_max_f32_e32 v74, v80, v80
	v_max_f32_e32 v76, 0, v75
	v_max_f32_e32 v75, v81, v81
	v_max_f32_e32 v78, 0, v78
	v_max_f32_e32 v79, 0, v79
	v_max_f32_e32 v74, 0, v74
	v_max_f32_e32 v75, 0, v75
	v_max_f32_e32 v77, 0, v77
	v_pk_mul_f32 v[78:79], v[78:79], v[78:79]
	v_pk_mul_f32 v[80:81], v[74:75], v[74:75]
	v_pk_mul_f32 v[86:87], v[76:77], v[76:77]
	v_lshl_add_u64 v[82:83], v[144:145], 1, s[18:19]
	v_cvt_pk_bf16_f32 v74, v78, v79
	v_cvt_pk_bf16_f32 v75, v80, v81
	v_cvt_pk_bf16_f32 v76, v84, v85
	v_cvt_pk_bf16_f32 v77, v86, v87
	v_max_f32_e32 v66, 0, v66
	v_max_f32_e32 v67, 0, v67
	global_store_dwordx4 v[82:83], v[74:77], off
	v_max_f32_e32 v70, v70, v70
	v_max_f32_e32 v71, v71, v71
	v_pk_mul_f32 v[74:75], v[66:67], v[66:67]
	v_max_f32_e32 v67, v68, v68
	v_max_f32_e32 v66, v72, v72
	v_max_f32_e32 v68, 0, v67
	v_max_f32_e32 v67, v73, v73
	v_max_f32_e32 v70, 0, v70
	v_max_f32_e32 v71, 0, v71
	v_max_f32_e32 v66, 0, v66
	v_max_f32_e32 v67, 0, v67
	v_max_f32_e32 v69, 0, v69
	v_pk_mul_f32 v[70:71], v[70:71], v[70:71]
	v_pk_mul_f32 v[72:73], v[66:67], v[66:67]
	v_pk_mul_f32 v[76:77], v[68:69], v[68:69]
	v_cvt_pk_bf16_f32 v66, v70, v71
	v_cvt_pk_bf16_f32 v67, v72, v73
	v_cvt_pk_bf16_f32 v68, v74, v75
	v_cvt_pk_bf16_f32 v69, v76, v77
	v_max_f32_e32 v58, 0, v58
	v_max_f32_e32 v59, 0, v59
	global_store_dwordx4 v[82:83], v[66:69], off offset:256
	v_max_f32_e32 v62, v62, v62
	v_max_f32_e32 v63, v63, v63
	v_pk_mul_f32 v[68:69], v[58:59], v[58:59]
	v_max_f32_e32 v59, v60, v60
	v_max_f32_e32 v58, v64, v64
	v_max_f32_e32 v60, 0, v59
	v_max_f32_e32 v59, v65, v65
	v_max_f32_e32 v62, 0, v62
	v_max_f32_e32 v63, 0, v63
	v_max_f32_e32 v58, 0, v58
	v_max_f32_e32 v59, 0, v59
	v_max_f32_e32 v61, 0, v61
	v_pk_mul_f32 v[62:63], v[62:63], v[62:63]
	v_pk_mul_f32 v[64:65], v[58:59], v[58:59]
	v_pk_mul_f32 v[70:71], v[60:61], v[60:61]
	v_lshl_add_u64 v[66:67], v[146:147], 1, s[18:19]
	v_cvt_pk_bf16_f32 v58, v62, v63
	v_cvt_pk_bf16_f32 v59, v64, v65
	v_cvt_pk_bf16_f32 v60, v68, v69
	v_cvt_pk_bf16_f32 v61, v70, v71
	v_max_f32_e32 v50, 0, v50
	v_max_f32_e32 v51, 0, v51
	global_store_dwordx4 v[66:67], v[58:61], off
	v_max_f32_e32 v54, v54, v54
	v_max_f32_e32 v55, v55, v55
	v_pk_mul_f32 v[58:59], v[50:51], v[50:51]
	v_max_f32_e32 v51, v52, v52
	v_max_f32_e32 v50, v56, v56
	v_max_f32_e32 v52, 0, v51
	v_max_f32_e32 v51, v57, v57
	v_max_f32_e32 v54, 0, v54
	v_max_f32_e32 v55, 0, v55
	v_max_f32_e32 v50, 0, v50
	v_max_f32_e32 v51, 0, v51
	v_max_f32_e32 v53, 0, v53
	v_pk_mul_f32 v[54:55], v[54:55], v[54:55]
	v_pk_mul_f32 v[56:57], v[50:51], v[50:51]
	v_pk_mul_f32 v[60:61], v[52:53], v[52:53]
	v_cvt_pk_bf16_f32 v50, v54, v55
	v_cvt_pk_bf16_f32 v51, v56, v57
	v_cvt_pk_bf16_f32 v52, v58, v59
	v_cvt_pk_bf16_f32 v53, v60, v61
	v_max_f32_e32 v42, 0, v42
	v_max_f32_e32 v43, 0, v43
	global_store_dwordx4 v[66:67], v[50:53], off offset:256
	v_max_f32_e32 v46, v46, v46
	v_max_f32_e32 v47, v47, v47
	v_pk_mul_f32 v[52:53], v[42:43], v[42:43]
	v_max_f32_e32 v43, v44, v44
	v_max_f32_e32 v42, v48, v48
	v_max_f32_e32 v44, 0, v43
	v_max_f32_e32 v43, v49, v49
	v_max_f32_e32 v46, 0, v46
	v_max_f32_e32 v47, 0, v47
	v_max_f32_e32 v42, 0, v42
	v_max_f32_e32 v43, 0, v43
	v_max_f32_e32 v45, 0, v45
	v_pk_mul_f32 v[46:47], v[46:47], v[46:47]
	v_pk_mul_f32 v[48:49], v[42:43], v[42:43]
	v_pk_mul_f32 v[54:55], v[44:45], v[44:45]
	v_lshl_add_u64 v[50:51], v[148:149], 1, s[18:19]
	v_cvt_pk_bf16_f32 v42, v46, v47
	v_cvt_pk_bf16_f32 v43, v48, v49
	v_cvt_pk_bf16_f32 v44, v52, v53
	v_cvt_pk_bf16_f32 v45, v54, v55
	v_max_f32_e32 v34, 0, v34
	v_max_f32_e32 v35, 0, v35
	global_store_dwordx4 v[50:51], v[42:45], off
	v_max_f32_e32 v38, v38, v38
	v_max_f32_e32 v39, v39, v39
	v_pk_mul_f32 v[42:43], v[34:35], v[34:35]
	v_max_f32_e32 v35, v36, v36
	v_max_f32_e32 v34, v40, v40
	v_max_f32_e32 v36, 0, v35
	v_max_f32_e32 v35, v41, v41
	v_max_f32_e32 v38, 0, v38
	v_max_f32_e32 v39, 0, v39
	v_max_f32_e32 v34, 0, v34
	v_max_f32_e32 v35, 0, v35
	v_max_f32_e32 v37, 0, v37
	v_pk_mul_f32 v[38:39], v[38:39], v[38:39]
	v_pk_mul_f32 v[40:41], v[34:35], v[34:35]
	v_pk_mul_f32 v[44:45], v[36:37], v[36:37]
	v_cvt_pk_bf16_f32 v34, v38, v39
	v_cvt_pk_bf16_f32 v35, v40, v41
	v_cvt_pk_bf16_f32 v36, v42, v43
	v_cvt_pk_bf16_f32 v37, v44, v45
	v_max_f32_e32 v26, 0, v26
	v_max_f32_e32 v27, 0, v27
	global_store_dwordx4 v[50:51], v[34:37], off offset:256
	v_max_f32_e32 v30, v30, v30
	v_max_f32_e32 v31, v31, v31
	v_pk_mul_f32 v[36:37], v[26:27], v[26:27]
	v_max_f32_e32 v27, v28, v28
	v_max_f32_e32 v26, v32, v32
	v_max_f32_e32 v28, 0, v27
	v_max_f32_e32 v27, v33, v33
	v_max_f32_e32 v30, 0, v30
	v_max_f32_e32 v31, 0, v31
	v_max_f32_e32 v26, 0, v26
	v_max_f32_e32 v27, 0, v27
	v_max_f32_e32 v29, 0, v29
	v_pk_mul_f32 v[30:31], v[30:31], v[30:31]
	v_pk_mul_f32 v[32:33], v[26:27], v[26:27]
	v_pk_mul_f32 v[38:39], v[28:29], v[28:29]
	v_lshl_add_u64 v[34:35], v[150:151], 1, s[18:19]
	v_cvt_pk_bf16_f32 v26, v30, v31
	v_cvt_pk_bf16_f32 v27, v32, v33
	v_cvt_pk_bf16_f32 v28, v36, v37
	v_cvt_pk_bf16_f32 v29, v38, v39
	v_max_f32_e32 v18, 0, v18
	v_max_f32_e32 v19, 0, v19
	global_store_dwordx4 v[34:35], v[26:29], off
	v_max_f32_e32 v22, v22, v22
	v_max_f32_e32 v23, v23, v23
	v_pk_mul_f32 v[26:27], v[18:19], v[18:19]
	v_max_f32_e32 v19, v20, v20
	v_max_f32_e32 v18, v24, v24
	v_max_f32_e32 v20, 0, v19
	v_max_f32_e32 v19, v25, v25
	v_max_f32_e32 v22, 0, v22
	v_max_f32_e32 v23, 0, v23
	v_max_f32_e32 v18, 0, v18
	v_max_f32_e32 v19, 0, v19
	v_max_f32_e32 v21, 0, v21
	v_pk_mul_f32 v[22:23], v[22:23], v[22:23]
	v_pk_mul_f32 v[24:25], v[18:19], v[18:19]
	v_pk_mul_f32 v[28:29], v[20:21], v[20:21]
	v_cvt_pk_bf16_f32 v18, v22, v23
	v_cvt_pk_bf16_f32 v19, v24, v25
	v_cvt_pk_bf16_f32 v20, v26, v27
	v_cvt_pk_bf16_f32 v21, v28, v29
	v_max_f32_e32 v10, 0, v10
	v_max_f32_e32 v11, 0, v11
	global_store_dwordx4 v[34:35], v[18:21], off offset:256
	v_max_f32_e32 v14, v14, v14
	v_max_f32_e32 v15, v15, v15
	v_pk_mul_f32 v[20:21], v[10:11], v[10:11]
	v_max_f32_e32 v11, v12, v12
	v_max_f32_e32 v10, v16, v16
	v_max_f32_e32 v12, 0, v11
	v_max_f32_e32 v11, v17, v17
	v_max_f32_e32 v14, 0, v14
	v_max_f32_e32 v15, 0, v15
	v_max_f32_e32 v10, 0, v10
	v_max_f32_e32 v11, 0, v11
	v_max_f32_e32 v13, 0, v13
	v_pk_mul_f32 v[14:15], v[14:15], v[14:15]
	v_pk_mul_f32 v[16:17], v[10:11], v[10:11]
	v_pk_mul_f32 v[22:23], v[12:13], v[12:13]
	v_lshl_add_u64 v[18:19], v[152:153], 1, s[18:19]
	v_cvt_pk_bf16_f32 v10, v14, v15
	v_cvt_pk_bf16_f32 v11, v16, v17
	v_cvt_pk_bf16_f32 v12, v20, v21
	v_cvt_pk_bf16_f32 v13, v22, v23
	v_max_f32_e32 v2, 0, v2
	v_max_f32_e32 v3, 0, v3
	global_store_dwordx4 v[18:19], v[10:13], off
	v_max_f32_e32 v6, v6, v6
	v_max_f32_e32 v7, v7, v7
	v_pk_mul_f32 v[10:11], v[2:3], v[2:3]
	v_max_f32_e32 v3, v4, v4
	v_max_f32_e32 v2, v8, v8
	v_max_f32_e32 v4, 0, v3
	v_max_f32_e32 v3, v9, v9
	v_max_f32_e32 v6, 0, v6
	v_max_f32_e32 v7, 0, v7
	v_max_f32_e32 v2, 0, v2
	v_max_f32_e32 v3, 0, v3
	v_max_f32_e32 v5, 0, v5
	v_pk_mul_f32 v[6:7], v[6:7], v[6:7]
	v_pk_mul_f32 v[8:9], v[2:3], v[2:3]
	v_pk_mul_f32 v[12:13], v[4:5], v[4:5]
	v_cvt_pk_bf16_f32 v2, v6, v7
	v_cvt_pk_bf16_f32 v3, v8, v9
	v_cvt_pk_bf16_f32 v4, v10, v11
	v_cvt_pk_bf16_f32 v5, v12, v13
	s_and_b64 vcc, exec, s[0:1]
	s_mov_b32 s51, s30
	s_mov_b32 s52, s38
	s_mov_b64 s[20:21], s[80:81]
	s_mov_b64 s[18:19], s[42:43]
	global_store_dwordx4 v[18:19], v[2:5], off offset:256
	s_cbranch_vccz .LBB0_742
	s_waitcnt vmcnt(0)
	v_readlane_b32 s38, v255, 28
	s_cmpk_gt_u32 s26, 0xff
	v_readlane_b32 s39, v255, 29
	v_readlane_b32 s42, v255, 32
	s_cbranch_scc1 .LBB0_753
	s_barrier

.LBB0_814:
	s_add_i32 s22, s55, 0xffff0000
	s_and_b32 s22, s22, 0x3e0000
	s_and_b32 s23, s90, 0x100
	s_or_b32 s56, s23, s22
	s_and_b32 s22, s55, 0x7e0000
	s_add_u32 vcc_lo, s90, 0x100
	s_addc_u32 vcc_hi, s91, 0
	s_and_b32 s23, vcc_lo, 0x100
	s_or_b32 s22, s22, s23
	s_add_u32 s22, s84, s22
	s_addc_u32 s23, s85, 0
	s_add_u32 s57, s30, s90
	s_addc_u32 s58, s31, s91
	s_add_u32 s57, s57, 0x100
	s_addc_u32 s58, s58, 0
	s_add_i32 s59, 0, 0x10000
	s_cmpk_eq_i32 s54, 0x7c
	s_cselect_b32 s91, s43, s58
	s_cselect_b32 s90, s53, s57
	s_cselect_b32 s23, s51, s23
	s_cselect_b32 s22, s52, s22
	s_add_u32 s56, s84, s56
	s_addc_u32 s57, s85, 0
	s_add_u32 s56, s56, 0x10080
	s_addc_u32 s57, s57, 0
	v_lshl_add_u64 v[204:205], s[56:57], 0, v[136:137]
	s_add_i32 m0, s28, 0xc000
	ds_read_b128 v[158:161], v140
	ds_read_b128 v[162:165], v140 offset:1024
	ds_read_b128 v[168:171], v140 offset:2048
	ds_read_b128 v[172:175], v140 offset:3072
	ds_read_b128 v[176:179], v140 offset:4096
	ds_read_b128 v[192:195], v140 offset:5120
	ds_read_b128 v[196:199], v140 offset:6144
	ds_read_b128 v[200:203], v140 offset:7168
	global_load_lds_dwordx4 v[204:205], off
	s_add_i32 m0, s28, 0xe000
	v_lshl_add_u64 v[204:205], s[56:57], 0, v[132:133]
	global_load_lds_dwordx4 v[204:205], off
	s_barrier
	s_waitcnt lgkmcnt(0)
	v_mfma_f32_16x16x32_bf16 v[86:89], v[142:145], v[158:161], v[86:89]
	v_mfma_f32_16x16x32_bf16 v[94:97], v[150:153], v[158:161], v[94:97]
	v_mfma_f32_16x16x32_bf16 v[98:101], v[142:145], v[168:171], v[98:101]
	v_mfma_f32_16x16x32_bf16 v[102:105], v[150:153], v[168:171], v[102:105]
	v_mfma_f32_16x16x32_bf16 v[114:117], v[142:145], v[176:179], v[114:117]
	v_mfma_f32_16x16x32_bf16 v[122:125], v[150:153], v[176:179], v[122:125]
	v_mfma_f32_16x16x32_bf16 v[126:129], v[142:145], v[196:199], v[126:129]
	v_mfma_f32_16x16x32_bf16 v[118:121], v[150:153], v[196:199], v[118:121]
	v_mfma_f32_16x16x32_bf16 v[86:89], v[146:149], v[162:165], v[86:89]
	v_mfma_f32_16x16x32_bf16 v[94:97], v[154:157], v[162:165], v[94:97]
	v_mfma_f32_16x16x32_bf16 v[98:101], v[146:149], v[172:175], v[98:101]
	v_mfma_f32_16x16x32_bf16 v[102:105], v[154:157], v[172:175], v[102:105]
	v_mfma_f32_16x16x32_bf16 v[114:117], v[146:149], v[192:195], v[114:117]
	v_mfma_f32_16x16x32_bf16 v[122:125], v[154:157], v[192:195], v[122:125]
	v_mfma_f32_16x16x32_bf16 v[126:129], v[146:149], v[200:203], v[126:129]
	v_mfma_f32_16x16x32_bf16 v[118:121], v[154:157], v[200:203], v[118:121]
	s_barrier
	s_add_i32 s56, s59, s81
	v_add_u32_e32 v141, 0x14000, v139
	v_lshl_add_u64 v[212:213], s[90:91], 0, v[134:135]
	s_mov_b32 m0, s56
	ds_read_b128 v[204:207], v141
	ds_read_b128 v[208:211], v141 offset:1024
	ds_read_b128 v[224:227], v141 offset:2048
	ds_read_b128 v[228:231], v141 offset:3072
	global_load_lds_dwordx4 v[212:213], off
	s_add_i32 m0, s56, 0x2000
	v_lshl_add_u64 v[222:223], s[90:91], 0, v[130:131]
	global_load_lds_dwordx4 v[222:223], off
	s_mov_b32 m0, s28
	v_lshl_add_u64 v[232:233], s[22:23], 0, v[136:137]
	s_waitcnt lgkmcnt(0)
	s_barrier
	v_mfma_f32_16x16x32_bf16 v[2:5], v[204:207], v[158:161], v[2:5]
	v_mfma_f32_16x16x32_bf16 v[6:9], v[224:227], v[158:161], v[6:9]
	v_mfma_f32_16x16x32_bf16 v[10:13], v[204:207], v[168:171], v[10:13]
	v_mfma_f32_16x16x32_bf16 v[14:17], v[224:227], v[168:171], v[14:17]
	v_mfma_f32_16x16x32_bf16 v[22:25], v[204:207], v[176:179], v[22:25]
	v_mfma_f32_16x16x32_bf16 v[18:21], v[224:227], v[176:179], v[18:21]
	v_mfma_f32_16x16x32_bf16 v[30:33], v[204:207], v[196:199], v[30:33]
	v_mfma_f32_16x16x32_bf16 v[26:29], v[224:227], v[196:199], v[26:29]
	v_mfma_f32_16x16x32_bf16 v[2:5], v[208:211], v[162:165], v[2:5]
	v_mfma_f32_16x16x32_bf16 v[6:9], v[228:231], v[162:165], v[6:9]
	v_mfma_f32_16x16x32_bf16 v[10:13], v[208:211], v[172:175], v[10:13]
	v_mfma_f32_16x16x32_bf16 v[14:17], v[228:231], v[172:175], v[14:17]
	v_mfma_f32_16x16x32_bf16 v[22:25], v[208:211], v[192:195], v[22:25]
	v_mfma_f32_16x16x32_bf16 v[18:21], v[228:231], v[192:195], v[18:21]
	v_mfma_f32_16x16x32_bf16 v[30:33], v[208:211], v[200:203], v[30:33]
	v_mfma_f32_16x16x32_bf16 v[26:29], v[228:231], v[200:203], v[26:29]
	s_barrier
	ds_read_b128 v[158:161], v140 offset:16384
	ds_read_b128 v[162:165], v140 offset:17408
	ds_read_b128 v[168:171], v140 offset:18432
	ds_read_b128 v[172:175], v140 offset:19456
	ds_read_b128 v[176:179], v140 offset:20480
	ds_read_b128 v[192:195], v140 offset:21504
	ds_read_b128 v[196:199], v140 offset:22528
	ds_read_b128 v[200:203], v140 offset:23552
	global_load_lds_dwordx4 v[232:233], off
	s_mov_b32 m0, s29
	v_lshl_add_u64 v[234:235], s[22:23], 0, v[132:133]
	global_load_lds_dwordx4 v[234:235], off
	s_waitcnt vmcnt(10)
	s_barrier
	s_waitcnt lgkmcnt(0)
	v_mfma_f32_16x16x32_bf16 v[110:113], v[142:145], v[158:161], v[110:113]
	v_mfma_f32_16x16x32_bf16 v[106:109], v[150:153], v[158:161], v[106:109]
	v_mfma_f32_16x16x32_bf16 v[90:93], v[142:145], v[168:171], v[90:93]
	v_mfma_f32_16x16x32_bf16 v[82:85], v[150:153], v[168:171], v[82:85]
	v_mfma_f32_16x16x32_bf16 v[78:81], v[142:145], v[176:179], v[78:81]
	v_mfma_f32_16x16x32_bf16 v[74:77], v[150:153], v[176:179], v[74:77]
	v_mfma_f32_16x16x32_bf16 v[70:73], v[142:145], v[196:199], v[70:73]
	v_mfma_f32_16x16x32_bf16 v[66:69], v[150:153], v[196:199], v[66:69]
	v_mfma_f32_16x16x32_bf16 v[110:113], v[146:149], v[162:165], v[110:113]
	v_mfma_f32_16x16x32_bf16 v[106:109], v[154:157], v[162:165], v[106:109]
	v_mfma_f32_16x16x32_bf16 v[90:93], v[146:149], v[172:175], v[90:93]
	v_mfma_f32_16x16x32_bf16 v[82:85], v[154:157], v[172:175], v[82:85]
	v_mfma_f32_16x16x32_bf16 v[78:81], v[146:149], v[192:195], v[78:81]
	v_mfma_f32_16x16x32_bf16 v[74:77], v[154:157], v[192:195], v[74:77]
	v_mfma_f32_16x16x32_bf16 v[70:73], v[146:149], v[200:203], v[70:73]
	v_mfma_f32_16x16x32_bf16 v[66:69], v[154:157], v[200:203], v[66:69]
	s_barrier
	s_add_u32 s56, s90, 0x200000
	s_addc_u32 s57, s91, 0
	s_add_i32 s58, s81, 0x14000
	s_mov_b32 m0, s58
	v_lshl_add_u64 v[142:143], s[56:57], 0, v[134:135]
	global_load_lds_dwordx4 v[142:143], off
	s_add_i32 m0, s58, 0x2000
	v_lshl_add_u64 v[142:143], s[56:57], 0, v[130:131]
	global_load_lds_dwordx4 v[142:143], off
	v_add_u32_e32 v141, 0x18000, v139
	ds_read_b128 v[142:145], v141
	ds_read_b128 v[146:149], v141 offset:1024
	ds_read_b128 v[150:153], v141 offset:2048
	ds_read_b128 v[154:157], v141 offset:3072
	s_add_i32 s56, 0, 0x18000
	s_waitcnt vmcnt(6)
	s_barrier
	v_mfma_f32_16x16x32_bf16 v[38:41], v[204:207], v[158:161], v[38:41]
	v_mfma_f32_16x16x32_bf16 v[34:37], v[224:227], v[158:161], v[34:37]
	v_mfma_f32_16x16x32_bf16 v[46:49], v[204:207], v[168:171], v[46:49]
	v_mfma_f32_16x16x32_bf16 v[42:45], v[224:227], v[168:171], v[42:45]
	v_mfma_f32_16x16x32_bf16 v[54:57], v[204:207], v[176:179], v[54:57]
	v_mfma_f32_16x16x32_bf16 v[50:53], v[224:227], v[176:179], v[50:53]
	v_mfma_f32_16x16x32_bf16 v[62:65], v[204:207], v[196:199], v[62:65]
	v_mfma_f32_16x16x32_bf16 v[58:61], v[224:227], v[196:199], v[58:61]
	v_mfma_f32_16x16x32_bf16 v[38:41], v[208:211], v[162:165], v[38:41]
	v_mfma_f32_16x16x32_bf16 v[34:37], v[228:231], v[162:165], v[34:37]
	v_mfma_f32_16x16x32_bf16 v[46:49], v[208:211], v[172:175], v[46:49]
	v_mfma_f32_16x16x32_bf16 v[42:45], v[228:231], v[172:175], v[42:45]
	v_mfma_f32_16x16x32_bf16 v[54:57], v[208:211], v[192:195], v[54:57]
	v_mfma_f32_16x16x32_bf16 v[50:53], v[228:231], v[192:195], v[50:53]
	v_mfma_f32_16x16x32_bf16 v[62:65], v[208:211], v[200:203], v[62:65]
	v_mfma_f32_16x16x32_bf16 v[58:61], v[228:231], v[200:203], v[58:61]
	s_barrier
	s_add_u32 s22, s22, 0x10000
	s_addc_u32 s23, s23, 0
	s_mov_b32 m0, s44
	v_lshl_add_u64 v[204:205], s[22:23], 0, v[136:137]
	ds_read_b128 v[158:161], v140 offset:32768
	ds_read_b128 v[162:165], v140 offset:33792
	ds_read_b128 v[168:171], v140 offset:34816
	ds_read_b128 v[172:175], v140 offset:35840
	ds_read_b128 v[176:179], v140 offset:36864
	ds_read_b128 v[192:195], v140 offset:37888
	ds_read_b128 v[196:199], v140 offset:38912
	ds_read_b128 v[200:203], v140 offset:39936
	global_load_lds_dwordx4 v[204:205], off
	s_mov_b32 m0, s45
	v_lshl_add_u64 v[204:205], s[22:23], 0, v[132:133]
	global_load_lds_dwordx4 v[204:205], off
	s_barrier
	s_waitcnt lgkmcnt(0)
	v_mfma_f32_16x16x32_bf16 v[86:89], v[142:145], v[158:161], v[86:89]
	v_mfma_f32_16x16x32_bf16 v[94:97], v[150:153], v[158:161], v[94:97]
	v_mfma_f32_16x16x32_bf16 v[98:101], v[142:145], v[168:171], v[98:101]
	v_mfma_f32_16x16x32_bf16 v[102:105], v[150:153], v[168:171], v[102:105]
	v_mfma_f32_16x16x32_bf16 v[114:117], v[142:145], v[176:179], v[114:117]
	v_mfma_f32_16x16x32_bf16 v[122:125], v[150:153], v[176:179], v[122:125]
	v_mfma_f32_16x16x32_bf16 v[126:129], v[142:145], v[196:199], v[126:129]
	v_mfma_f32_16x16x32_bf16 v[118:121], v[150:153], v[196:199], v[118:121]
	v_mfma_f32_16x16x32_bf16 v[86:89], v[146:149], v[162:165], v[86:89]
	v_mfma_f32_16x16x32_bf16 v[94:97], v[154:157], v[162:165], v[94:97]
	v_mfma_f32_16x16x32_bf16 v[98:101], v[146:149], v[172:175], v[98:101]
	v_mfma_f32_16x16x32_bf16 v[102:105], v[154:157], v[172:175], v[102:105]
	v_mfma_f32_16x16x32_bf16 v[114:117], v[146:149], v[192:195], v[114:117]
	v_mfma_f32_16x16x32_bf16 v[122:125], v[154:157], v[192:195], v[122:125]
	v_mfma_f32_16x16x32_bf16 v[126:129], v[146:149], v[200:203], v[126:129]
	v_mfma_f32_16x16x32_bf16 v[118:121], v[154:157], v[200:203], v[118:121]
	s_barrier
	s_add_i32 s57, 0, 0x1c000
	s_add_i32 s22, s56, s81
	v_add_u32_e32 v141, s57, v139
	v_lshl_add_u64 v[212:213], v[212:213], 0, s[78:79]
	s_mov_b32 m0, s22
	ds_read_b128 v[204:207], v141
	ds_read_b128 v[208:211], v141 offset:1024
	ds_read_b128 v[224:227], v141 offset:2048
	ds_read_b128 v[228:231], v141 offset:3072
	global_load_lds_dwordx4 v[212:213], off
	s_add_i32 m0, s22, 0x2000
	v_lshl_add_u64 v[212:213], v[222:223], 0, s[78:79]
	global_load_lds_dwordx4 v[212:213], off
	s_mov_b32 m0, s47
	v_lshl_add_u64 v[212:213], v[232:233], 0, s[78:79]
	s_waitcnt lgkmcnt(0)
	s_barrier
	v_mfma_f32_16x16x32_bf16 v[2:5], v[204:207], v[158:161], v[2:5]
	v_mfma_f32_16x16x32_bf16 v[6:9], v[224:227], v[158:161], v[6:9]
	v_mfma_f32_16x16x32_bf16 v[10:13], v[204:207], v[168:171], v[10:13]
	v_mfma_f32_16x16x32_bf16 v[14:17], v[224:227], v[168:171], v[14:17]
	v_mfma_f32_16x16x32_bf16 v[22:25], v[204:207], v[176:179], v[22:25]
	v_mfma_f32_16x16x32_bf16 v[18:21], v[224:227], v[176:179], v[18:21]
	v_mfma_f32_16x16x32_bf16 v[30:33], v[204:207], v[196:199], v[30:33]
	v_mfma_f32_16x16x32_bf16 v[26:29], v[224:227], v[196:199], v[26:29]
	v_mfma_f32_16x16x32_bf16 v[2:5], v[208:211], v[162:165], v[2:5]
	v_mfma_f32_16x16x32_bf16 v[6:9], v[228:231], v[162:165], v[6:9]
	v_mfma_f32_16x16x32_bf16 v[10:13], v[208:211], v[172:175], v[10:13]
	v_mfma_f32_16x16x32_bf16 v[14:17], v[228:231], v[172:175], v[14:17]
	v_mfma_f32_16x16x32_bf16 v[22:25], v[208:211], v[192:195], v[22:25]
	v_mfma_f32_16x16x32_bf16 v[18:21], v[228:231], v[192:195], v[18:21]
	v_mfma_f32_16x16x32_bf16 v[30:33], v[208:211], v[200:203], v[30:33]
	v_mfma_f32_16x16x32_bf16 v[26:29], v[228:231], v[200:203], v[26:29]
	s_barrier
	ds_read_b128 v[158:161], v140 offset:49152
	ds_read_b128 v[162:165], v140 offset:50176
	ds_read_b128 v[168:171], v140 offset:51200
	ds_read_b128 v[172:175], v140 offset:52224
	ds_read_b128 v[176:179], v140 offset:53248
	ds_read_b128 v[192:195], v140 offset:54272
	ds_read_b128 v[196:199], v140 offset:55296
	ds_read_b128 v[200:203], v140 offset:56320
	global_load_lds_dwordx4 v[212:213], off
	s_mov_b32 m0, s48
	v_lshl_add_u64 v[212:213], v[234:235], 0, s[78:79]
	global_load_lds_dwordx4 v[212:213], off
	s_waitcnt vmcnt(10)
	s_barrier
	s_waitcnt lgkmcnt(0)
	v_mfma_f32_16x16x32_bf16 v[110:113], v[142:145], v[158:161], v[110:113]
	v_mfma_f32_16x16x32_bf16 v[106:109], v[150:153], v[158:161], v[106:109]
	v_mfma_f32_16x16x32_bf16 v[90:93], v[142:145], v[168:171], v[90:93]
	v_mfma_f32_16x16x32_bf16 v[82:85], v[150:153], v[168:171], v[82:85]
	v_mfma_f32_16x16x32_bf16 v[78:81], v[142:145], v[176:179], v[78:81]
	v_mfma_f32_16x16x32_bf16 v[74:77], v[150:153], v[176:179], v[74:77]
	v_mfma_f32_16x16x32_bf16 v[70:73], v[142:145], v[196:199], v[70:73]
	v_mfma_f32_16x16x32_bf16 v[66:69], v[150:153], v[196:199], v[66:69]
	v_mfma_f32_16x16x32_bf16 v[110:113], v[146:149], v[162:165], v[110:113]
	v_mfma_f32_16x16x32_bf16 v[106:109], v[154:157], v[162:165], v[106:109]
	v_mfma_f32_16x16x32_bf16 v[90:93], v[146:149], v[172:175], v[90:93]
	v_mfma_f32_16x16x32_bf16 v[82:85], v[154:157], v[172:175], v[82:85]
	v_mfma_f32_16x16x32_bf16 v[78:81], v[146:149], v[192:195], v[78:81]
	v_mfma_f32_16x16x32_bf16 v[74:77], v[154:157], v[192:195], v[74:77]
	v_mfma_f32_16x16x32_bf16 v[70:73], v[146:149], v[200:203], v[70:73]
	v_mfma_f32_16x16x32_bf16 v[66:69], v[154:157], v[200:203], v[66:69]
	s_barrier
	s_add_u32 s22, s90, 0x200080
	s_addc_u32 s23, s91, 0
	s_add_i32 s56, s57, s81
	s_mov_b32 m0, s56
	v_lshl_add_u64 v[142:143], s[22:23], 0, v[134:135]
	global_load_lds_dwordx4 v[142:143], off
	s_add_i32 m0, s56, 0x2000
	v_lshl_add_u64 v[142:143], s[22:23], 0, v[130:131]
	global_load_lds_dwordx4 v[142:143], off
	v_add_u32_e32 v141, 0x10000, v139
	ds_read_b128 v[142:145], v141
	ds_read_b128 v[146:149], v141 offset:1024
	ds_read_b128 v[150:153], v141 offset:2048
	ds_read_b128 v[154:157], v141 offset:3072
	s_add_i32 s54, s54, 2
	s_add_i32 s55, s55, 0x10000
	s_cmpk_gt_u32 s54, 0x7d
	s_mov_b64 s[90:91], vcc
	s_waitcnt vmcnt(6)
	s_barrier
	v_mfma_f32_16x16x32_bf16 v[38:41], v[204:207], v[158:161], v[38:41]
	v_mfma_f32_16x16x32_bf16 v[34:37], v[224:227], v[158:161], v[34:37]
	v_mfma_f32_16x16x32_bf16 v[46:49], v[204:207], v[168:171], v[46:49]
	v_mfma_f32_16x16x32_bf16 v[42:45], v[224:227], v[168:171], v[42:45]
	v_mfma_f32_16x16x32_bf16 v[54:57], v[204:207], v[176:179], v[54:57]
	v_mfma_f32_16x16x32_bf16 v[50:53], v[224:227], v[176:179], v[50:53]
	v_mfma_f32_16x16x32_bf16 v[62:65], v[204:207], v[196:199], v[62:65]
	v_mfma_f32_16x16x32_bf16 v[58:61], v[224:227], v[196:199], v[58:61]
	v_mfma_f32_16x16x32_bf16 v[38:41], v[208:211], v[162:165], v[38:41]
	v_mfma_f32_16x16x32_bf16 v[34:37], v[228:231], v[162:165], v[34:37]
	v_mfma_f32_16x16x32_bf16 v[46:49], v[208:211], v[172:175], v[46:49]
	v_mfma_f32_16x16x32_bf16 v[42:45], v[228:231], v[172:175], v[42:45]
	v_mfma_f32_16x16x32_bf16 v[54:57], v[208:211], v[192:195], v[54:57]
	v_mfma_f32_16x16x32_bf16 v[50:53], v[228:231], v[192:195], v[50:53]
	v_mfma_f32_16x16x32_bf16 v[62:65], v[208:211], v[200:203], v[62:65]
	v_mfma_f32_16x16x32_bf16 v[58:61], v[228:231], v[200:203], v[58:61]
	s_barrier
	s_cbranch_scc0 .LBB0_814
	s_waitcnt lgkmcnt(0)
	s_andn2_b64 vcc, exec, s[38:39]
	s_cbranch_vccnz .LBB0_806
	v_mov_b32_e32 v58, 0
	s_mov_b32 s80, s42
	s_mov_b32 s25, s82
	s_mov_b64 s[30:31], s[20:21]
	s_mov_b64 s[84:85], s[18:19]
	s_mov_b32 s49, s50
	v_mov_b32_e32 v59, v58
	v_mov_b32_e32 v60, v58
	v_mov_b32_e32 v61, v58
	v_mov_b32_e32 v62, v58
	v_mov_b32_e32 v63, v58
	v_mov_b32_e32 v64, v58
	v_mov_b32_e32 v65, v58
	v_mov_b32_e32 v50, v58
	v_mov_b32_e32 v51, v58
	v_mov_b32_e32 v52, v58
	v_mov_b32_e32 v53, v58
	v_mov_b32_e32 v54, v58
	v_mov_b32_e32 v55, v58
	v_mov_b32_e32 v56, v58
	v_mov_b32_e32 v57, v58
	v_mov_b32_e32 v42, v58
	v_mov_b32_e32 v43, v58
	v_mov_b32_e32 v44, v58
	v_mov_b32_e32 v45, v58
	v_mov_b32_e32 v46, v58
	v_mov_b32_e32 v47, v58
	v_mov_b32_e32 v48, v58
	v_mov_b32_e32 v49, v58
	v_mov_b32_e32 v34, v58
	v_mov_b32_e32 v35, v58
	v_mov_b32_e32 v36, v58
	v_mov_b32_e32 v37, v58
	v_mov_b32_e32 v38, v58
	v_mov_b32_e32 v39, v58
	v_mov_b32_e32 v40, v58
	v_mov_b32_e32 v41, v58
	v_mov_b32_e32 v66, v58
	v_mov_b32_e32 v67, v58
	v_mov_b32_e32 v68, v58
	v_mov_b32_e32 v69, v58
	v_mov_b32_e32 v70, v58
	v_mov_b32_e32 v71, v58
	v_mov_b32_e32 v72, v58
	v_mov_b32_e32 v73, v58
	v_mov_b32_e32 v74, v58
	v_mov_b32_e32 v75, v58
	v_mov_b32_e32 v76, v58
	v_mov_b32_e32 v77, v58
	v_mov_b32_e32 v78, v58
	v_mov_b32_e32 v79, v58
	v_mov_b32_e32 v80, v58
	v_mov_b32_e32 v81, v58
	v_mov_b32_e32 v82, v58
	v_mov_b32_e32 v83, v58
	v_mov_b32_e32 v84, v58
	v_mov_b32_e32 v85, v58
	v_mov_b32_e32 v90, v58
	v_mov_b32_e32 v91, v58
	v_mov_b32_e32 v92, v58
	v_mov_b32_e32 v93, v58
	v_mov_b32_e32 v106, v58
	v_mov_b32_e32 v107, v58
	v_mov_b32_e32 v108, v58
	v_mov_b32_e32 v109, v58
	v_mov_b32_e32 v110, v58
	v_mov_b32_e32 v111, v58
	v_mov_b32_e32 v112, v58
	v_mov_b32_e32 v113, v58
	v_mov_b32_e32 v26, v58
	v_mov_b32_e32 v27, v58
	v_mov_b32_e32 v28, v58
	v_mov_b32_e32 v29, v58
	v_mov_b32_e32 v30, v58
	v_mov_b32_e32 v31, v58
	v_mov_b32_e32 v32, v58
	v_mov_b32_e32 v33, v58
	v_mov_b32_e32 v18, v58
	v_mov_b32_e32 v19, v58
	v_mov_b32_e32 v20, v58
	v_mov_b32_e32 v21, v58
	v_mov_b32_e32 v22, v58
	v_mov_b32_e32 v23, v58
	v_mov_b32_e32 v24, v58
	v_mov_b32_e32 v25, v58
	v_mov_b32_e32 v14, v58
	v_mov_b32_e32 v15, v58
	v_mov_b32_e32 v16, v58
	v_mov_b32_e32 v17, v58
	v_mov_b32_e32 v10, v58
	v_mov_b32_e32 v11, v58
	v_mov_b32_e32 v12, v58
	v_mov_b32_e32 v13, v58
	v_mov_b32_e32 v6, v58
	v_mov_b32_e32 v7, v58
	v_mov_b32_e32 v8, v58
	v_mov_b32_e32 v9, v58
	v_mov_b32_e32 v2, v58
	v_mov_b32_e32 v3, v58
	v_mov_b32_e32 v4, v58
	v_mov_b32_e32 v5, v58
	v_mov_b32_e32 v118, v58
	v_mov_b32_e32 v119, v58
	v_mov_b32_e32 v120, v58
	v_mov_b32_e32 v121, v58
	v_mov_b32_e32 v126, v58
	v_mov_b32_e32 v127, v58
	v_mov_b32_e32 v128, v58
	v_mov_b32_e32 v129, v58
	v_mov_b32_e32 v122, v58
	v_mov_b32_e32 v123, v58
	v_mov_b32_e32 v124, v58
	v_mov_b32_e32 v125, v58
	v_mov_b32_e32 v114, v58
	v_mov_b32_e32 v115, v58
	v_mov_b32_e32 v116, v58
	v_mov_b32_e32 v117, v58
	v_mov_b32_e32 v102, v58
	v_mov_b32_e32 v103, v58
	v_mov_b32_e32 v104, v58
	v_mov_b32_e32 v105, v58
	v_mov_b32_e32 v98, v58
	v_mov_b32_e32 v99, v58
	v_mov_b32_e32 v100, v58
	v_mov_b32_e32 v101, v58
	v_mov_b32_e32 v94, v58
	v_mov_b32_e32 v95, v58
	v_mov_b32_e32 v96, v58
	v_mov_b32_e32 v97, v58
	v_mov_b32_e32 v86, v58
	v_mov_b32_e32 v87, v58
	v_mov_b32_e32 v88, v58
	v_mov_b32_e32 v89, v58
	s_branch .LBB0_806
